# static priority raise for waves 4-7 set once at entry, per-phase s_setprio toggles in the GEMM K-loops removed
# speedup vs baseline: 1.0131x; 1.0131x over previous
_ZN2mk4megaENS_6ParamsE:
	s_load_dwordx16 s[4:19], s[0:1], 0x100
	s_mov_b32 s96, s2
	v_readfirstlane_b32 s100, v0
	s_and_b32 s100, s100, 0x3ff
	s_cmp_gt_u32 s100, 255
	s_cbranch_scc0 .Lprio_skip
	s_setprio 1
.Lprio_skip:
	s_waitcnt lgkmcnt(0)
	v_writelane_b32 v253, s4, 0
	s_nop 1
	v_writelane_b32 v253, s5, 1
	v_writelane_b32 v253, s6, 2
	v_writelane_b32 v253, s7, 3
	v_writelane_b32 v253, s8, 4
	v_writelane_b32 v253, s9, 5
	v_writelane_b32 v253, s10, 6
	v_writelane_b32 v253, s11, 7
	v_writelane_b32 v253, s12, 8
	v_writelane_b32 v253, s13, 9
	v_writelane_b32 v253, s14, 10
	v_writelane_b32 v253, s15, 11
	v_writelane_b32 v253, s16, 12
	v_writelane_b32 v253, s17, 13
	v_writelane_b32 v253, s18, 14
	v_writelane_b32 v253, s19, 15
	v_cmp_eq_u32_e64 s[4:5], 0, v0
	s_mov_b64 s[2:3], exec
	s_nop 0
	v_writelane_b32 v253, s4, 16
	s_nop 1
	v_writelane_b32 v253, s5, 17
	s_and_b64 s[4:5], s[2:3], s[4:5]
	s_mov_b64 exec, s[4:5]
	s_cbranch_execz .LBB0_2
	s_add_i32 s4, 0, 0x23ff0
	v_mov_b32_e32 v2, 0
	v_mov_b32_e32 v3, v2
	v_mov_b32_e32 v4, v2
	v_mov_b32_e32 v5, v2
	v_mov_b32_e32 v1, s4
	ds_write_b128 v1, v[2:5]

.LBB0_154:
	ds_read_b128 v[130:133], v139
	ds_read_b128 v[134:137], v139 offset:1024
	ds_read_b128 v[150:153], v139 offset:2048
	ds_read_b128 v[154:157], v139 offset:3072
	s_add_u32 s6, s2, 0xfffc0080
	s_addc_u32 s7, s3, -1
	s_cmp_eq_u32 s15, 12
	s_cselect_b32 s9, s1, s7
	s_cselect_b32 s8, s10, s6
	s_cselect_b32 s7, s11, s14
	s_cselect_b32 s6, s12, s13
	v_lshl_add_u64 v[174:175], s[2:3], 0, v[142:143]
	s_add_i32 m0, s47, 0xc000
	ds_read_b128 v[158:161], v176
	ds_read_b128 v[162:165], v176 offset:1024
	ds_read_b128 v[166:169], v176 offset:2048
	ds_read_b128 v[170:173], v176 offset:3072
	ds_read_b128 v[184:187], v176 offset:4096
	ds_read_b128 v[188:191], v176 offset:5120
	ds_read_b128 v[192:195], v176 offset:6144
	ds_read_b128 v[196:199], v176 offset:7168
	global_load_lds_dwordx4 v[174:175], off
	v_lshl_add_u64 v[174:175], s[2:3], 0, v[144:145]
	s_add_i32 m0, s47, 0xe000
	s_nop 0
	global_load_lds_dwordx4 v[174:175], off
	s_waitcnt lgkmcnt(8)
	s_barrier
	s_waitcnt lgkmcnt(0)
	s_nop 0
	s_waitcnt lgkmcnt(0)
	v_mfma_f32_16x16x32_bf16 v[126:129], v[130:133], v[158:161], v[126:129]
	v_mfma_f32_16x16x32_bf16 v[118:121], v[150:153], v[158:161], v[118:121]
	v_mfma_f32_16x16x32_bf16 v[110:113], v[130:133], v[166:169], v[110:113]
	v_mfma_f32_16x16x32_bf16 v[102:105], v[150:153], v[166:169], v[102:105]
	v_mfma_f32_16x16x32_bf16 v[94:97], v[130:133], v[184:187], v[94:97]
	v_mfma_f32_16x16x32_bf16 v[86:89], v[150:153], v[184:187], v[86:89]
	v_mfma_f32_16x16x32_bf16 v[78:81], v[130:133], v[192:195], v[78:81]
	v_mfma_f32_16x16x32_bf16 v[70:73], v[150:153], v[192:195], v[70:73]
	v_mfma_f32_16x16x32_bf16 v[126:129], v[134:137], v[162:165], v[126:129]
	v_mfma_f32_16x16x32_bf16 v[118:121], v[154:157], v[162:165], v[118:121]
	v_mfma_f32_16x16x32_bf16 v[110:113], v[134:137], v[170:173], v[110:113]
	v_mfma_f32_16x16x32_bf16 v[102:105], v[154:157], v[170:173], v[102:105]
	v_mfma_f32_16x16x32_bf16 v[94:97], v[134:137], v[188:191], v[94:97]
	v_mfma_f32_16x16x32_bf16 v[86:89], v[154:157], v[188:191], v[86:89]
	v_mfma_f32_16x16x32_bf16 v[78:81], v[134:137], v[196:199], v[78:81]
	v_mfma_f32_16x16x32_bf16 v[70:73], v[154:157], v[196:199], v[70:73]
	s_nop 0
	s_barrier
	s_add_i32 s33, s60, s48
	v_lshl_add_u64 v[174:175], s[6:7], 0, v[226:227]
	s_mov_b32 m0, s33
	ds_read_b128 v[200:203], v177
	ds_read_b128 v[204:207], v177 offset:1024
	ds_read_b128 v[208:211], v177 offset:2048
	ds_read_b128 v[212:215], v177 offset:3072
	global_load_lds_dwordx4 v[174:175], off
	v_lshl_add_u64 v[216:217], s[6:7], 0, v[228:229]
	s_add_i32 m0, s33, 0x2000
	s_nop 0
	global_load_lds_dwordx4 v[216:217], off
	s_barrier
	s_waitcnt lgkmcnt(0)
	s_nop 0
	s_waitcnt lgkmcnt(0)
	v_mfma_f32_16x16x32_bf16 v[122:125], v[200:203], v[158:161], v[122:125]
	v_mfma_f32_16x16x32_bf16 v[114:117], v[208:211], v[158:161], v[114:117]
	v_mfma_f32_16x16x32_bf16 v[106:109], v[200:203], v[166:169], v[106:109]
	v_mfma_f32_16x16x32_bf16 v[98:101], v[208:211], v[166:169], v[98:101]
	v_mfma_f32_16x16x32_bf16 v[90:93], v[200:203], v[184:187], v[90:93]
	v_mfma_f32_16x16x32_bf16 v[82:85], v[208:211], v[184:187], v[82:85]
	v_mfma_f32_16x16x32_bf16 v[74:77], v[200:203], v[192:195], v[74:77]
	v_mfma_f32_16x16x32_bf16 v[66:69], v[208:211], v[192:195], v[66:69]
	v_mfma_f32_16x16x32_bf16 v[122:125], v[204:207], v[162:165], v[122:125]
	v_mfma_f32_16x16x32_bf16 v[114:117], v[212:215], v[162:165], v[114:117]
	v_mfma_f32_16x16x32_bf16 v[106:109], v[204:207], v[170:173], v[106:109]
	v_mfma_f32_16x16x32_bf16 v[98:101], v[212:215], v[170:173], v[98:101]
	v_mfma_f32_16x16x32_bf16 v[90:93], v[204:207], v[188:191], v[90:93]
	v_mfma_f32_16x16x32_bf16 v[82:85], v[212:215], v[188:191], v[82:85]
	v_mfma_f32_16x16x32_bf16 v[74:77], v[204:207], v[196:199], v[74:77]
	v_mfma_f32_16x16x32_bf16 v[66:69], v[212:215], v[196:199], v[66:69]
	s_nop 0
	s_mov_b32 m0, s47
	v_lshl_add_u64 v[218:219], s[8:9], 0, v[226:227]
	s_barrier
	ds_read_b128 v[158:161], v176 offset:16384
	ds_read_b128 v[162:165], v176 offset:17408
	ds_read_b128 v[166:169], v176 offset:18432
	ds_read_b128 v[170:173], v176 offset:19456
	ds_read_b128 v[184:187], v176 offset:20480
	ds_read_b128 v[188:191], v176 offset:21504
	ds_read_b128 v[192:195], v176 offset:22528
	ds_read_b128 v[196:199], v176 offset:23552
	global_load_lds_dwordx4 v[218:219], off
	v_lshl_add_u64 v[220:221], s[8:9], 0, v[228:229]
	s_mov_b32 m0, s49
	s_nop 0
	global_load_lds_dwordx4 v[220:221], off
	s_barrier
	s_waitcnt lgkmcnt(0)
	s_nop 0
	s_waitcnt lgkmcnt(0)
	v_mfma_f32_16x16x32_bf16 v[62:65], v[130:133], v[158:161], v[62:65]
	v_mfma_f32_16x16x32_bf16 v[54:57], v[150:153], v[158:161], v[54:57]
	v_mfma_f32_16x16x32_bf16 v[46:49], v[130:133], v[166:169], v[46:49]
	v_mfma_f32_16x16x32_bf16 v[38:41], v[150:153], v[166:169], v[38:41]
	v_mfma_f32_16x16x32_bf16 v[30:33], v[130:133], v[184:187], v[30:33]
	v_mfma_f32_16x16x32_bf16 v[22:25], v[150:153], v[184:187], v[22:25]
	v_mfma_f32_16x16x32_bf16 v[14:17], v[130:133], v[192:195], v[14:17]
	v_mfma_f32_16x16x32_bf16 v[6:9], v[150:153], v[192:195], v[6:9]
	v_mfma_f32_16x16x32_bf16 v[62:65], v[134:137], v[162:165], v[62:65]
	v_mfma_f32_16x16x32_bf16 v[54:57], v[154:157], v[162:165], v[54:57]
	v_mfma_f32_16x16x32_bf16 v[46:49], v[134:137], v[170:173], v[46:49]
	v_mfma_f32_16x16x32_bf16 v[38:41], v[154:157], v[170:173], v[38:41]
	v_mfma_f32_16x16x32_bf16 v[30:33], v[134:137], v[188:191], v[30:33]
	v_mfma_f32_16x16x32_bf16 v[22:25], v[154:157], v[188:191], v[22:25]
	v_mfma_f32_16x16x32_bf16 v[14:17], v[134:137], v[196:199], v[14:17]
	v_mfma_f32_16x16x32_bf16 v[6:9], v[154:157], v[196:199], v[6:9]
	s_nop 0
	s_barrier
	s_add_u32 s82, s6, 0x40000
	s_addc_u32 s83, s7, 0
	s_add_i32 s33, s61, s48
	v_lshl_add_u64 v[130:131], s[82:83], 0, v[226:227]
	s_mov_b32 m0, s33
	s_nop 0
	global_load_lds_dwordx4 v[130:131], off
	v_lshl_add_u64 v[130:131], s[82:83], 0, v[228:229]
	s_add_i32 m0, s33, 0x2000
	s_nop 0
	global_load_lds_dwordx4 v[130:131], off
	s_waitcnt vmcnt(6)
	s_barrier
	s_nop 0
	v_mfma_f32_16x16x32_bf16 v[58:61], v[200:203], v[158:161], v[58:61]
	v_mfma_f32_16x16x32_bf16 v[50:53], v[208:211], v[158:161], v[50:53]
	v_mfma_f32_16x16x32_bf16 v[42:45], v[200:203], v[166:169], v[42:45]
	v_mfma_f32_16x16x32_bf16 v[34:37], v[208:211], v[166:169], v[34:37]
	v_mfma_f32_16x16x32_bf16 v[26:29], v[200:203], v[184:187], v[26:29]
	v_mfma_f32_16x16x32_bf16 v[18:21], v[208:211], v[184:187], v[18:21]
	v_mfma_f32_16x16x32_bf16 v[10:13], v[200:203], v[192:195], v[10:13]
	v_mfma_f32_16x16x32_bf16 v[2:5], v[208:211], v[192:195], v[2:5]
	v_mfma_f32_16x16x32_bf16 v[58:61], v[204:207], v[162:165], v[58:61]
	v_mfma_f32_16x16x32_bf16 v[50:53], v[212:215], v[162:165], v[50:53]
	v_mfma_f32_16x16x32_bf16 v[42:45], v[204:207], v[170:173], v[42:45]
	v_mfma_f32_16x16x32_bf16 v[34:37], v[212:215], v[170:173], v[34:37]
	v_mfma_f32_16x16x32_bf16 v[26:29], v[204:207], v[188:191], v[26:29]
	v_mfma_f32_16x16x32_bf16 v[18:21], v[212:215], v[188:191], v[18:21]
	v_mfma_f32_16x16x32_bf16 v[10:13], v[204:207], v[196:199], v[10:13]
	v_mfma_f32_16x16x32_bf16 v[2:5], v[212:215], v[196:199], v[2:5]
	s_nop 0
	s_add_i32 s33, 0, 0x18000
	v_add_u32_e32 v140, s33, v1
	s_barrier
	ds_read_b128 v[130:133], v140
	ds_read_b128 v[134:137], v140 offset:1024
	ds_read_b128 v[150:153], v140 offset:2048
	ds_read_b128 v[154:157], v140 offset:3072
	s_add_u32 s8, s8, 0x40000
	s_addc_u32 s9, s9, 0
	s_mov_b32 m0, s50
	v_lshl_add_u64 v[200:201], s[8:9], 0, v[226:227]
	ds_read_b128 v[158:161], v176 offset:32768
	ds_read_b128 v[162:165], v176 offset:33792
	ds_read_b128 v[166:169], v176 offset:34816
	ds_read_b128 v[170:173], v176 offset:35840
	ds_read_b128 v[184:187], v176 offset:36864
	ds_read_b128 v[188:191], v176 offset:37888
	ds_read_b128 v[192:195], v176 offset:38912
	ds_read_b128 v[196:199], v176 offset:39936
	global_load_lds_dwordx4 v[200:201], off
	v_lshl_add_u64 v[200:201], s[8:9], 0, v[228:229]
	s_mov_b32 m0, s51
	s_nop 0
	global_load_lds_dwordx4 v[200:201], off
	s_waitcnt lgkmcnt(8)
	s_barrier
	s_waitcnt lgkmcnt(0)
	s_nop 0
	s_waitcnt lgkmcnt(0)
	v_mfma_f32_16x16x32_bf16 v[126:129], v[130:133], v[158:161], v[126:129]
	v_mfma_f32_16x16x32_bf16 v[118:121], v[150:153], v[158:161], v[118:121]
	v_mfma_f32_16x16x32_bf16 v[110:113], v[130:133], v[166:169], v[110:113]
	v_mfma_f32_16x16x32_bf16 v[102:105], v[150:153], v[166:169], v[102:105]
	v_mfma_f32_16x16x32_bf16 v[94:97], v[130:133], v[184:187], v[94:97]
	v_mfma_f32_16x16x32_bf16 v[86:89], v[150:153], v[184:187], v[86:89]
	v_mfma_f32_16x16x32_bf16 v[78:81], v[130:133], v[192:195], v[78:81]
	v_mfma_f32_16x16x32_bf16 v[70:73], v[150:153], v[192:195], v[70:73]
	v_mfma_f32_16x16x32_bf16 v[126:129], v[134:137], v[162:165], v[126:129]
	v_mfma_f32_16x16x32_bf16 v[118:121], v[154:157], v[162:165], v[118:121]
	v_mfma_f32_16x16x32_bf16 v[110:113], v[134:137], v[170:173], v[110:113]
	v_mfma_f32_16x16x32_bf16 v[102:105], v[154:157], v[170:173], v[102:105]
	v_mfma_f32_16x16x32_bf16 v[94:97], v[134:137], v[188:191], v[94:97]
	v_mfma_f32_16x16x32_bf16 v[86:89], v[154:157], v[188:191], v[86:89]
	v_mfma_f32_16x16x32_bf16 v[78:81], v[134:137], v[196:199], v[78:81]
	v_mfma_f32_16x16x32_bf16 v[70:73], v[154:157], v[196:199], v[70:73]
	s_nop 0
	s_barrier
	s_add_i32 s8, 0, 0x1c000
	s_add_i32 s9, s33, s48
	v_add_u32_e32 v140, s8, v1
	v_lshl_add_u64 v[174:175], v[174:175], 0, s[24:25]
	s_mov_b32 m0, s9
	ds_read_b128 v[200:203], v140
	ds_read_b128 v[204:207], v140 offset:1024
	ds_read_b128 v[208:211], v140 offset:2048
	ds_read_b128 v[212:215], v140 offset:3072
	global_load_lds_dwordx4 v[174:175], off
	v_lshl_add_u64 v[174:175], v[216:217], 0, s[24:25]
	s_add_i32 m0, s9, 0x2000
	s_nop 0
	global_load_lds_dwordx4 v[174:175], off
	s_barrier
	s_waitcnt lgkmcnt(0)
	s_nop 0
	s_waitcnt lgkmcnt(0)
	v_mfma_f32_16x16x32_bf16 v[122:125], v[200:203], v[158:161], v[122:125]
	v_mfma_f32_16x16x32_bf16 v[114:117], v[208:211], v[158:161], v[114:117]
	v_mfma_f32_16x16x32_bf16 v[106:109], v[200:203], v[166:169], v[106:109]
	v_mfma_f32_16x16x32_bf16 v[98:101], v[208:211], v[166:169], v[98:101]
	v_mfma_f32_16x16x32_bf16 v[90:93], v[200:203], v[184:187], v[90:93]
	v_mfma_f32_16x16x32_bf16 v[82:85], v[208:211], v[184:187], v[82:85]
	v_mfma_f32_16x16x32_bf16 v[74:77], v[200:203], v[192:195], v[74:77]
	v_mfma_f32_16x16x32_bf16 v[66:69], v[208:211], v[192:195], v[66:69]
	v_mfma_f32_16x16x32_bf16 v[122:125], v[204:207], v[162:165], v[122:125]
	v_mfma_f32_16x16x32_bf16 v[114:117], v[212:215], v[162:165], v[114:117]
	v_mfma_f32_16x16x32_bf16 v[106:109], v[204:207], v[170:173], v[106:109]
	v_mfma_f32_16x16x32_bf16 v[98:101], v[212:215], v[170:173], v[98:101]
	v_mfma_f32_16x16x32_bf16 v[90:93], v[204:207], v[188:191], v[90:93]
	v_mfma_f32_16x16x32_bf16 v[82:85], v[212:215], v[188:191], v[82:85]
	v_mfma_f32_16x16x32_bf16 v[74:77], v[204:207], v[196:199], v[74:77]
	v_mfma_f32_16x16x32_bf16 v[66:69], v[212:215], v[196:199], v[66:69]
	s_nop 0
	s_mov_b32 m0, s56
	v_lshl_add_u64 v[174:175], v[218:219], 0, s[24:25]
	s_barrier
	ds_read_b128 v[158:161], v176 offset:49152
	ds_read_b128 v[162:165], v176 offset:50176
	ds_read_b128 v[166:169], v176 offset:51200
	ds_read_b128 v[170:173], v176 offset:52224
	ds_read_b128 v[184:187], v176 offset:53248
	ds_read_b128 v[188:191], v176 offset:54272
	ds_read_b128 v[192:195], v176 offset:55296
	ds_read_b128 v[196:199], v176 offset:56320
	global_load_lds_dwordx4 v[174:175], off
	v_lshl_add_u64 v[174:175], v[220:221], 0, s[24:25]
	s_mov_b32 m0, s57
	s_nop 0
	global_load_lds_dwordx4 v[174:175], off
	s_barrier
	s_waitcnt lgkmcnt(0)
	s_nop 0
	s_waitcnt lgkmcnt(0)
	v_mfma_f32_16x16x32_bf16 v[62:65], v[130:133], v[158:161], v[62:65]
	v_mfma_f32_16x16x32_bf16 v[54:57], v[150:153], v[158:161], v[54:57]
	v_mfma_f32_16x16x32_bf16 v[46:49], v[130:133], v[166:169], v[46:49]
	v_mfma_f32_16x16x32_bf16 v[38:41], v[150:153], v[166:169], v[38:41]
	v_mfma_f32_16x16x32_bf16 v[30:33], v[130:133], v[184:187], v[30:33]
	v_mfma_f32_16x16x32_bf16 v[22:25], v[150:153], v[184:187], v[22:25]
	v_mfma_f32_16x16x32_bf16 v[14:17], v[130:133], v[192:195], v[14:17]
	v_mfma_f32_16x16x32_bf16 v[6:9], v[150:153], v[192:195], v[6:9]
	v_mfma_f32_16x16x32_bf16 v[62:65], v[134:137], v[162:165], v[62:65]
	v_mfma_f32_16x16x32_bf16 v[54:57], v[154:157], v[162:165], v[54:57]
	v_mfma_f32_16x16x32_bf16 v[46:49], v[134:137], v[170:173], v[46:49]
	v_mfma_f32_16x16x32_bf16 v[38:41], v[154:157], v[170:173], v[38:41]
	v_mfma_f32_16x16x32_bf16 v[30:33], v[134:137], v[188:191], v[30:33]
	v_mfma_f32_16x16x32_bf16 v[22:25], v[154:157], v[188:191], v[22:25]
	v_mfma_f32_16x16x32_bf16 v[14:17], v[134:137], v[196:199], v[14:17]
	v_mfma_f32_16x16x32_bf16 v[6:9], v[154:157], v[196:199], v[6:9]
	s_nop 0
	s_barrier
	s_add_u32 s6, s6, 0x40080
	s_addc_u32 s7, s7, 0
	s_add_i32 s8, s8, s48
	v_lshl_add_u64 v[130:131], s[6:7], 0, v[226:227]
	s_mov_b32 m0, s8
	s_nop 0
	global_load_lds_dwordx4 v[130:131], off
	v_lshl_add_u64 v[130:131], s[6:7], 0, v[228:229]
	s_add_i32 m0, s8, 0x2000
	s_nop 0
	global_load_lds_dwordx4 v[130:131], off
	s_waitcnt vmcnt(6)
	s_barrier
	s_nop 0
	v_mfma_f32_16x16x32_bf16 v[58:61], v[200:203], v[158:161], v[58:61]
	v_mfma_f32_16x16x32_bf16 v[50:53], v[208:211], v[158:161], v[50:53]
	v_mfma_f32_16x16x32_bf16 v[42:45], v[200:203], v[166:169], v[42:45]
	v_mfma_f32_16x16x32_bf16 v[34:37], v[208:211], v[166:169], v[34:37]
	v_mfma_f32_16x16x32_bf16 v[26:29], v[200:203], v[184:187], v[26:29]
	v_mfma_f32_16x16x32_bf16 v[18:21], v[208:211], v[184:187], v[18:21]
	v_mfma_f32_16x16x32_bf16 v[10:13], v[200:203], v[192:195], v[10:13]
	v_mfma_f32_16x16x32_bf16 v[2:5], v[208:211], v[192:195], v[2:5]
	v_mfma_f32_16x16x32_bf16 v[58:61], v[204:207], v[162:165], v[58:61]
	v_mfma_f32_16x16x32_bf16 v[50:53], v[212:215], v[162:165], v[50:53]
	v_mfma_f32_16x16x32_bf16 v[42:45], v[204:207], v[170:173], v[42:45]
	v_mfma_f32_16x16x32_bf16 v[34:37], v[212:215], v[170:173], v[34:37]
	v_mfma_f32_16x16x32_bf16 v[26:29], v[204:207], v[188:191], v[26:29]
	v_mfma_f32_16x16x32_bf16 v[18:21], v[212:215], v[188:191], v[18:21]
	v_mfma_f32_16x16x32_bf16 v[10:13], v[204:207], v[196:199], v[10:13]
	v_mfma_f32_16x16x32_bf16 v[2:5], v[212:215], v[196:199], v[2:5]
	s_nop 0
	s_add_i32 s15, s15, 2
	s_add_u32 s2, s2, 0x100
	s_addc_u32 s3, s3, 0
	s_add_u32 s13, s13, 0x100
	s_addc_u32 s14, s14, 0
	s_cmp_gt_u32 s15, 13
	s_barrier
	s_cbranch_scc0 .LBB0_154
	v_mov_b32_e32 v183, v238
	v_mov_b32_e32 v130, v239
	s_lshl_b32 s0, s0, 8
	s_add_i32 s0, s0, s54
	v_lshlrev_b32_e32 v154, 2, v130
	v_add_u32_e32 v150, s0, v183
	v_add_u32_e32 v152, s55, v154
	s_cmp_gt_i32 s46, 7
	s_mov_b64 s[0:1], -1
	s_cbranch_scc0 .LBB0_502
	s_cmp_gt_u32 s46, 23
	s_cbranch_scc0 .LBB0_435
	s_cmp_gt_u32 s46, 28
	s_cbranch_scc0 .LBB0_337
	s_cmp_lg_u32 s46, 29
	s_cbranch_scc0 .LBB0_238
	s_cmp_gt_u32 s46, 31
	s_cbranch_scc0 .LBB0_235
	s_cmp_gt_u32 s46, 39
	s_cbranch_scc0 .LBB0_232
	s_and_b64 vcc, exec, s[84:85]
	s_cbranch_vccz .LBB0_165
	v_cmp_gt_i32_e32 vcc, 2, v130
	s_and_b64 s[2:3], s[86:87], vcc
	s_and_saveexec_b64 s[0:1], s[2:3]
	s_cbranch_execz .LBB0_164
	v_ashrrev_i32_e32 v151, 31, v150
	v_readlane_b32 s68, v251, 35
	v_lshlrev_b64 v[134:135], 5, v[150:151]
	v_readlane_b32 s74, v251, 41
	v_readlane_b32 s75, v251, 42
	v_ashrrev_i32_e32 v155, 31, v154
	v_pk_mul_f32 v[132:133], v[128:129], s[34:35] op_sel_hi:[1,0]
	v_lshl_add_u64 v[134:135], s[74:75], 0, v[134:135]
	v_pk_mul_f32 v[130:131], v[126:127], s[34:35] op_sel_hi:[1,0]
	v_lshl_add_u64 v[134:135], v[154:155], 2, v[134:135]
	global_store_dwordx4 v[134:135], v[130:133], off
	s_movk_i32 s2, 0x1000
	v_readlane_b32 s69, v251, 36
	v_pk_mul_f32 v[132:133], v[112:113], s[34:35] op_sel_hi:[1,0]
	v_pk_mul_f32 v[130:131], v[110:111], s[34:35] op_sel_hi:[1,0]
	global_store_dwordx4 v[134:135], v[130:133], off offset:512
	v_readlane_b32 s70, v251, 37
	v_readlane_b32 s71, v251, 38
	v_pk_mul_f32 v[132:133], v[96:97], s[34:35] op_sel_hi:[1,0]
	v_pk_mul_f32 v[130:131], v[94:95], s[34:35] op_sel_hi:[1,0]
	global_store_dwordx4 v[134:135], v[130:133], off offset:1024
	v_readlane_b32 s72, v251, 39
	v_readlane_b32 s73, v251, 40
	v_pk_mul_f32 v[132:133], v[80:81], s[34:35] op_sel_hi:[1,0]
	v_pk_mul_f32 v[130:131], v[78:79], s[34:35] op_sel_hi:[1,0]
	global_store_dwordx4 v[134:135], v[130:133], off offset:1536
	v_add_co_u32_e32 v134, vcc, s2, v134
	s_nop 0
	v_pk_mul_f32 v[132:133], v[64:65], s[34:35] op_sel_hi:[1,0]
	v_pk_mul_f32 v[130:131], v[62:63], s[34:35] op_sel_hi:[1,0]
	v_addc_co_u32_e32 v135, vcc, 0, v135, vcc
	global_store_dwordx4 v[134:135], v[130:133], off
	v_readlane_b32 s76, v251, 43
	v_readlane_b32 s77, v251, 44
	v_pk_mul_f32 v[132:133], v[48:49], s[34:35] op_sel_hi:[1,0]
	v_pk_mul_f32 v[130:131], v[46:47], s[34:35] op_sel_hi:[1,0]
	global_store_dwordx4 v[134:135], v[130:133], off offset:512
	v_readlane_b32 s78, v251, 45
	v_readlane_b32 s79, v251, 46
	v_pk_mul_f32 v[132:133], v[32:33], s[34:35] op_sel_hi:[1,0]
	v_pk_mul_f32 v[130:131], v[30:31], s[34:35] op_sel_hi:[1,0]
	global_store_dwordx4 v[134:135], v[130:133], off offset:1024
	v_readlane_b32 s80, v251, 47
	v_readlane_b32 s81, v251, 48
	v_pk_mul_f32 v[132:133], v[16:17], s[34:35] op_sel_hi:[1,0]
	v_pk_mul_f32 v[130:131], v[14:15], s[34:35] op_sel_hi:[1,0]
	v_readlane_b32 s82, v251, 49
	v_readlane_b32 s83, v251, 50
	global_store_dwordx4 v[134:135], v[130:133], off offset:1536

.LBB0_3150:
	ds_read_b128 v[142:145], v176
	ds_read_b128 v[146:149], v176 offset:1024
	ds_read_b128 v[150:153], v176 offset:2048
	ds_read_b128 v[154:157], v176 offset:3072
	s_add_u32 s18, s16, 0xfff80080
	s_addc_u32 s19, s17, -1
	s_cmp_eq_u32 s43, 28
	s_cselect_b32 s21, s5, s19
	s_cselect_b32 s20, s39, s18
	s_cselect_b32 s19, s3, s42
	s_cselect_b32 s18, s40, s41
	v_lshl_add_u64 v[174:175], s[16:17], 0, v[134:135]
	s_add_i32 m0, s15, 0xc000
	ds_read_b128 v[158:161], v177
	ds_read_b128 v[162:165], v177 offset:1024
	ds_read_b128 v[166:169], v177 offset:2048
	ds_read_b128 v[170:173], v177 offset:3072
	ds_read_b128 v[184:187], v177 offset:4096
	ds_read_b128 v[188:191], v177 offset:5120
	ds_read_b128 v[192:195], v177 offset:6144
	ds_read_b128 v[196:199], v177 offset:7168
	global_load_lds_dwordx4 v[174:175], off
	v_lshl_add_u64 v[174:175], s[16:17], 0, v[136:137]
	s_add_i32 m0, s15, 0xe000
	s_nop 0
	global_load_lds_dwordx4 v[174:175], off
	s_waitcnt lgkmcnt(8)
	s_barrier
	s_waitcnt lgkmcnt(0)
	s_nop 0
	s_waitcnt lgkmcnt(0)
	v_mfma_f32_16x16x32_bf16 v[126:129], v[142:145], v[158:161], v[126:129]
	v_mfma_f32_16x16x32_bf16 v[122:125], v[150:153], v[158:161], v[122:125]
	v_mfma_f32_16x16x32_bf16 v[110:113], v[142:145], v[166:169], v[110:113]
	v_mfma_f32_16x16x32_bf16 v[106:109], v[150:153], v[166:169], v[106:109]
	v_mfma_f32_16x16x32_bf16 v[98:101], v[142:145], v[184:187], v[98:101]
	v_mfma_f32_16x16x32_bf16 v[90:93], v[150:153], v[184:187], v[90:93]
	v_mfma_f32_16x16x32_bf16 v[82:85], v[142:145], v[192:195], v[82:85]
	v_mfma_f32_16x16x32_bf16 v[74:77], v[150:153], v[192:195], v[74:77]
	v_mfma_f32_16x16x32_bf16 v[126:129], v[146:149], v[162:165], v[126:129]
	v_mfma_f32_16x16x32_bf16 v[122:125], v[154:157], v[162:165], v[122:125]
	v_mfma_f32_16x16x32_bf16 v[110:113], v[146:149], v[170:173], v[110:113]
	v_mfma_f32_16x16x32_bf16 v[106:109], v[154:157], v[170:173], v[106:109]
	v_mfma_f32_16x16x32_bf16 v[98:101], v[146:149], v[188:191], v[98:101]
	v_mfma_f32_16x16x32_bf16 v[90:93], v[154:157], v[188:191], v[90:93]
	v_mfma_f32_16x16x32_bf16 v[82:85], v[146:149], v[196:199], v[82:85]
	v_mfma_f32_16x16x32_bf16 v[74:77], v[154:157], v[196:199], v[74:77]
	s_nop 0
	s_barrier
	s_add_i32 s44, s36, s24
	v_lshl_add_u64 v[174:175], s[18:19], 0, v[130:131]
	s_mov_b32 m0, s44
	ds_read_b128 v[200:203], v178
	ds_read_b128 v[204:207], v178 offset:1024
	ds_read_b128 v[208:211], v178 offset:2048
	ds_read_b128 v[212:215], v178 offset:3072
	global_load_lds_dwordx4 v[174:175], off
	v_lshl_add_u64 v[180:181], s[18:19], 0, v[132:133]
	s_add_i32 m0, s44, 0x2000
	s_nop 0
	global_load_lds_dwordx4 v[180:181], off
	s_barrier
	s_waitcnt lgkmcnt(0)
	s_nop 0
	s_waitcnt lgkmcnt(0)
	v_mfma_f32_16x16x32_bf16 v[118:121], v[200:203], v[158:161], v[118:121]
	v_mfma_f32_16x16x32_bf16 v[114:117], v[208:211], v[158:161], v[114:117]
	v_mfma_f32_16x16x32_bf16 v[102:105], v[200:203], v[166:169], v[102:105]
	v_mfma_f32_16x16x32_bf16 v[94:97], v[208:211], v[166:169], v[94:97]
	v_mfma_f32_16x16x32_bf16 v[86:89], v[200:203], v[184:187], v[86:89]
	v_mfma_f32_16x16x32_bf16 v[78:81], v[208:211], v[184:187], v[78:81]
	v_mfma_f32_16x16x32_bf16 v[70:73], v[200:203], v[192:195], v[70:73]
	v_mfma_f32_16x16x32_bf16 v[66:69], v[208:211], v[192:195], v[66:69]
	v_mfma_f32_16x16x32_bf16 v[118:121], v[204:207], v[162:165], v[118:121]
	v_mfma_f32_16x16x32_bf16 v[114:117], v[212:215], v[162:165], v[114:117]
	v_mfma_f32_16x16x32_bf16 v[102:105], v[204:207], v[170:173], v[102:105]
	v_mfma_f32_16x16x32_bf16 v[94:97], v[212:215], v[170:173], v[94:97]
	v_mfma_f32_16x16x32_bf16 v[86:89], v[204:207], v[188:191], v[86:89]
	v_mfma_f32_16x16x32_bf16 v[78:81], v[212:215], v[188:191], v[78:81]
	v_mfma_f32_16x16x32_bf16 v[70:73], v[204:207], v[196:199], v[70:73]
	v_mfma_f32_16x16x32_bf16 v[66:69], v[212:215], v[196:199], v[66:69]
	s_nop 0
	s_mov_b32 m0, s15
	v_lshl_add_u64 v[216:217], s[20:21], 0, v[130:131]
	s_barrier
	ds_read_b128 v[158:161], v177 offset:16384
	ds_read_b128 v[162:165], v177 offset:17408
	ds_read_b128 v[166:169], v177 offset:18432
	ds_read_b128 v[170:173], v177 offset:19456
	ds_read_b128 v[184:187], v177 offset:20480
	ds_read_b128 v[188:191], v177 offset:21504
	ds_read_b128 v[192:195], v177 offset:22528
	ds_read_b128 v[196:199], v177 offset:23552
	global_load_lds_dwordx4 v[216:217], off
	v_lshl_add_u64 v[218:219], s[20:21], 0, v[132:133]
	s_mov_b32 m0, s25
	s_nop 0
	global_load_lds_dwordx4 v[218:219], off
	s_barrier
	s_waitcnt lgkmcnt(0)
	s_nop 0
	s_waitcnt lgkmcnt(0)
	v_mfma_f32_16x16x32_bf16 v[62:65], v[142:145], v[158:161], v[62:65]
	v_mfma_f32_16x16x32_bf16 v[58:61], v[150:153], v[158:161], v[58:61]
	v_mfma_f32_16x16x32_bf16 v[50:53], v[142:145], v[166:169], v[50:53]
	v_mfma_f32_16x16x32_bf16 v[42:45], v[150:153], v[166:169], v[42:45]
	v_mfma_f32_16x16x32_bf16 v[34:37], v[142:145], v[184:187], v[34:37]
	v_mfma_f32_16x16x32_bf16 v[26:29], v[150:153], v[184:187], v[26:29]
	v_mfma_f32_16x16x32_bf16 v[18:21], v[142:145], v[192:195], v[18:21]
	v_mfma_f32_16x16x32_bf16 v[10:13], v[150:153], v[192:195], v[10:13]
	v_mfma_f32_16x16x32_bf16 v[62:65], v[146:149], v[162:165], v[62:65]
	v_mfma_f32_16x16x32_bf16 v[58:61], v[154:157], v[162:165], v[58:61]
	v_mfma_f32_16x16x32_bf16 v[50:53], v[146:149], v[170:173], v[50:53]
	v_mfma_f32_16x16x32_bf16 v[42:45], v[154:157], v[170:173], v[42:45]
	v_mfma_f32_16x16x32_bf16 v[34:37], v[146:149], v[188:191], v[34:37]
	v_mfma_f32_16x16x32_bf16 v[26:29], v[154:157], v[188:191], v[26:29]
	v_mfma_f32_16x16x32_bf16 v[18:21], v[146:149], v[196:199], v[18:21]
	v_mfma_f32_16x16x32_bf16 v[10:13], v[154:157], v[196:199], v[10:13]
	s_nop 0
	s_barrier
	s_add_u32 s44, s18, 0x80000
	s_addc_u32 s45, s19, 0
	s_add_i32 s46, s37, s24
	v_lshl_add_u64 v[142:143], s[44:45], 0, v[130:131]
	s_mov_b32 m0, s46
	s_nop 0
	global_load_lds_dwordx4 v[142:143], off
	v_lshl_add_u64 v[142:143], s[44:45], 0, v[132:133]
	s_add_i32 m0, s46, 0x2000
	s_nop 0
	global_load_lds_dwordx4 v[142:143], off
	s_waitcnt vmcnt(6)
	s_barrier
	s_nop 0
	v_mfma_f32_16x16x32_bf16 v[54:57], v[200:203], v[158:161], v[54:57]
	v_mfma_f32_16x16x32_bf16 v[46:49], v[208:211], v[158:161], v[46:49]
	v_mfma_f32_16x16x32_bf16 v[38:41], v[200:203], v[166:169], v[38:41]
	v_mfma_f32_16x16x32_bf16 v[30:33], v[208:211], v[166:169], v[30:33]
	v_mfma_f32_16x16x32_bf16 v[22:25], v[200:203], v[184:187], v[22:25]
	v_mfma_f32_16x16x32_bf16 v[14:17], v[208:211], v[184:187], v[14:17]
	v_mfma_f32_16x16x32_bf16 v[6:9], v[200:203], v[192:195], v[6:9]
	v_mfma_f32_16x16x32_bf16 v[2:5], v[208:211], v[192:195], v[2:5]
	v_mfma_f32_16x16x32_bf16 v[54:57], v[204:207], v[162:165], v[54:57]
	v_mfma_f32_16x16x32_bf16 v[46:49], v[212:215], v[162:165], v[46:49]
	v_mfma_f32_16x16x32_bf16 v[38:41], v[204:207], v[170:173], v[38:41]
	v_mfma_f32_16x16x32_bf16 v[30:33], v[212:215], v[170:173], v[30:33]
	v_mfma_f32_16x16x32_bf16 v[22:25], v[204:207], v[188:191], v[22:25]
	v_mfma_f32_16x16x32_bf16 v[14:17], v[212:215], v[188:191], v[14:17]
	v_mfma_f32_16x16x32_bf16 v[6:9], v[204:207], v[196:199], v[6:9]
	v_mfma_f32_16x16x32_bf16 v[2:5], v[212:215], v[196:199], v[2:5]
	s_nop 0
	s_add_i32 s44, 0, 0x18000
	v_add_u32_e32 v154, s44, v1
	s_barrier
	ds_read_b128 v[142:145], v154
	ds_read_b128 v[146:149], v154 offset:1024
	ds_read_b128 v[150:153], v154 offset:2048
	ds_read_b128 v[154:157], v154 offset:3072
	s_add_u32 s20, s20, 0x80000
	s_addc_u32 s21, s21, 0
	s_mov_b32 m0, s26
	v_lshl_add_u64 v[200:201], s[20:21], 0, v[130:131]
	ds_read_b128 v[158:161], v177 offset:32768
	ds_read_b128 v[162:165], v177 offset:33792
	ds_read_b128 v[166:169], v177 offset:34816
	ds_read_b128 v[170:173], v177 offset:35840
	ds_read_b128 v[184:187], v177 offset:36864
	ds_read_b128 v[188:191], v177 offset:37888
	ds_read_b128 v[192:195], v177 offset:38912
	ds_read_b128 v[196:199], v177 offset:39936
	global_load_lds_dwordx4 v[200:201], off
	v_lshl_add_u64 v[200:201], s[20:21], 0, v[132:133]
	s_mov_b32 m0, s27
	s_nop 0
	global_load_lds_dwordx4 v[200:201], off
	s_waitcnt lgkmcnt(8)
	s_barrier
	s_waitcnt lgkmcnt(0)
	s_nop 0
	s_waitcnt lgkmcnt(0)
	v_mfma_f32_16x16x32_bf16 v[126:129], v[142:145], v[158:161], v[126:129]
	v_mfma_f32_16x16x32_bf16 v[122:125], v[150:153], v[158:161], v[122:125]
	v_mfma_f32_16x16x32_bf16 v[110:113], v[142:145], v[166:169], v[110:113]
	v_mfma_f32_16x16x32_bf16 v[106:109], v[150:153], v[166:169], v[106:109]
	v_mfma_f32_16x16x32_bf16 v[98:101], v[142:145], v[184:187], v[98:101]
	v_mfma_f32_16x16x32_bf16 v[90:93], v[150:153], v[184:187], v[90:93]
	v_mfma_f32_16x16x32_bf16 v[82:85], v[142:145], v[192:195], v[82:85]
	v_mfma_f32_16x16x32_bf16 v[74:77], v[150:153], v[192:195], v[74:77]
	v_mfma_f32_16x16x32_bf16 v[126:129], v[146:149], v[162:165], v[126:129]
	v_mfma_f32_16x16x32_bf16 v[122:125], v[154:157], v[162:165], v[122:125]
	v_mfma_f32_16x16x32_bf16 v[110:113], v[146:149], v[170:173], v[110:113]
	v_mfma_f32_16x16x32_bf16 v[106:109], v[154:157], v[170:173], v[106:109]
	v_mfma_f32_16x16x32_bf16 v[98:101], v[146:149], v[188:191], v[98:101]
	v_mfma_f32_16x16x32_bf16 v[90:93], v[154:157], v[188:191], v[90:93]
	v_mfma_f32_16x16x32_bf16 v[82:85], v[146:149], v[196:199], v[82:85]
	v_mfma_f32_16x16x32_bf16 v[74:77], v[154:157], v[196:199], v[74:77]
	s_nop 0
	s_barrier
	s_add_i32 s20, 0, 0x1c000
	s_add_i32 s21, s44, s24
	v_add_u32_e32 v179, s20, v1
	v_lshl_add_u64 v[174:175], v[174:175], 0, s[0:1]
	s_mov_b32 m0, s21
	ds_read_b128 v[200:203], v179
	ds_read_b128 v[204:207], v179 offset:1024
	ds_read_b128 v[208:211], v179 offset:2048
	ds_read_b128 v[212:215], v179 offset:3072
	global_load_lds_dwordx4 v[174:175], off
	v_lshl_add_u64 v[174:175], v[180:181], 0, s[0:1]
	s_add_i32 m0, s21, 0x2000
	s_nop 0
	global_load_lds_dwordx4 v[174:175], off
	s_barrier
	s_waitcnt lgkmcnt(0)
	s_nop 0
	s_waitcnt lgkmcnt(0)
	v_mfma_f32_16x16x32_bf16 v[118:121], v[200:203], v[158:161], v[118:121]
	v_mfma_f32_16x16x32_bf16 v[114:117], v[208:211], v[158:161], v[114:117]
	v_mfma_f32_16x16x32_bf16 v[102:105], v[200:203], v[166:169], v[102:105]
	v_mfma_f32_16x16x32_bf16 v[94:97], v[208:211], v[166:169], v[94:97]
	v_mfma_f32_16x16x32_bf16 v[86:89], v[200:203], v[184:187], v[86:89]
	v_mfma_f32_16x16x32_bf16 v[78:81], v[208:211], v[184:187], v[78:81]
	v_mfma_f32_16x16x32_bf16 v[70:73], v[200:203], v[192:195], v[70:73]
	v_mfma_f32_16x16x32_bf16 v[66:69], v[208:211], v[192:195], v[66:69]
	v_mfma_f32_16x16x32_bf16 v[118:121], v[204:207], v[162:165], v[118:121]
	v_mfma_f32_16x16x32_bf16 v[114:117], v[212:215], v[162:165], v[114:117]
	v_mfma_f32_16x16x32_bf16 v[102:105], v[204:207], v[170:173], v[102:105]
	v_mfma_f32_16x16x32_bf16 v[94:97], v[212:215], v[170:173], v[94:97]
	v_mfma_f32_16x16x32_bf16 v[86:89], v[204:207], v[188:191], v[86:89]
	v_mfma_f32_16x16x32_bf16 v[78:81], v[212:215], v[188:191], v[78:81]
	v_mfma_f32_16x16x32_bf16 v[70:73], v[204:207], v[196:199], v[70:73]
	v_mfma_f32_16x16x32_bf16 v[66:69], v[212:215], v[196:199], v[66:69]
	s_nop 0
	s_mov_b32 m0, s33
	v_lshl_add_u64 v[174:175], v[216:217], 0, s[0:1]
	s_barrier
	ds_read_b128 v[158:161], v177 offset:49152
	ds_read_b128 v[162:165], v177 offset:50176
	ds_read_b128 v[166:169], v177 offset:51200
	ds_read_b128 v[170:173], v177 offset:52224
	ds_read_b128 v[184:187], v177 offset:53248
	ds_read_b128 v[188:191], v177 offset:54272
	ds_read_b128 v[192:195], v177 offset:55296
	ds_read_b128 v[196:199], v177 offset:56320
	global_load_lds_dwordx4 v[174:175], off
	v_lshl_add_u64 v[174:175], v[218:219], 0, s[0:1]
	s_mov_b32 m0, s34
	s_nop 0
	global_load_lds_dwordx4 v[174:175], off
	s_barrier
	s_waitcnt lgkmcnt(0)
	s_nop 0
	s_waitcnt lgkmcnt(0)
	v_mfma_f32_16x16x32_bf16 v[62:65], v[142:145], v[158:161], v[62:65]
	v_mfma_f32_16x16x32_bf16 v[58:61], v[150:153], v[158:161], v[58:61]
	v_mfma_f32_16x16x32_bf16 v[50:53], v[142:145], v[166:169], v[50:53]
	v_mfma_f32_16x16x32_bf16 v[42:45], v[150:153], v[166:169], v[42:45]
	v_mfma_f32_16x16x32_bf16 v[34:37], v[142:145], v[184:187], v[34:37]
	v_mfma_f32_16x16x32_bf16 v[26:29], v[150:153], v[184:187], v[26:29]
	v_mfma_f32_16x16x32_bf16 v[18:21], v[142:145], v[192:195], v[18:21]
	v_mfma_f32_16x16x32_bf16 v[10:13], v[150:153], v[192:195], v[10:13]
	v_mfma_f32_16x16x32_bf16 v[62:65], v[146:149], v[162:165], v[62:65]
	v_mfma_f32_16x16x32_bf16 v[58:61], v[154:157], v[162:165], v[58:61]
	v_mfma_f32_16x16x32_bf16 v[50:53], v[146:149], v[170:173], v[50:53]
	v_mfma_f32_16x16x32_bf16 v[42:45], v[154:157], v[170:173], v[42:45]
	v_mfma_f32_16x16x32_bf16 v[34:37], v[146:149], v[188:191], v[34:37]
	v_mfma_f32_16x16x32_bf16 v[26:29], v[154:157], v[188:191], v[26:29]
	v_mfma_f32_16x16x32_bf16 v[18:21], v[146:149], v[196:199], v[18:21]
	v_mfma_f32_16x16x32_bf16 v[10:13], v[154:157], v[196:199], v[10:13]
	s_nop 0
	s_barrier
	s_add_u32 s18, s18, 0x80080
	s_addc_u32 s19, s19, 0
	s_add_i32 s20, s20, s24
	v_lshl_add_u64 v[142:143], s[18:19], 0, v[130:131]
	s_mov_b32 m0, s20
	s_nop 0
	global_load_lds_dwordx4 v[142:143], off
	v_lshl_add_u64 v[142:143], s[18:19], 0, v[132:133]
	s_add_i32 m0, s20, 0x2000
	s_nop 0
	global_load_lds_dwordx4 v[142:143], off
	s_waitcnt vmcnt(6)
	s_barrier
	s_nop 0
	v_mfma_f32_16x16x32_bf16 v[54:57], v[200:203], v[158:161], v[54:57]
	v_mfma_f32_16x16x32_bf16 v[46:49], v[208:211], v[158:161], v[46:49]
	v_mfma_f32_16x16x32_bf16 v[38:41], v[200:203], v[166:169], v[38:41]
	v_mfma_f32_16x16x32_bf16 v[30:33], v[208:211], v[166:169], v[30:33]
	v_mfma_f32_16x16x32_bf16 v[22:25], v[200:203], v[184:187], v[22:25]
	v_mfma_f32_16x16x32_bf16 v[14:17], v[208:211], v[184:187], v[14:17]
	v_mfma_f32_16x16x32_bf16 v[6:9], v[200:203], v[192:195], v[6:9]
	v_mfma_f32_16x16x32_bf16 v[2:5], v[208:211], v[192:195], v[2:5]
	v_mfma_f32_16x16x32_bf16 v[54:57], v[204:207], v[162:165], v[54:57]
	v_mfma_f32_16x16x32_bf16 v[46:49], v[212:215], v[162:165], v[46:49]
	v_mfma_f32_16x16x32_bf16 v[38:41], v[204:207], v[170:173], v[38:41]
	v_mfma_f32_16x16x32_bf16 v[30:33], v[212:215], v[170:173], v[30:33]
	v_mfma_f32_16x16x32_bf16 v[22:25], v[204:207], v[188:191], v[22:25]
	v_mfma_f32_16x16x32_bf16 v[14:17], v[212:215], v[188:191], v[14:17]
	v_mfma_f32_16x16x32_bf16 v[6:9], v[204:207], v[196:199], v[6:9]
	v_mfma_f32_16x16x32_bf16 v[2:5], v[212:215], v[196:199], v[2:5]
	s_nop 0
	s_add_i32 s43, s43, 2
	s_add_u32 s16, s16, 0x100
	s_addc_u32 s17, s17, 0
	s_add_u32 s41, s41, 0x100
	s_addc_u32 s42, s42, 0
	s_cmp_gt_u32 s43, 29
	s_barrier
	s_cbranch_scc0 .LBB0_3150
	s_lshl_b32 s3, s14, 8
	v_mov_b32_e32 v142, v238
	v_mov_b32_e32 v143, v239
	s_add_i32 s3, s3, s29
	v_readlane_b32 s40, v251, 19
	v_add_u32_e32 v146, s3, v142
	s_lshl_b32 s3, s38, 8
	s_or_b32 s3, s3, s31
	v_lshl_add_u32 v142, v143, 2, s3
	v_ashrrev_i32_e32 v143, 31, v142
	v_lshlrev_b64 v[142:143], 1, v[142:143]
	v_readlane_b32 s54, v251, 33
	v_readlane_b32 s55, v251, 34
	v_ashrrev_i32_e32 v147, 31, v146
	v_lshlrev_b64 v[146:147], 11, v[146:147]
	v_lshl_add_u64 v[144:145], s[54:55], 0, v[142:143]
	v_lshl_add_u64 v[148:149], v[144:145], 0, v[146:147]
	global_load_dwordx2 v[180:181], v[148:149], off
	global_load_dwordx2 v[184:185], v[148:149], off offset:32
	global_load_dwordx2 v[186:187], v[148:149], off offset:256
	global_load_dwordx2 v[188:189], v[148:149], off offset:288
	s_mov_b64 s[16:17], 0x8000
	v_lshl_add_u64 v[174:175], v[146:147], 0, s[16:17]
	v_lshl_add_u64 v[148:149], v[144:145], 0, v[174:175]
	global_load_dwordx2 v[190:191], v[148:149], off
	global_load_dwordx2 v[172:173], v[148:149], off offset:32
	global_load_dwordx2 v[170:171], v[148:149], off offset:256
	global_load_dwordx2 v[168:169], v[148:149], off offset:288
	s_mov_b64 s[16:17], 0x10000
	v_lshl_add_u64 v[164:165], v[146:147], 0, s[16:17]
	v_lshl_add_u64 v[148:149], v[144:145], 0, v[164:165]
	global_load_dwordx2 v[166:167], v[148:149], off
	global_load_dwordx2 v[162:163], v[148:149], off offset:32
	global_load_dwordx2 v[160:161], v[148:149], off offset:256
	global_load_dwordx2 v[154:155], v[148:149], off offset:288
	s_mov_b64 s[16:17], 0x18000
	v_lshl_add_u64 v[156:157], v[146:147], 0, s[16:17]
	v_lshl_add_u64 v[148:149], v[144:145], 0, v[156:157]
	global_load_dwordx2 v[158:159], v[148:149], off
	global_load_dwordx2 v[152:153], v[148:149], off offset:32
	global_load_dwordx2 v[150:151], v[148:149], off offset:256
	s_nop 0
	global_load_dwordx2 v[148:149], v[148:149], off offset:288
	v_lshl_add_u64 v[194:195], s[92:93], 0, v[146:147]
	v_lshl_add_u64 v[194:195], v[194:195], 0, v[142:143]
	s_mov_b64 s[16:17], 0x40000
	s_and_b64 vcc, exec, s[10:11]
	s_mov_b32 s38, s2
	s_mov_b32 s14, s4
	s_mov_b64 s[18:19], s[12:13]
	v_readlane_b32 s41, v251, 20
	v_readlane_b32 s42, v251, 21
	v_readlane_b32 s43, v251, 22
	v_readlane_b32 s44, v251, 23
	v_readlane_b32 s45, v251, 24
	v_readlane_b32 s46, v251, 25
	v_readlane_b32 s47, v251, 26
	v_readlane_b32 s48, v251, 27
	v_readlane_b32 s49, v251, 28
	v_readlane_b32 s50, v251, 29
	v_readlane_b32 s51, v251, 30
	v_readlane_b32 s52, v251, 31
	v_readlane_b32 s53, v251, 32
	s_waitcnt vmcnt(0)
	v_lshlrev_b32_e32 v192, 16, v180
	v_and_b32_e32 v193, 0xffff0000, v180
	v_lshlrev_b32_e32 v180, 16, v181
	v_and_b32_e32 v181, 0xffff0000, v181
	v_pk_mul_f32 v[126:127], v[126:127], v[192:193]
	v_pk_mul_f32 v[128:129], v[128:129], v[180:181]
	v_cvt_pk_bf16_f32 v126, v126, v127
	s_nop 0
	v_cvt_pk_bf16_f32 v127, v128, v129
	global_store_dwordx2 v[194:195], v[126:127], off
	v_lshlrev_b32_e32 v126, 16, v184
	v_and_b32_e32 v127, 0xffff0000, v184
	v_lshlrev_b32_e32 v128, 16, v185
	v_and_b32_e32 v129, 0xffff0000, v185
	v_pk_mul_f32 v[122:123], v[122:123], v[126:127]
	v_pk_mul_f32 v[124:125], v[124:125], v[128:129]
	v_cvt_pk_bf16_f32 v122, v122, v123
	s_nop 0
	v_cvt_pk_bf16_f32 v123, v124, v125
	global_store_dwordx2 v[194:195], v[122:123], off offset:32
	v_lshlrev_b32_e32 v122, 16, v186
	v_and_b32_e32 v123, 0xffff0000, v186
	v_lshlrev_b32_e32 v124, 16, v187
	v_and_b32_e32 v125, 0xffff0000, v187
	v_pk_mul_f32 v[118:119], v[118:119], v[122:123]
	v_pk_mul_f32 v[120:121], v[120:121], v[124:125]
	v_cvt_pk_bf16_f32 v118, v118, v119
	s_nop 0
	v_cvt_pk_bf16_f32 v119, v120, v121
	global_store_dwordx2 v[194:195], v[118:119], off offset:256
	v_lshlrev_b32_e32 v118, 16, v188
	v_and_b32_e32 v119, 0xffff0000, v188
	v_lshlrev_b32_e32 v120, 16, v189
	v_and_b32_e32 v121, 0xffff0000, v189
	v_pk_mul_f32 v[116:117], v[116:117], v[120:121]
	v_pk_mul_f32 v[114:115], v[114:115], v[118:119]
	v_lshlrev_b32_e32 v118, 16, v191
	v_cvt_pk_bf16_f32 v114, v114, v115
	v_cvt_pk_bf16_f32 v115, v116, v117
	v_lshlrev_b32_e32 v116, 16, v190
	v_and_b32_e32 v117, 0xffff0000, v190
	global_store_dwordx2 v[194:195], v[114:115], off offset:288
	v_and_b32_e32 v119, 0xffff0000, v191
	v_lshl_add_u64 v[114:115], s[92:93], 0, v[174:175]
	v_pk_mul_f32 v[110:111], v[110:111], v[116:117]
	v_lshl_add_u64 v[114:115], v[114:115], 0, v[142:143]
	v_pk_mul_f32 v[112:113], v[112:113], v[118:119]
	v_cvt_pk_bf16_f32 v110, v110, v111
	s_nop 0
	v_cvt_pk_bf16_f32 v111, v112, v113
	global_store_dwordx2 v[114:115], v[110:111], off
	v_lshlrev_b32_e32 v110, 16, v172
	v_and_b32_e32 v111, 0xffff0000, v172
	v_lshlrev_b32_e32 v112, 16, v173
	v_and_b32_e32 v113, 0xffff0000, v173
	v_pk_mul_f32 v[106:107], v[106:107], v[110:111]
	v_pk_mul_f32 v[108:109], v[108:109], v[112:113]
	v_cvt_pk_bf16_f32 v106, v106, v107
	s_nop 0
	v_cvt_pk_bf16_f32 v107, v108, v109
	global_store_dwordx2 v[114:115], v[106:107], off offset:32
	v_lshlrev_b32_e32 v106, 16, v170
	v_and_b32_e32 v107, 0xffff0000, v170
	v_lshlrev_b32_e32 v108, 16, v171
	v_and_b32_e32 v109, 0xffff0000, v171
	v_pk_mul_f32 v[102:103], v[102:103], v[106:107]
	v_pk_mul_f32 v[104:105], v[104:105], v[108:109]
	v_cvt_pk_bf16_f32 v102, v102, v103
	s_nop 0
	v_cvt_pk_bf16_f32 v103, v104, v105
	global_store_dwordx2 v[114:115], v[102:103], off offset:256
	v_lshlrev_b32_e32 v102, 16, v168
	v_and_b32_e32 v103, 0xffff0000, v168
	v_lshlrev_b32_e32 v104, 16, v169
	v_and_b32_e32 v105, 0xffff0000, v169
	v_pk_mul_f32 v[94:95], v[94:95], v[102:103]
	v_pk_mul_f32 v[96:97], v[96:97], v[104:105]
	v_cvt_pk_bf16_f32 v94, v94, v95
	v_lshl_add_u64 v[102:103], s[92:93], 0, v[164:165]
	v_cvt_pk_bf16_f32 v95, v96, v97
	global_store_dwordx2 v[114:115], v[94:95], off offset:288
	v_lshlrev_b32_e32 v94, 16, v166
	v_and_b32_e32 v95, 0xffff0000, v166
	v_lshlrev_b32_e32 v96, 16, v167
	v_and_b32_e32 v97, 0xffff0000, v167
	v_pk_mul_f32 v[94:95], v[98:99], v[94:95]
	v_lshl_add_u64 v[102:103], v[102:103], 0, v[142:143]
	v_pk_mul_f32 v[96:97], v[100:101], v[96:97]
	v_cvt_pk_bf16_f32 v94, v94, v95
	s_nop 0
	v_cvt_pk_bf16_f32 v95, v96, v97
	global_store_dwordx2 v[102:103], v[94:95], off
	v_lshlrev_b32_e32 v94, 16, v162
	v_and_b32_e32 v95, 0xffff0000, v162
	v_lshlrev_b32_e32 v96, 16, v163
	v_and_b32_e32 v97, 0xffff0000, v163
	v_pk_mul_f32 v[90:91], v[90:91], v[94:95]
	v_pk_mul_f32 v[92:93], v[92:93], v[96:97]
	v_cvt_pk_bf16_f32 v90, v90, v91
	s_nop 0
	v_cvt_pk_bf16_f32 v91, v92, v93
	global_store_dwordx2 v[102:103], v[90:91], off offset:32
	v_lshlrev_b32_e32 v90, 16, v160
	v_and_b32_e32 v91, 0xffff0000, v160
	v_lshlrev_b32_e32 v92, 16, v161
	v_and_b32_e32 v93, 0xffff0000, v161
	v_pk_mul_f32 v[86:87], v[86:87], v[90:91]
	v_pk_mul_f32 v[88:89], v[88:89], v[92:93]
	v_cvt_pk_bf16_f32 v86, v86, v87
	s_nop 0
	v_cvt_pk_bf16_f32 v87, v88, v89
	global_store_dwordx2 v[102:103], v[86:87], off offset:256
	v_lshlrev_b32_e32 v86, 16, v154
	v_and_b32_e32 v87, 0xffff0000, v154
	v_lshlrev_b32_e32 v88, 16, v155
	v_and_b32_e32 v89, 0xffff0000, v155
	v_pk_mul_f32 v[78:79], v[78:79], v[86:87]
	v_pk_mul_f32 v[80:81], v[80:81], v[88:89]
	v_cvt_pk_bf16_f32 v78, v78, v79
	v_lshl_add_u64 v[86:87], s[92:93], 0, v[156:157]
	v_cvt_pk_bf16_f32 v79, v80, v81
	global_store_dwordx2 v[102:103], v[78:79], off offset:288
	v_lshlrev_b32_e32 v78, 16, v158
	v_and_b32_e32 v79, 0xffff0000, v158
	v_lshlrev_b32_e32 v80, 16, v159
	v_and_b32_e32 v81, 0xffff0000, v159
	v_pk_mul_f32 v[78:79], v[82:83], v[78:79]
	v_lshl_add_u64 v[86:87], v[86:87], 0, v[142:143]
	v_pk_mul_f32 v[80:81], v[84:85], v[80:81]
	v_cvt_pk_bf16_f32 v78, v78, v79
	s_nop 0
	v_cvt_pk_bf16_f32 v79, v80, v81
	global_store_dwordx2 v[86:87], v[78:79], off
	v_lshlrev_b32_e32 v78, 16, v152
	v_and_b32_e32 v79, 0xffff0000, v152
	v_lshlrev_b32_e32 v80, 16, v153
	v_and_b32_e32 v81, 0xffff0000, v153
	v_pk_mul_f32 v[74:75], v[74:75], v[78:79]
	v_pk_mul_f32 v[76:77], v[76:77], v[80:81]
	v_cvt_pk_bf16_f32 v74, v74, v75
	s_nop 0
	v_cvt_pk_bf16_f32 v75, v76, v77
	global_store_dwordx2 v[86:87], v[74:75], off offset:32
	v_lshlrev_b32_e32 v74, 16, v150
	v_and_b32_e32 v75, 0xffff0000, v150
	v_lshlrev_b32_e32 v76, 16, v151
	v_and_b32_e32 v77, 0xffff0000, v151
	v_pk_mul_f32 v[70:71], v[70:71], v[74:75]
	v_pk_mul_f32 v[72:73], v[72:73], v[76:77]
	v_cvt_pk_bf16_f32 v70, v70, v71
	v_lshl_add_u64 v[76:77], v[146:147], 0, s[16:17]
	v_cvt_pk_bf16_f32 v71, v72, v73
	global_store_dwordx2 v[86:87], v[70:71], off offset:256
	v_lshlrev_b32_e32 v70, 16, v148
	v_and_b32_e32 v71, 0xffff0000, v148
	v_lshlrev_b32_e32 v72, 16, v149
	v_and_b32_e32 v73, 0xffff0000, v149
	v_pk_mul_f32 v[66:67], v[66:67], v[70:71]
	v_pk_mul_f32 v[68:69], v[68:69], v[72:73]
	v_cvt_pk_bf16_f32 v66, v66, v67
	s_mov_b64 s[16:17], 0x48000
	v_cvt_pk_bf16_f32 v67, v68, v69
	global_store_dwordx2 v[86:87], v[66:67], off offset:288
	v_lshl_add_u64 v[66:67], v[144:145], 0, v[76:77]
	global_load_dwordx2 v[78:79], v[66:67], off
	global_load_dwordx2 v[80:81], v[66:67], off offset:32
	global_load_dwordx2 v[82:83], v[66:67], off offset:256
	global_load_dwordx2 v[84:85], v[66:67], off offset:288
	v_lshl_add_u64 v[86:87], v[146:147], 0, s[16:17]
	v_lshl_add_u64 v[66:67], v[144:145], 0, v[86:87]
	global_load_dwordx2 v[88:89], v[66:67], off
	global_load_dwordx2 v[90:91], v[66:67], off offset:32
	global_load_dwordx2 v[92:93], v[66:67], off offset:256
	global_load_dwordx2 v[94:95], v[66:67], off offset:288
	s_mov_b64 s[16:17], 0x50000
	v_lshl_add_u64 v[96:97], v[146:147], 0, s[16:17]
	v_lshl_add_u64 v[66:67], v[144:145], 0, v[96:97]
	global_load_dwordx2 v[98:99], v[66:67], off
	global_load_dwordx2 v[100:101], v[66:67], off offset:32
	global_load_dwordx2 v[102:103], v[66:67], off offset:256
	global_load_dwordx2 v[104:105], v[66:67], off offset:288
	s_mov_b64 s[16:17], 0x58000
	v_lshl_add_u64 v[72:73], v[146:147], 0, s[16:17]
	v_lshl_add_u64 v[66:67], v[144:145], 0, v[72:73]
	global_load_dwordx2 v[74:75], v[66:67], off
	global_load_dwordx2 v[70:71], v[66:67], off offset:32
	global_load_dwordx2 v[68:69], v[66:67], off offset:256
	s_nop 0
	global_load_dwordx2 v[66:67], v[66:67], off offset:288
	v_lshl_add_u64 v[76:77], s[92:93], 0, v[76:77]
	v_lshl_add_u64 v[76:77], v[76:77], 0, v[142:143]
	s_mov_b64 s[16:17], s[6:7]
	s_waitcnt vmcnt(0)
	v_lshlrev_b32_e32 v106, 16, v78
	v_and_b32_e32 v107, 0xffff0000, v78
	v_lshlrev_b32_e32 v78, 16, v79
	v_and_b32_e32 v79, 0xffff0000, v79
	v_pk_mul_f32 v[62:63], v[62:63], v[106:107]
	v_pk_mul_f32 v[64:65], v[64:65], v[78:79]
	v_cvt_pk_bf16_f32 v62, v62, v63
	s_nop 0
	v_cvt_pk_bf16_f32 v63, v64, v65
	global_store_dwordx2 v[76:77], v[62:63], off
	v_lshlrev_b32_e32 v62, 16, v80
	v_and_b32_e32 v63, 0xffff0000, v80
	v_lshlrev_b32_e32 v64, 16, v81
	v_and_b32_e32 v65, 0xffff0000, v81
	v_pk_mul_f32 v[58:59], v[58:59], v[62:63]
	v_pk_mul_f32 v[60:61], v[60:61], v[64:65]
	v_cvt_pk_bf16_f32 v58, v58, v59
	s_nop 0
	v_cvt_pk_bf16_f32 v59, v60, v61
	global_store_dwordx2 v[76:77], v[58:59], off offset:32
	v_lshlrev_b32_e32 v58, 16, v82
	v_and_b32_e32 v59, 0xffff0000, v82
	v_lshlrev_b32_e32 v60, 16, v83
	v_and_b32_e32 v61, 0xffff0000, v83
	v_pk_mul_f32 v[54:55], v[54:55], v[58:59]
	v_pk_mul_f32 v[56:57], v[56:57], v[60:61]
	v_cvt_pk_bf16_f32 v54, v54, v55
	s_nop 0
	v_cvt_pk_bf16_f32 v55, v56, v57
	global_store_dwordx2 v[76:77], v[54:55], off offset:256
	v_lshlrev_b32_e32 v54, 16, v84
	v_and_b32_e32 v55, 0xffff0000, v84
	v_lshlrev_b32_e32 v56, 16, v85
	v_and_b32_e32 v57, 0xffff0000, v85
	v_pk_mul_f32 v[46:47], v[46:47], v[54:55]
	v_pk_mul_f32 v[48:49], v[48:49], v[56:57]
	v_cvt_pk_bf16_f32 v46, v46, v47
	v_lshl_add_u64 v[54:55], s[92:93], 0, v[86:87]
	v_cvt_pk_bf16_f32 v47, v48, v49
	global_store_dwordx2 v[76:77], v[46:47], off offset:288
	v_lshlrev_b32_e32 v46, 16, v88
	v_and_b32_e32 v47, 0xffff0000, v88
	v_lshlrev_b32_e32 v48, 16, v89
	v_and_b32_e32 v49, 0xffff0000, v89
	v_pk_mul_f32 v[46:47], v[50:51], v[46:47]
	v_lshl_add_u64 v[54:55], v[54:55], 0, v[142:143]
	v_pk_mul_f32 v[48:49], v[52:53], v[48:49]
	v_cvt_pk_bf16_f32 v46, v46, v47
	s_nop 0
	v_cvt_pk_bf16_f32 v47, v48, v49
	global_store_dwordx2 v[54:55], v[46:47], off
	v_lshlrev_b32_e32 v46, 16, v90
	v_and_b32_e32 v47, 0xffff0000, v90
	v_lshlrev_b32_e32 v48, 16, v91
	v_and_b32_e32 v49, 0xffff0000, v91
	v_pk_mul_f32 v[42:43], v[42:43], v[46:47]
	v_pk_mul_f32 v[44:45], v[44:45], v[48:49]
	v_cvt_pk_bf16_f32 v42, v42, v43
	s_nop 0
	v_cvt_pk_bf16_f32 v43, v44, v45
	global_store_dwordx2 v[54:55], v[42:43], off offset:32
	v_lshlrev_b32_e32 v42, 16, v92
	v_and_b32_e32 v43, 0xffff0000, v92
	v_lshlrev_b32_e32 v44, 16, v93
	v_and_b32_e32 v45, 0xffff0000, v93
	v_pk_mul_f32 v[38:39], v[38:39], v[42:43]
	v_pk_mul_f32 v[40:41], v[40:41], v[44:45]
	v_cvt_pk_bf16_f32 v38, v38, v39
	s_nop 0
	v_cvt_pk_bf16_f32 v39, v40, v41
	global_store_dwordx2 v[54:55], v[38:39], off offset:256
	v_lshlrev_b32_e32 v38, 16, v94
	v_and_b32_e32 v39, 0xffff0000, v94
	v_lshlrev_b32_e32 v40, 16, v95
	v_and_b32_e32 v41, 0xffff0000, v95
	v_pk_mul_f32 v[30:31], v[30:31], v[38:39]
	v_pk_mul_f32 v[32:33], v[32:33], v[40:41]
	v_cvt_pk_bf16_f32 v30, v30, v31
	v_lshl_add_u64 v[38:39], s[92:93], 0, v[96:97]
	v_cvt_pk_bf16_f32 v31, v32, v33
	global_store_dwordx2 v[54:55], v[30:31], off offset:288
	v_lshlrev_b32_e32 v30, 16, v98
	v_and_b32_e32 v31, 0xffff0000, v98
	v_lshlrev_b32_e32 v32, 16, v99
	v_and_b32_e32 v33, 0xffff0000, v99
	v_pk_mul_f32 v[30:31], v[34:35], v[30:31]
	v_lshl_add_u64 v[38:39], v[38:39], 0, v[142:143]
	v_pk_mul_f32 v[32:33], v[36:37], v[32:33]
	v_cvt_pk_bf16_f32 v30, v30, v31
	s_nop 0
	v_cvt_pk_bf16_f32 v31, v32, v33
	global_store_dwordx2 v[38:39], v[30:31], off
	v_lshlrev_b32_e32 v30, 16, v100
	v_and_b32_e32 v31, 0xffff0000, v100
	v_lshlrev_b32_e32 v32, 16, v101
	v_and_b32_e32 v33, 0xffff0000, v101
	v_pk_mul_f32 v[26:27], v[26:27], v[30:31]
	v_pk_mul_f32 v[28:29], v[28:29], v[32:33]
	v_cvt_pk_bf16_f32 v26, v26, v27
	s_nop 0
	v_cvt_pk_bf16_f32 v27, v28, v29
	global_store_dwordx2 v[38:39], v[26:27], off offset:32
	v_lshlrev_b32_e32 v26, 16, v102
	v_and_b32_e32 v27, 0xffff0000, v102
	v_lshlrev_b32_e32 v28, 16, v103
	v_and_b32_e32 v29, 0xffff0000, v103
	v_pk_mul_f32 v[22:23], v[22:23], v[26:27]
	v_pk_mul_f32 v[24:25], v[24:25], v[28:29]
	v_cvt_pk_bf16_f32 v22, v22, v23
	s_nop 0
	v_cvt_pk_bf16_f32 v23, v24, v25
	global_store_dwordx2 v[38:39], v[22:23], off offset:256
	v_lshlrev_b32_e32 v22, 16, v104
	v_and_b32_e32 v23, 0xffff0000, v104
	v_lshlrev_b32_e32 v24, 16, v105
	v_and_b32_e32 v25, 0xffff0000, v105
	v_pk_mul_f32 v[14:15], v[14:15], v[22:23]
	v_pk_mul_f32 v[16:17], v[16:17], v[24:25]
	v_cvt_pk_bf16_f32 v14, v14, v15
	v_lshl_add_u64 v[22:23], s[92:93], 0, v[72:73]
	v_cvt_pk_bf16_f32 v15, v16, v17
	global_store_dwordx2 v[38:39], v[14:15], off offset:288
	v_lshlrev_b32_e32 v14, 16, v74
	v_and_b32_e32 v15, 0xffff0000, v74
	v_lshlrev_b32_e32 v16, 16, v75
	v_and_b32_e32 v17, 0xffff0000, v75
	v_pk_mul_f32 v[14:15], v[18:19], v[14:15]
	v_lshl_add_u64 v[22:23], v[22:23], 0, v[142:143]
	v_pk_mul_f32 v[16:17], v[20:21], v[16:17]
	v_cvt_pk_bf16_f32 v14, v14, v15
	s_nop 0
	v_cvt_pk_bf16_f32 v15, v16, v17
	global_store_dwordx2 v[22:23], v[14:15], off
	v_lshlrev_b32_e32 v14, 16, v70
	v_and_b32_e32 v15, 0xffff0000, v70
	v_lshlrev_b32_e32 v16, 16, v71
	v_and_b32_e32 v17, 0xffff0000, v71
	v_pk_mul_f32 v[10:11], v[10:11], v[14:15]
	v_pk_mul_f32 v[12:13], v[12:13], v[16:17]
	v_cvt_pk_bf16_f32 v10, v10, v11
	s_nop 0
	v_cvt_pk_bf16_f32 v11, v12, v13
	global_store_dwordx2 v[22:23], v[10:11], off offset:32
	v_lshlrev_b32_e32 v10, 16, v68
	v_and_b32_e32 v11, 0xffff0000, v68
	v_lshlrev_b32_e32 v12, 16, v69
	v_and_b32_e32 v13, 0xffff0000, v69
	v_pk_mul_f32 v[6:7], v[6:7], v[10:11]
	v_pk_mul_f32 v[8:9], v[8:9], v[12:13]
	v_cvt_pk_bf16_f32 v6, v6, v7
	s_nop 0
	v_cvt_pk_bf16_f32 v7, v8, v9
	global_store_dwordx2 v[22:23], v[6:7], off offset:256
	v_lshlrev_b32_e32 v6, 16, v66
	v_and_b32_e32 v7, 0xffff0000, v66
	v_lshlrev_b32_e32 v8, 16, v67
	v_and_b32_e32 v9, 0xffff0000, v67
	v_pk_mul_f32 v[2:3], v[2:3], v[6:7]
	v_pk_mul_f32 v[4:5], v[4:5], v[8:9]
	v_cvt_pk_bf16_f32 v2, v2, v3
	s_nop 0
	v_cvt_pk_bf16_f32 v3, v4, v5
	global_store_dwordx2 v[22:23], v[2:3], off offset:288
	s_cbranch_vccz .LBB0_3143
	s_waitcnt vmcnt(0)
	s_cmpk_gt_u32 s22, 0xff
	s_cbranch_scc1 .LBB0_3154
	s_barrier

.LBB0_3170:
	ds_read_b128 v[138:141], v144
	ds_read_b128 v[148:151], v144 offset:1024
	ds_read_b128 v[152:155], v144 offset:2048
	ds_read_b128 v[156:159], v144 offset:3072
	s_add_u32 s18, s16, 0xfffc0080
	s_addc_u32 s19, s17, -1
	s_cmp_eq_u32 s43, 12
	s_cselect_b32 s21, s5, s19
	s_cselect_b32 s20, s39, s18
	s_cselect_b32 s19, s3, s42
	s_cselect_b32 s18, s40, s41
	v_lshl_add_u64 v[142:143], s[16:17], 0, v[130:131]
	s_add_i32 m0, s15, 0xc000
	ds_read_b128 v[160:163], v145
	ds_read_b128 v[164:167], v145 offset:1024
	ds_read_b128 v[168:171], v145 offset:2048
	ds_read_b128 v[172:175], v145 offset:3072
	ds_read_b128 v[176:179], v145 offset:4096
	ds_read_b128 v[184:187], v145 offset:5120
	ds_read_b128 v[188:191], v145 offset:6144
	ds_read_b128 v[192:195], v145 offset:7168
	global_load_lds_dwordx4 v[142:143], off
	v_lshl_add_u64 v[142:143], s[16:17], 0, v[132:133]
	s_add_i32 m0, s15, 0xe000
	s_nop 0
	global_load_lds_dwordx4 v[142:143], off
	s_waitcnt lgkmcnt(8)
	s_barrier
	s_waitcnt lgkmcnt(0)
	s_nop 0
	s_waitcnt lgkmcnt(0)
	v_mfma_f32_16x16x32_bf16 v[126:129], v[138:141], v[160:163], v[126:129]
	v_mfma_f32_16x16x32_bf16 v[122:125], v[152:155], v[160:163], v[122:125]
	v_mfma_f32_16x16x32_bf16 v[110:113], v[138:141], v[168:171], v[110:113]
	v_mfma_f32_16x16x32_bf16 v[106:109], v[152:155], v[168:171], v[106:109]
	v_mfma_f32_16x16x32_bf16 v[94:97], v[138:141], v[176:179], v[94:97]
	v_mfma_f32_16x16x32_bf16 v[90:93], v[152:155], v[176:179], v[90:93]
	v_mfma_f32_16x16x32_bf16 v[78:81], v[138:141], v[188:191], v[78:81]
	v_mfma_f32_16x16x32_bf16 v[74:77], v[152:155], v[188:191], v[74:77]
	v_mfma_f32_16x16x32_bf16 v[126:129], v[148:151], v[164:167], v[126:129]
	v_mfma_f32_16x16x32_bf16 v[122:125], v[156:159], v[164:167], v[122:125]
	v_mfma_f32_16x16x32_bf16 v[110:113], v[148:151], v[172:175], v[110:113]
	v_mfma_f32_16x16x32_bf16 v[106:109], v[156:159], v[172:175], v[106:109]
	v_mfma_f32_16x16x32_bf16 v[94:97], v[148:151], v[184:187], v[94:97]
	v_mfma_f32_16x16x32_bf16 v[90:93], v[156:159], v[184:187], v[90:93]
	v_mfma_f32_16x16x32_bf16 v[78:81], v[148:151], v[192:195], v[78:81]
	v_mfma_f32_16x16x32_bf16 v[74:77], v[156:159], v[192:195], v[74:77]
	s_nop 0
	s_barrier
	s_add_i32 s44, s36, s24
	v_lshl_add_u64 v[142:143], s[18:19], 0, v[226:227]
	s_mov_b32 m0, s44
	ds_read_b128 v[196:199], v146
	ds_read_b128 v[200:203], v146 offset:1024
	ds_read_b128 v[204:207], v146 offset:2048
	ds_read_b128 v[208:211], v146 offset:3072
	global_load_lds_dwordx4 v[142:143], off
	v_lshl_add_u64 v[180:181], s[18:19], 0, v[228:229]
	s_add_i32 m0, s44, 0x2000
	s_nop 0
	global_load_lds_dwordx4 v[180:181], off
	s_barrier
	s_waitcnt lgkmcnt(0)
	s_nop 0
	s_waitcnt lgkmcnt(0)
	v_mfma_f32_16x16x32_bf16 v[118:121], v[196:199], v[160:163], v[118:121]
	v_mfma_f32_16x16x32_bf16 v[114:117], v[204:207], v[160:163], v[114:117]
	v_mfma_f32_16x16x32_bf16 v[102:105], v[196:199], v[168:171], v[102:105]
	v_mfma_f32_16x16x32_bf16 v[98:101], v[204:207], v[168:171], v[98:101]
	v_mfma_f32_16x16x32_bf16 v[86:89], v[196:199], v[176:179], v[86:89]
	v_mfma_f32_16x16x32_bf16 v[82:85], v[204:207], v[176:179], v[82:85]
	v_mfma_f32_16x16x32_bf16 v[70:73], v[196:199], v[188:191], v[70:73]
	v_mfma_f32_16x16x32_bf16 v[66:69], v[204:207], v[188:191], v[66:69]
	v_mfma_f32_16x16x32_bf16 v[118:121], v[200:203], v[164:167], v[118:121]
	v_mfma_f32_16x16x32_bf16 v[114:117], v[208:211], v[164:167], v[114:117]
	v_mfma_f32_16x16x32_bf16 v[102:105], v[200:203], v[172:175], v[102:105]
	v_mfma_f32_16x16x32_bf16 v[98:101], v[208:211], v[172:175], v[98:101]
	v_mfma_f32_16x16x32_bf16 v[86:89], v[200:203], v[184:187], v[86:89]
	v_mfma_f32_16x16x32_bf16 v[82:85], v[208:211], v[184:187], v[82:85]
	v_mfma_f32_16x16x32_bf16 v[70:73], v[200:203], v[192:195], v[70:73]
	v_mfma_f32_16x16x32_bf16 v[66:69], v[208:211], v[192:195], v[66:69]
	s_nop 0
	s_mov_b32 m0, s15
	v_lshl_add_u64 v[212:213], s[20:21], 0, v[226:227]
	s_barrier
	ds_read_b128 v[160:163], v145 offset:16384
	ds_read_b128 v[164:167], v145 offset:17408
	ds_read_b128 v[168:171], v145 offset:18432
	ds_read_b128 v[172:175], v145 offset:19456
	ds_read_b128 v[176:179], v145 offset:20480
	ds_read_b128 v[184:187], v145 offset:21504
	ds_read_b128 v[188:191], v145 offset:22528
	ds_read_b128 v[192:195], v145 offset:23552
	global_load_lds_dwordx4 v[212:213], off
	v_lshl_add_u64 v[214:215], s[20:21], 0, v[228:229]
	s_mov_b32 m0, s25
	s_nop 0
	global_load_lds_dwordx4 v[214:215], off
	s_barrier
	s_waitcnt lgkmcnt(0)
	s_nop 0
	s_waitcnt lgkmcnt(0)
	v_mfma_f32_16x16x32_bf16 v[62:65], v[138:141], v[160:163], v[62:65]
	v_mfma_f32_16x16x32_bf16 v[58:61], v[152:155], v[160:163], v[58:61]
	v_mfma_f32_16x16x32_bf16 v[50:53], v[138:141], v[168:171], v[50:53]
	v_mfma_f32_16x16x32_bf16 v[42:45], v[152:155], v[168:171], v[42:45]
	v_mfma_f32_16x16x32_bf16 v[30:33], v[138:141], v[176:179], v[30:33]
	v_mfma_f32_16x16x32_bf16 v[26:29], v[152:155], v[176:179], v[26:29]
	v_mfma_f32_16x16x32_bf16 v[18:21], v[138:141], v[188:191], v[18:21]
	v_mfma_f32_16x16x32_bf16 v[10:13], v[152:155], v[188:191], v[10:13]
	v_mfma_f32_16x16x32_bf16 v[62:65], v[148:151], v[164:167], v[62:65]
	v_mfma_f32_16x16x32_bf16 v[58:61], v[156:159], v[164:167], v[58:61]
	v_mfma_f32_16x16x32_bf16 v[50:53], v[148:151], v[172:175], v[50:53]
	v_mfma_f32_16x16x32_bf16 v[42:45], v[156:159], v[172:175], v[42:45]
	v_mfma_f32_16x16x32_bf16 v[30:33], v[148:151], v[184:187], v[30:33]
	v_mfma_f32_16x16x32_bf16 v[26:29], v[156:159], v[184:187], v[26:29]
	v_mfma_f32_16x16x32_bf16 v[18:21], v[148:151], v[192:195], v[18:21]
	v_mfma_f32_16x16x32_bf16 v[10:13], v[156:159], v[192:195], v[10:13]
	s_nop 0
	s_barrier
	s_add_u32 s44, s18, 0x40000
	s_addc_u32 s45, s19, 0
	s_add_i32 s46, s37, s24
	v_lshl_add_u64 v[138:139], s[44:45], 0, v[226:227]
	s_mov_b32 m0, s46
	s_nop 0
	global_load_lds_dwordx4 v[138:139], off
	v_lshl_add_u64 v[138:139], s[44:45], 0, v[228:229]
	s_add_i32 m0, s46, 0x2000
	s_nop 0
	global_load_lds_dwordx4 v[138:139], off
	s_waitcnt vmcnt(6)
	s_barrier
	s_nop 0
	v_mfma_f32_16x16x32_bf16 v[54:57], v[196:199], v[160:163], v[54:57]
	v_mfma_f32_16x16x32_bf16 v[46:49], v[204:207], v[160:163], v[46:49]
	v_mfma_f32_16x16x32_bf16 v[38:41], v[196:199], v[168:171], v[38:41]
	v_mfma_f32_16x16x32_bf16 v[34:37], v[204:207], v[168:171], v[34:37]
	v_mfma_f32_16x16x32_bf16 v[22:25], v[196:199], v[176:179], v[22:25]
	v_mfma_f32_16x16x32_bf16 v[14:17], v[204:207], v[176:179], v[14:17]
	v_mfma_f32_16x16x32_bf16 v[6:9], v[196:199], v[188:191], v[6:9]
	v_mfma_f32_16x16x32_bf16 v[2:5], v[204:207], v[188:191], v[2:5]
	v_mfma_f32_16x16x32_bf16 v[54:57], v[200:203], v[164:167], v[54:57]
	v_mfma_f32_16x16x32_bf16 v[46:49], v[208:211], v[164:167], v[46:49]
	v_mfma_f32_16x16x32_bf16 v[38:41], v[200:203], v[172:175], v[38:41]
	v_mfma_f32_16x16x32_bf16 v[34:37], v[208:211], v[172:175], v[34:37]
	v_mfma_f32_16x16x32_bf16 v[22:25], v[200:203], v[184:187], v[22:25]
	v_mfma_f32_16x16x32_bf16 v[14:17], v[208:211], v[184:187], v[14:17]
	v_mfma_f32_16x16x32_bf16 v[6:9], v[200:203], v[192:195], v[6:9]
	v_mfma_f32_16x16x32_bf16 v[2:5], v[208:211], v[192:195], v[2:5]
	s_nop 0
	s_add_i32 s44, 0, 0x18000
	v_add_u32_e32 v147, s44, v1
	s_barrier
	ds_read_b128 v[138:141], v147
	ds_read_b128 v[148:151], v147 offset:1024
	ds_read_b128 v[152:155], v147 offset:2048
	ds_read_b128 v[156:159], v147 offset:3072
	s_add_u32 s20, s20, 0x40000
	s_addc_u32 s21, s21, 0
	s_mov_b32 m0, s26
	v_lshl_add_u64 v[196:197], s[20:21], 0, v[226:227]
	ds_read_b128 v[160:163], v145 offset:32768
	ds_read_b128 v[164:167], v145 offset:33792
	ds_read_b128 v[168:171], v145 offset:34816
	ds_read_b128 v[172:175], v145 offset:35840
	ds_read_b128 v[176:179], v145 offset:36864
	ds_read_b128 v[184:187], v145 offset:37888
	ds_read_b128 v[188:191], v145 offset:38912
	ds_read_b128 v[192:195], v145 offset:39936
	global_load_lds_dwordx4 v[196:197], off
	v_lshl_add_u64 v[196:197], s[20:21], 0, v[228:229]
	s_mov_b32 m0, s27
	s_nop 0
	global_load_lds_dwordx4 v[196:197], off
	s_waitcnt lgkmcnt(8)
	s_barrier
	s_waitcnt lgkmcnt(0)
	s_nop 0
	s_waitcnt lgkmcnt(0)
	v_mfma_f32_16x16x32_bf16 v[126:129], v[138:141], v[160:163], v[126:129]
	v_mfma_f32_16x16x32_bf16 v[122:125], v[152:155], v[160:163], v[122:125]
	v_mfma_f32_16x16x32_bf16 v[110:113], v[138:141], v[168:171], v[110:113]
	v_mfma_f32_16x16x32_bf16 v[106:109], v[152:155], v[168:171], v[106:109]
	v_mfma_f32_16x16x32_bf16 v[94:97], v[138:141], v[176:179], v[94:97]
	v_mfma_f32_16x16x32_bf16 v[90:93], v[152:155], v[176:179], v[90:93]
	v_mfma_f32_16x16x32_bf16 v[78:81], v[138:141], v[188:191], v[78:81]
	v_mfma_f32_16x16x32_bf16 v[74:77], v[152:155], v[188:191], v[74:77]
	v_mfma_f32_16x16x32_bf16 v[126:129], v[148:151], v[164:167], v[126:129]
	v_mfma_f32_16x16x32_bf16 v[122:125], v[156:159], v[164:167], v[122:125]
	v_mfma_f32_16x16x32_bf16 v[110:113], v[148:151], v[172:175], v[110:113]
	v_mfma_f32_16x16x32_bf16 v[106:109], v[156:159], v[172:175], v[106:109]
	v_mfma_f32_16x16x32_bf16 v[94:97], v[148:151], v[184:187], v[94:97]
	v_mfma_f32_16x16x32_bf16 v[90:93], v[156:159], v[184:187], v[90:93]
	v_mfma_f32_16x16x32_bf16 v[78:81], v[148:151], v[192:195], v[78:81]
	v_mfma_f32_16x16x32_bf16 v[74:77], v[156:159], v[192:195], v[74:77]
	s_nop 0
	s_barrier
	s_add_i32 s20, 0, 0x1c000
	s_add_i32 s21, s44, s24
	v_add_u32_e32 v147, s20, v1
	v_lshl_add_u64 v[142:143], v[142:143], 0, s[0:1]
	s_mov_b32 m0, s21
	ds_read_b128 v[196:199], v147
	ds_read_b128 v[200:203], v147 offset:1024
	ds_read_b128 v[204:207], v147 offset:2048
	ds_read_b128 v[208:211], v147 offset:3072
	global_load_lds_dwordx4 v[142:143], off
	v_lshl_add_u64 v[142:143], v[180:181], 0, s[0:1]
	s_add_i32 m0, s21, 0x2000
	s_nop 0
	global_load_lds_dwordx4 v[142:143], off
	s_barrier
	s_waitcnt lgkmcnt(0)
	s_nop 0
	s_waitcnt lgkmcnt(0)
	v_mfma_f32_16x16x32_bf16 v[118:121], v[196:199], v[160:163], v[118:121]
	v_mfma_f32_16x16x32_bf16 v[114:117], v[204:207], v[160:163], v[114:117]
	v_mfma_f32_16x16x32_bf16 v[102:105], v[196:199], v[168:171], v[102:105]
	v_mfma_f32_16x16x32_bf16 v[98:101], v[204:207], v[168:171], v[98:101]
	v_mfma_f32_16x16x32_bf16 v[86:89], v[196:199], v[176:179], v[86:89]
	v_mfma_f32_16x16x32_bf16 v[82:85], v[204:207], v[176:179], v[82:85]
	v_mfma_f32_16x16x32_bf16 v[70:73], v[196:199], v[188:191], v[70:73]
	v_mfma_f32_16x16x32_bf16 v[66:69], v[204:207], v[188:191], v[66:69]
	v_mfma_f32_16x16x32_bf16 v[118:121], v[200:203], v[164:167], v[118:121]
	v_mfma_f32_16x16x32_bf16 v[114:117], v[208:211], v[164:167], v[114:117]
	v_mfma_f32_16x16x32_bf16 v[102:105], v[200:203], v[172:175], v[102:105]
	v_mfma_f32_16x16x32_bf16 v[98:101], v[208:211], v[172:175], v[98:101]
	v_mfma_f32_16x16x32_bf16 v[86:89], v[200:203], v[184:187], v[86:89]
	v_mfma_f32_16x16x32_bf16 v[82:85], v[208:211], v[184:187], v[82:85]
	v_mfma_f32_16x16x32_bf16 v[70:73], v[200:203], v[192:195], v[70:73]
	v_mfma_f32_16x16x32_bf16 v[66:69], v[208:211], v[192:195], v[66:69]
	s_nop 0
	s_mov_b32 m0, s33
	v_lshl_add_u64 v[142:143], v[212:213], 0, s[0:1]
	s_barrier
	ds_read_b128 v[160:163], v145 offset:49152
	ds_read_b128 v[164:167], v145 offset:50176
	ds_read_b128 v[168:171], v145 offset:51200
	ds_read_b128 v[172:175], v145 offset:52224
	ds_read_b128 v[176:179], v145 offset:53248
	ds_read_b128 v[184:187], v145 offset:54272
	ds_read_b128 v[188:191], v145 offset:55296
	ds_read_b128 v[192:195], v145 offset:56320
	global_load_lds_dwordx4 v[142:143], off
	v_lshl_add_u64 v[142:143], v[214:215], 0, s[0:1]
	s_mov_b32 m0, s34
	s_nop 0
	global_load_lds_dwordx4 v[142:143], off
	s_barrier
	s_waitcnt lgkmcnt(0)
	s_nop 0
	s_waitcnt lgkmcnt(0)
	v_mfma_f32_16x16x32_bf16 v[62:65], v[138:141], v[160:163], v[62:65]
	v_mfma_f32_16x16x32_bf16 v[58:61], v[152:155], v[160:163], v[58:61]
	v_mfma_f32_16x16x32_bf16 v[50:53], v[138:141], v[168:171], v[50:53]
	v_mfma_f32_16x16x32_bf16 v[42:45], v[152:155], v[168:171], v[42:45]
	v_mfma_f32_16x16x32_bf16 v[30:33], v[138:141], v[176:179], v[30:33]
	v_mfma_f32_16x16x32_bf16 v[26:29], v[152:155], v[176:179], v[26:29]
	v_mfma_f32_16x16x32_bf16 v[18:21], v[138:141], v[188:191], v[18:21]
	v_mfma_f32_16x16x32_bf16 v[10:13], v[152:155], v[188:191], v[10:13]
	v_mfma_f32_16x16x32_bf16 v[62:65], v[148:151], v[164:167], v[62:65]
	v_mfma_f32_16x16x32_bf16 v[58:61], v[156:159], v[164:167], v[58:61]
	v_mfma_f32_16x16x32_bf16 v[50:53], v[148:151], v[172:175], v[50:53]
	v_mfma_f32_16x16x32_bf16 v[42:45], v[156:159], v[172:175], v[42:45]
	v_mfma_f32_16x16x32_bf16 v[30:33], v[148:151], v[184:187], v[30:33]
	v_mfma_f32_16x16x32_bf16 v[26:29], v[156:159], v[184:187], v[26:29]
	v_mfma_f32_16x16x32_bf16 v[18:21], v[148:151], v[192:195], v[18:21]
	v_mfma_f32_16x16x32_bf16 v[10:13], v[156:159], v[192:195], v[10:13]
	s_nop 0
	s_barrier
	s_add_u32 s18, s18, 0x40080
	s_addc_u32 s19, s19, 0
	s_add_i32 s20, s20, s24
	v_lshl_add_u64 v[138:139], s[18:19], 0, v[226:227]
	s_mov_b32 m0, s20
	s_nop 0
	global_load_lds_dwordx4 v[138:139], off
	v_lshl_add_u64 v[138:139], s[18:19], 0, v[228:229]
	s_add_i32 m0, s20, 0x2000
	s_nop 0
	global_load_lds_dwordx4 v[138:139], off
	s_waitcnt vmcnt(6)
	s_barrier
	s_nop 0
	v_mfma_f32_16x16x32_bf16 v[54:57], v[196:199], v[160:163], v[54:57]
	v_mfma_f32_16x16x32_bf16 v[46:49], v[204:207], v[160:163], v[46:49]
	v_mfma_f32_16x16x32_bf16 v[38:41], v[196:199], v[168:171], v[38:41]
	v_mfma_f32_16x16x32_bf16 v[34:37], v[204:207], v[168:171], v[34:37]
	v_mfma_f32_16x16x32_bf16 v[22:25], v[196:199], v[176:179], v[22:25]
	v_mfma_f32_16x16x32_bf16 v[14:17], v[204:207], v[176:179], v[14:17]
	v_mfma_f32_16x16x32_bf16 v[6:9], v[196:199], v[188:191], v[6:9]
	v_mfma_f32_16x16x32_bf16 v[2:5], v[204:207], v[188:191], v[2:5]
	v_mfma_f32_16x16x32_bf16 v[54:57], v[200:203], v[164:167], v[54:57]
	v_mfma_f32_16x16x32_bf16 v[46:49], v[208:211], v[164:167], v[46:49]
	v_mfma_f32_16x16x32_bf16 v[38:41], v[200:203], v[172:175], v[38:41]
	v_mfma_f32_16x16x32_bf16 v[34:37], v[208:211], v[172:175], v[34:37]
	v_mfma_f32_16x16x32_bf16 v[22:25], v[200:203], v[184:187], v[22:25]
	v_mfma_f32_16x16x32_bf16 v[14:17], v[208:211], v[184:187], v[14:17]
	v_mfma_f32_16x16x32_bf16 v[6:9], v[200:203], v[192:195], v[6:9]
	v_mfma_f32_16x16x32_bf16 v[2:5], v[208:211], v[192:195], v[2:5]
	s_nop 0
	s_add_i32 s43, s43, 2
	s_add_u32 s16, s16, 0x100
	s_addc_u32 s17, s17, 0
	s_add_u32 s41, s41, 0x100
	s_addc_u32 s42, s42, 0
	s_cmp_gt_u32 s43, 13
	s_barrier
	s_cbranch_scc0 .LBB0_3170
	s_lshl_b32 s3, s14, 8
	v_mov_b32_e32 v138, v238
	v_mov_b32_e32 v139, v239
	s_add_i32 s3, s3, s29
	v_readlane_b32 s40, v251, 35
	v_add_u32_e32 v142, s3, v138
	s_lshl_b32 s3, s38, 8
	s_or_b32 s3, s3, s31
	v_lshl_add_u32 v140, v139, 2, s3
	v_ashrrev_i32_e32 v143, 31, v142
	v_ashrrev_i32_e32 v141, 31, v140
	v_lshlrev_b64 v[138:139], 10, v[142:143]
	v_lshl_add_u64 v[138:139], v[138:139], 0, v[140:141]
	v_lshlrev_b64 v[138:139], 1, v[138:139]
	v_readlane_b32 s41, v251, 36
	v_add_u32_e32 v158, 16, v142
	v_lshl_add_u64 v[148:149], s[92:93], 0, v[138:139]
	v_lshl_add_u64 v[138:139], s[40:41], 0, v[138:139]
	v_ashrrev_i32_e32 v159, 31, v158
	global_load_dwordx2 v[150:151], v[148:149], off
	global_load_dwordx2 v[152:153], v[148:149], off offset:32
	global_load_dwordx2 v[154:155], v[148:149], off offset:256
	s_nop 0
	global_load_dwordx2 v[148:149], v[148:149], off offset:288
	v_lshlrev_b64 v[160:161], 10, v[158:159]
	global_load_dwordx2 v[156:157], v[138:139], off
	global_load_dwordx2 v[162:163], v[138:139], off offset:32
	v_lshl_add_u64 v[160:161], v[160:161], 0, v[140:141]
	v_lshlrev_b64 v[160:161], 1, v[160:161]
	v_lshl_add_u64 v[164:165], s[92:93], 0, v[160:161]
	global_load_dwordx2 v[166:167], v[164:165], off
	global_load_dwordx2 v[168:169], v[164:165], off offset:32
	global_load_dwordx2 v[170:171], v[164:165], off offset:256
	s_nop 0
	global_load_dwordx2 v[164:165], v[164:165], off offset:288
	s_nop 0
	global_load_dwordx2 v[172:173], v[138:139], off offset:256
	global_load_dwordx2 v[174:175], v[138:139], off offset:288
	v_lshl_add_u64 v[160:161], s[40:41], 0, v[160:161]
	global_load_dwordx2 v[176:177], v[160:161], off
	global_load_dwordx2 v[180:181], v[160:161], off offset:32
	global_load_dwordx2 v[184:185], v[160:161], off offset:256
	s_nop 0
	global_load_dwordx2 v[160:161], v[160:161], off offset:288
	v_lshlrev_b64 v[178:179], 11, v[142:143]
	v_lshlrev_b64 v[138:139], 1, v[140:141]
	v_lshl_add_u64 v[178:179], s[94:95], 0, v[178:179]
	v_lshl_add_u64 v[178:179], v[178:179], 0, v[138:139]
	s_and_b64 vcc, exec, s[10:11]
	s_mov_b32 s38, s2
	s_mov_b32 s14, s4
	s_mov_b64 s[18:19], s[12:13]
	s_mov_b64 s[16:17], s[6:7]
	v_readlane_b32 s42, v251, 37
	v_readlane_b32 s43, v251, 38
	v_readlane_b32 s44, v251, 39
	v_readlane_b32 s45, v251, 40
	v_readlane_b32 s46, v251, 41
	v_readlane_b32 s47, v251, 42
	v_readlane_b32 s48, v251, 43
	v_readlane_b32 s49, v251, 44
	v_readlane_b32 s50, v251, 45
	v_readlane_b32 s51, v251, 46
	v_readlane_b32 s52, v251, 47
	v_readlane_b32 s53, v251, 48
	v_readlane_b32 s54, v251, 49
	v_readlane_b32 s55, v251, 50
	s_waitcnt vmcnt(0)
	v_lshlrev_b32_e32 v186, 16, v150
	v_and_b32_e32 v187, 0xffff0000, v150
	v_lshlrev_b32_e32 v188, 16, v152
	v_and_b32_e32 v189, 0xffff0000, v152
	v_lshlrev_b32_e32 v150, 16, v151
	v_lshlrev_b32_e32 v194, 16, v156
	v_and_b32_e32 v195, 0xffff0000, v156
	v_lshlrev_b32_e32 v196, 16, v162
	v_and_b32_e32 v197, 0xffff0000, v162
	v_and_b32_e32 v151, 0xffff0000, v151
	v_lshlrev_b32_e32 v152, 16, v153
	v_and_b32_e32 v153, 0xffff0000, v153
	v_lshlrev_b32_e32 v156, 16, v157
	v_and_b32_e32 v157, 0xffff0000, v157
	v_lshlrev_b32_e32 v162, 16, v163
	v_and_b32_e32 v163, 0xffff0000, v163
	v_pk_fma_f32 v[126:127], v[126:127], v[194:195], v[186:187]
	v_pk_fma_f32 v[122:123], v[122:123], v[196:197], v[188:189]
	v_pk_fma_f32 v[128:129], v[128:129], v[156:157], v[150:151]
	v_pk_fma_f32 v[124:125], v[124:125], v[162:163], v[152:153]
	v_cvt_pk_bf16_f32 v126, v126, v127
	v_cvt_pk_bf16_f32 v127, v128, v129
	global_store_dwordx2 v[178:179], v[126:127], off
	v_cvt_pk_bf16_f32 v122, v122, v123
	v_cvt_pk_bf16_f32 v123, v124, v125
	v_lshlrev_b32_e32 v190, 16, v154
	v_and_b32_e32 v191, 0xffff0000, v154
	global_store_dwordx2 v[178:179], v[122:123], off offset:32
	v_lshlrev_b32_e32 v122, 16, v172
	v_and_b32_e32 v123, 0xffff0000, v172
	v_lshlrev_b32_e32 v154, 16, v155
	v_and_b32_e32 v155, 0xffff0000, v155
	v_lshlrev_b32_e32 v124, 16, v173
	v_and_b32_e32 v125, 0xffff0000, v173
	v_pk_fma_f32 v[118:119], v[118:119], v[122:123], v[190:191]
	v_pk_fma_f32 v[120:121], v[120:121], v[124:125], v[154:155]
	v_cvt_pk_bf16_f32 v118, v118, v119
	v_lshlrev_b32_e32 v192, 16, v148
	v_cvt_pk_bf16_f32 v119, v120, v121
	v_and_b32_e32 v193, 0xffff0000, v148
	global_store_dwordx2 v[178:179], v[118:119], off offset:256
	v_lshlrev_b32_e32 v118, 16, v174
	v_and_b32_e32 v119, 0xffff0000, v174
	v_lshlrev_b32_e32 v148, 16, v149
	v_and_b32_e32 v149, 0xffff0000, v149
	v_lshlrev_b32_e32 v120, 16, v175
	v_and_b32_e32 v121, 0xffff0000, v175
	v_pk_fma_f32 v[114:115], v[114:115], v[118:119], v[192:193]
	v_pk_fma_f32 v[116:117], v[116:117], v[120:121], v[148:149]
	v_cvt_pk_bf16_f32 v114, v114, v115
	v_lshlrev_b32_e32 v198, 16, v166
	v_cvt_pk_bf16_f32 v115, v116, v117
	v_and_b32_e32 v199, 0xffff0000, v166
	global_store_dwordx2 v[178:179], v[114:115], off offset:288
	v_lshlrev_b64 v[114:115], 11, v[158:159]
	v_lshlrev_b32_e32 v116, 16, v176
	v_and_b32_e32 v117, 0xffff0000, v176
	v_lshlrev_b32_e32 v166, 16, v167
	v_and_b32_e32 v167, 0xffff0000, v167
	v_lshlrev_b32_e32 v118, 16, v177
	v_and_b32_e32 v119, 0xffff0000, v177
	v_lshl_add_u64 v[114:115], s[94:95], 0, v[114:115]
	v_pk_fma_f32 v[110:111], v[110:111], v[116:117], v[198:199]
	v_lshl_add_u64 v[114:115], v[114:115], 0, v[138:139]
	v_pk_fma_f32 v[112:113], v[112:113], v[118:119], v[166:167]
	v_cvt_pk_bf16_f32 v110, v110, v111
	v_lshlrev_b32_e32 v200, 16, v168
	v_cvt_pk_bf16_f32 v111, v112, v113
	v_and_b32_e32 v201, 0xffff0000, v168
	global_store_dwordx2 v[114:115], v[110:111], off
	v_lshlrev_b32_e32 v110, 16, v180
	v_and_b32_e32 v111, 0xffff0000, v180
	v_lshlrev_b32_e32 v168, 16, v169
	v_and_b32_e32 v169, 0xffff0000, v169
	v_lshlrev_b32_e32 v112, 16, v181
	v_and_b32_e32 v113, 0xffff0000, v181
	v_pk_fma_f32 v[106:107], v[106:107], v[110:111], v[200:201]
	v_pk_fma_f32 v[108:109], v[108:109], v[112:113], v[168:169]
	v_cvt_pk_bf16_f32 v106, v106, v107
	v_lshlrev_b32_e32 v202, 16, v170
	v_cvt_pk_bf16_f32 v107, v108, v109
	v_and_b32_e32 v203, 0xffff0000, v170
	global_store_dwordx2 v[114:115], v[106:107], off offset:32
	v_lshlrev_b32_e32 v106, 16, v184
	v_and_b32_e32 v107, 0xffff0000, v184
	v_lshlrev_b32_e32 v170, 16, v171
	v_and_b32_e32 v171, 0xffff0000, v171
	v_lshlrev_b32_e32 v108, 16, v185
	v_and_b32_e32 v109, 0xffff0000, v185
	v_pk_fma_f32 v[102:103], v[102:103], v[106:107], v[202:203]
	v_pk_fma_f32 v[104:105], v[104:105], v[108:109], v[170:171]
	v_cvt_pk_bf16_f32 v102, v102, v103
	v_lshlrev_b32_e32 v204, 16, v164
	v_cvt_pk_bf16_f32 v103, v104, v105
	v_and_b32_e32 v205, 0xffff0000, v164
	global_store_dwordx2 v[114:115], v[102:103], off offset:256
	v_lshlrev_b32_e32 v102, 16, v160
	v_and_b32_e32 v103, 0xffff0000, v160
	v_pk_fma_f32 v[98:99], v[98:99], v[102:103], v[204:205]
	v_lshlrev_b32_e32 v164, 16, v165
	v_and_b32_e32 v165, 0xffff0000, v165
	v_lshlrev_b32_e32 v104, 16, v161
	v_and_b32_e32 v105, 0xffff0000, v161
	v_cvt_pk_bf16_f32 v98, v98, v99
	v_pk_fma_f32 v[100:101], v[100:101], v[104:105], v[164:165]
	v_add_u32_e32 v110, 48, v142
	v_cvt_pk_bf16_f32 v99, v100, v101
	global_store_dwordx2 v[114:115], v[98:99], off offset:288
	v_add_u32_e32 v98, 32, v142
	v_ashrrev_i32_e32 v99, 31, v98
	v_ashrrev_i32_e32 v111, 31, v110
	v_lshlrev_b64 v[100:101], 10, v[98:99]
	v_lshlrev_b64 v[112:113], 10, v[110:111]
	v_lshl_add_u64 v[100:101], v[100:101], 0, v[140:141]
	v_lshl_add_u64 v[112:113], v[112:113], 0, v[140:141]
	v_lshlrev_b64 v[100:101], 1, v[100:101]
	v_lshlrev_b64 v[112:113], 1, v[112:113]
	v_lshl_add_u64 v[102:103], s[92:93], 0, v[100:101]
	v_lshl_add_u64 v[114:115], s[92:93], 0, v[112:113]
	v_lshl_add_u64 v[100:101], s[40:41], 0, v[100:101]
	global_load_dwordx2 v[104:105], v[102:103], off
	global_load_dwordx2 v[106:107], v[102:103], off offset:32
	global_load_dwordx2 v[108:109], v[102:103], off offset:256
	s_nop 0
	global_load_dwordx2 v[102:103], v[102:103], off offset:288
	s_nop 0
	global_load_dwordx2 v[116:117], v[114:115], off
	global_load_dwordx2 v[118:119], v[114:115], off offset:32
	global_load_dwordx2 v[120:121], v[114:115], off offset:256
	s_nop 0
	global_load_dwordx2 v[114:115], v[114:115], off offset:288
	s_nop 0
	global_load_dwordx2 v[122:123], v[100:101], off
	global_load_dwordx2 v[124:125], v[100:101], off offset:32
	global_load_dwordx2 v[126:127], v[100:101], off offset:256
	s_nop 0
	global_load_dwordx2 v[100:101], v[100:101], off offset:288
	v_lshl_add_u64 v[112:113], s[40:41], 0, v[112:113]
	global_load_dwordx2 v[128:129], v[112:113], off
	global_load_dwordx2 v[152:153], v[112:113], off offset:32
	global_load_dwordx2 v[158:159], v[112:113], off offset:256
	v_lshlrev_b64 v[98:99], 11, v[98:99]
	global_load_dwordx2 v[112:113], v[112:113], off offset:288
	v_lshl_add_u64 v[98:99], s[94:95], 0, v[98:99]
	v_lshl_add_u64 v[98:99], v[98:99], 0, v[138:139]
	s_waitcnt vmcnt(0)
	v_lshlrev_b32_e32 v148, 16, v104
	v_and_b32_e32 v149, 0xffff0000, v104
	v_lshlrev_b32_e32 v168, 16, v122
	v_and_b32_e32 v169, 0xffff0000, v122
	v_lshlrev_b32_e32 v104, 16, v105
	v_and_b32_e32 v105, 0xffff0000, v105
	v_lshlrev_b32_e32 v122, 16, v123
	v_and_b32_e32 v123, 0xffff0000, v123
	v_pk_fma_f32 v[94:95], v[94:95], v[168:169], v[148:149]
	v_pk_fma_f32 v[96:97], v[96:97], v[122:123], v[104:105]
	v_cvt_pk_bf16_f32 v94, v94, v95
	v_lshlrev_b32_e32 v150, 16, v106
	v_cvt_pk_bf16_f32 v95, v96, v97
	v_and_b32_e32 v151, 0xffff0000, v106
	global_store_dwordx2 v[98:99], v[94:95], off
	v_lshlrev_b32_e32 v94, 16, v124
	v_and_b32_e32 v95, 0xffff0000, v124
	v_lshlrev_b32_e32 v106, 16, v107
	v_and_b32_e32 v107, 0xffff0000, v107
	v_lshlrev_b32_e32 v96, 16, v125
	v_and_b32_e32 v97, 0xffff0000, v125
	v_pk_fma_f32 v[90:91], v[90:91], v[94:95], v[150:151]
	v_pk_fma_f32 v[92:93], v[92:93], v[96:97], v[106:107]
	v_cvt_pk_bf16_f32 v90, v90, v91
	v_lshlrev_b32_e32 v154, 16, v108
	v_cvt_pk_bf16_f32 v91, v92, v93
	v_and_b32_e32 v155, 0xffff0000, v108
	global_store_dwordx2 v[98:99], v[90:91], off offset:32
	v_lshlrev_b32_e32 v90, 16, v126
	v_and_b32_e32 v91, 0xffff0000, v126
	v_lshlrev_b32_e32 v108, 16, v109
	v_and_b32_e32 v109, 0xffff0000, v109
	v_lshlrev_b32_e32 v92, 16, v127
	v_and_b32_e32 v93, 0xffff0000, v127
	v_pk_fma_f32 v[86:87], v[86:87], v[90:91], v[154:155]
	v_pk_fma_f32 v[88:89], v[88:89], v[92:93], v[108:109]
	v_cvt_pk_bf16_f32 v86, v86, v87
	v_lshlrev_b32_e32 v156, 16, v102
	v_cvt_pk_bf16_f32 v87, v88, v89
	v_and_b32_e32 v157, 0xffff0000, v102
	global_store_dwordx2 v[98:99], v[86:87], off offset:256
	v_lshlrev_b32_e32 v86, 16, v100
	v_and_b32_e32 v87, 0xffff0000, v100
	v_lshlrev_b32_e32 v102, 16, v103
	v_and_b32_e32 v103, 0xffff0000, v103
	v_lshlrev_b32_e32 v88, 16, v101
	v_and_b32_e32 v89, 0xffff0000, v101
	v_pk_fma_f32 v[82:83], v[82:83], v[86:87], v[156:157]
	v_pk_fma_f32 v[84:85], v[84:85], v[88:89], v[102:103]
	v_cvt_pk_bf16_f32 v82, v82, v83
	v_lshlrev_b32_e32 v160, 16, v116
	v_cvt_pk_bf16_f32 v83, v84, v85
	v_and_b32_e32 v161, 0xffff0000, v116
	global_store_dwordx2 v[98:99], v[82:83], off offset:288
	v_lshlrev_b64 v[82:83], 11, v[110:111]
	v_lshlrev_b32_e32 v84, 16, v128
	v_and_b32_e32 v85, 0xffff0000, v128
	v_lshlrev_b32_e32 v116, 16, v117
	v_and_b32_e32 v117, 0xffff0000, v117
	v_lshlrev_b32_e32 v86, 16, v129
	v_and_b32_e32 v87, 0xffff0000, v129
	v_lshl_add_u64 v[82:83], s[94:95], 0, v[82:83]
	v_pk_fma_f32 v[78:79], v[78:79], v[84:85], v[160:161]
	v_lshl_add_u64 v[82:83], v[82:83], 0, v[138:139]
	v_pk_fma_f32 v[80:81], v[80:81], v[86:87], v[116:117]
	v_cvt_pk_bf16_f32 v78, v78, v79
	v_lshlrev_b32_e32 v162, 16, v118
	v_cvt_pk_bf16_f32 v79, v80, v81
	v_and_b32_e32 v163, 0xffff0000, v118
	global_store_dwordx2 v[82:83], v[78:79], off
	v_lshlrev_b32_e32 v78, 16, v152
	v_and_b32_e32 v79, 0xffff0000, v152
	v_lshlrev_b32_e32 v118, 16, v119
	v_and_b32_e32 v119, 0xffff0000, v119
	v_lshlrev_b32_e32 v80, 16, v153
	v_and_b32_e32 v81, 0xffff0000, v153
	v_pk_fma_f32 v[74:75], v[74:75], v[78:79], v[162:163]
	v_pk_fma_f32 v[76:77], v[76:77], v[80:81], v[118:119]
	v_cvt_pk_bf16_f32 v74, v74, v75
	v_lshlrev_b32_e32 v164, 16, v120
	v_cvt_pk_bf16_f32 v75, v76, v77
	v_and_b32_e32 v165, 0xffff0000, v120
	global_store_dwordx2 v[82:83], v[74:75], off offset:32
	v_lshlrev_b32_e32 v74, 16, v158
	v_and_b32_e32 v75, 0xffff0000, v158
	v_lshlrev_b32_e32 v120, 16, v121
	v_and_b32_e32 v121, 0xffff0000, v121
	v_lshlrev_b32_e32 v76, 16, v159
	v_and_b32_e32 v77, 0xffff0000, v159
	v_pk_fma_f32 v[70:71], v[70:71], v[74:75], v[164:165]
	v_pk_fma_f32 v[72:73], v[72:73], v[76:77], v[120:121]
	v_cvt_pk_bf16_f32 v70, v70, v71
	v_lshlrev_b32_e32 v166, 16, v114
	v_cvt_pk_bf16_f32 v71, v72, v73
	v_and_b32_e32 v167, 0xffff0000, v114
	global_store_dwordx2 v[82:83], v[70:71], off offset:256
	v_lshlrev_b32_e32 v70, 16, v112
	v_and_b32_e32 v71, 0xffff0000, v112
	v_pk_fma_f32 v[66:67], v[66:67], v[70:71], v[166:167]
	v_lshlrev_b32_e32 v114, 16, v115
	v_and_b32_e32 v115, 0xffff0000, v115
	v_lshlrev_b32_e32 v72, 16, v113
	v_and_b32_e32 v73, 0xffff0000, v113
	v_cvt_pk_bf16_f32 v66, v66, v67
	v_pk_fma_f32 v[68:69], v[68:69], v[72:73], v[114:115]
	v_add_u32_e32 v78, 0x90, v142
	v_cvt_pk_bf16_f32 v67, v68, v69
	global_store_dwordx2 v[82:83], v[66:67], off offset:288
	v_add_u32_e32 v66, 0x80, v142
	v_ashrrev_i32_e32 v67, 31, v66
	v_ashrrev_i32_e32 v79, 31, v78
	v_lshlrev_b64 v[68:69], 10, v[66:67]
	v_lshlrev_b64 v[80:81], 10, v[78:79]
	v_lshl_add_u64 v[68:69], v[68:69], 0, v[140:141]
	v_lshl_add_u64 v[80:81], v[80:81], 0, v[140:141]
	v_lshlrev_b64 v[68:69], 1, v[68:69]
	v_lshlrev_b64 v[80:81], 1, v[80:81]
	v_lshl_add_u64 v[70:71], s[92:93], 0, v[68:69]
	v_lshl_add_u64 v[82:83], s[92:93], 0, v[80:81]
	v_lshl_add_u64 v[68:69], s[40:41], 0, v[68:69]
	global_load_dwordx2 v[72:73], v[70:71], off
	global_load_dwordx2 v[74:75], v[70:71], off offset:32
	global_load_dwordx2 v[76:77], v[70:71], off offset:256
	s_nop 0
	global_load_dwordx2 v[70:71], v[70:71], off offset:288
	s_nop 0
	global_load_dwordx2 v[84:85], v[82:83], off
	global_load_dwordx2 v[86:87], v[82:83], off offset:32
	global_load_dwordx2 v[88:89], v[82:83], off offset:256
	s_nop 0
	global_load_dwordx2 v[82:83], v[82:83], off offset:288
	s_nop 0
	global_load_dwordx2 v[90:91], v[68:69], off
	global_load_dwordx2 v[92:93], v[68:69], off offset:32
	global_load_dwordx2 v[94:95], v[68:69], off offset:256
	s_nop 0
	global_load_dwordx2 v[68:69], v[68:69], off offset:288
	v_lshl_add_u64 v[80:81], s[40:41], 0, v[80:81]
	global_load_dwordx2 v[96:97], v[80:81], off
	global_load_dwordx2 v[102:103], v[80:81], off offset:32
	global_load_dwordx2 v[108:109], v[80:81], off offset:256
	v_lshlrev_b64 v[66:67], 11, v[66:67]
	global_load_dwordx2 v[80:81], v[80:81], off offset:288
	v_lshl_add_u64 v[66:67], s[94:95], 0, v[66:67]
	v_lshl_add_u64 v[66:67], v[66:67], 0, v[138:139]
	s_waitcnt vmcnt(0)
	v_lshlrev_b32_e32 v98, 16, v72
	v_and_b32_e32 v99, 0xffff0000, v72
	v_lshlrev_b32_e32 v118, 16, v90
	v_and_b32_e32 v119, 0xffff0000, v90
	v_lshlrev_b32_e32 v72, 16, v73
	v_and_b32_e32 v73, 0xffff0000, v73
	v_lshlrev_b32_e32 v90, 16, v91
	v_and_b32_e32 v91, 0xffff0000, v91
	v_pk_fma_f32 v[62:63], v[62:63], v[118:119], v[98:99]
	v_pk_fma_f32 v[64:65], v[64:65], v[90:91], v[72:73]
	v_cvt_pk_bf16_f32 v62, v62, v63
	v_lshlrev_b32_e32 v100, 16, v74
	v_cvt_pk_bf16_f32 v63, v64, v65
	v_and_b32_e32 v101, 0xffff0000, v74
	global_store_dwordx2 v[66:67], v[62:63], off
	v_lshlrev_b32_e32 v62, 16, v92
	v_and_b32_e32 v63, 0xffff0000, v92
	v_lshlrev_b32_e32 v74, 16, v75
	v_and_b32_e32 v75, 0xffff0000, v75
	v_lshlrev_b32_e32 v64, 16, v93
	v_and_b32_e32 v65, 0xffff0000, v93
	v_pk_fma_f32 v[58:59], v[58:59], v[62:63], v[100:101]
	v_pk_fma_f32 v[60:61], v[60:61], v[64:65], v[74:75]
	v_cvt_pk_bf16_f32 v58, v58, v59
	v_lshlrev_b32_e32 v104, 16, v76
	v_cvt_pk_bf16_f32 v59, v60, v61
	v_and_b32_e32 v105, 0xffff0000, v76
	global_store_dwordx2 v[66:67], v[58:59], off offset:32
	v_lshlrev_b32_e32 v58, 16, v94
	v_and_b32_e32 v59, 0xffff0000, v94
	v_lshlrev_b32_e32 v76, 16, v77
	v_and_b32_e32 v77, 0xffff0000, v77
	v_lshlrev_b32_e32 v60, 16, v95
	v_and_b32_e32 v61, 0xffff0000, v95
	v_pk_fma_f32 v[54:55], v[54:55], v[58:59], v[104:105]
	v_pk_fma_f32 v[56:57], v[56:57], v[60:61], v[76:77]
	v_cvt_pk_bf16_f32 v54, v54, v55
	v_lshlrev_b32_e32 v106, 16, v70
	v_cvt_pk_bf16_f32 v55, v56, v57
	v_and_b32_e32 v107, 0xffff0000, v70
	global_store_dwordx2 v[66:67], v[54:55], off offset:256
	v_lshlrev_b32_e32 v54, 16, v68
	v_and_b32_e32 v55, 0xffff0000, v68
	v_lshlrev_b32_e32 v70, 16, v71
	v_and_b32_e32 v71, 0xffff0000, v71
	v_lshlrev_b32_e32 v56, 16, v69
	v_and_b32_e32 v57, 0xffff0000, v69
	v_pk_fma_f32 v[46:47], v[46:47], v[54:55], v[106:107]
	v_pk_fma_f32 v[48:49], v[48:49], v[56:57], v[70:71]
	v_cvt_pk_bf16_f32 v46, v46, v47
	v_lshlrev_b32_e32 v110, 16, v84
	v_cvt_pk_bf16_f32 v47, v48, v49
	v_and_b32_e32 v111, 0xffff0000, v84
	global_store_dwordx2 v[66:67], v[46:47], off offset:288
	v_lshlrev_b64 v[46:47], 11, v[78:79]
	v_lshlrev_b32_e32 v48, 16, v96
	v_and_b32_e32 v49, 0xffff0000, v96
	v_lshlrev_b32_e32 v84, 16, v85
	v_and_b32_e32 v85, 0xffff0000, v85
	v_lshlrev_b32_e32 v54, 16, v97
	v_and_b32_e32 v55, 0xffff0000, v97
	v_lshl_add_u64 v[46:47], s[94:95], 0, v[46:47]
	v_pk_fma_f32 v[48:49], v[50:51], v[48:49], v[110:111]
	v_lshl_add_u64 v[46:47], v[46:47], 0, v[138:139]
	v_pk_fma_f32 v[52:53], v[52:53], v[54:55], v[84:85]
	v_cvt_pk_bf16_f32 v48, v48, v49
	v_lshlrev_b32_e32 v112, 16, v86
	v_cvt_pk_bf16_f32 v49, v52, v53
	v_and_b32_e32 v113, 0xffff0000, v86
	global_store_dwordx2 v[46:47], v[48:49], off
	v_lshlrev_b32_e32 v48, 16, v102
	v_and_b32_e32 v49, 0xffff0000, v102
	v_lshlrev_b32_e32 v86, 16, v87
	v_and_b32_e32 v87, 0xffff0000, v87
	v_lshlrev_b32_e32 v50, 16, v103
	v_and_b32_e32 v51, 0xffff0000, v103
	v_pk_fma_f32 v[42:43], v[42:43], v[48:49], v[112:113]
	v_pk_fma_f32 v[44:45], v[44:45], v[50:51], v[86:87]
	v_cvt_pk_bf16_f32 v42, v42, v43
	v_lshlrev_b32_e32 v114, 16, v88
	v_cvt_pk_bf16_f32 v43, v44, v45
	v_and_b32_e32 v115, 0xffff0000, v88
	global_store_dwordx2 v[46:47], v[42:43], off offset:32
	v_lshlrev_b32_e32 v42, 16, v108
	v_and_b32_e32 v43, 0xffff0000, v108
	v_lshlrev_b32_e32 v88, 16, v89
	v_and_b32_e32 v89, 0xffff0000, v89
	v_lshlrev_b32_e32 v44, 16, v109
	v_and_b32_e32 v45, 0xffff0000, v109
	v_pk_fma_f32 v[38:39], v[38:39], v[42:43], v[114:115]
	v_pk_fma_f32 v[40:41], v[40:41], v[44:45], v[88:89]
	v_cvt_pk_bf16_f32 v38, v38, v39
	v_lshlrev_b32_e32 v116, 16, v82
	v_cvt_pk_bf16_f32 v39, v40, v41
	v_and_b32_e32 v117, 0xffff0000, v82
	global_store_dwordx2 v[46:47], v[38:39], off offset:256
	v_lshlrev_b32_e32 v38, 16, v80
	v_and_b32_e32 v39, 0xffff0000, v80
	v_pk_fma_f32 v[34:35], v[34:35], v[38:39], v[116:117]
	v_lshlrev_b32_e32 v82, 16, v83
	v_and_b32_e32 v83, 0xffff0000, v83
	v_lshlrev_b32_e32 v40, 16, v81
	v_and_b32_e32 v41, 0xffff0000, v81
	v_cvt_pk_bf16_f32 v34, v34, v35
	v_pk_fma_f32 v[36:37], v[36:37], v[40:41], v[82:83]
	s_nop 0
	v_cvt_pk_bf16_f32 v35, v36, v37
	global_store_dwordx2 v[46:47], v[34:35], off offset:288
	v_add_u32_e32 v34, 0xa0, v142
	v_add_u32_e32 v46, 0xb0, v142
	v_ashrrev_i32_e32 v35, 31, v34
	v_ashrrev_i32_e32 v47, 31, v46
	v_lshlrev_b64 v[36:37], 10, v[34:35]
	v_lshlrev_b64 v[48:49], 10, v[46:47]
	v_lshl_add_u64 v[36:37], v[36:37], 0, v[140:141]
	v_lshl_add_u64 v[48:49], v[48:49], 0, v[140:141]
	v_lshlrev_b64 v[36:37], 1, v[36:37]
	v_lshlrev_b64 v[48:49], 1, v[48:49]
	v_lshl_add_u64 v[38:39], s[92:93], 0, v[36:37]
	v_lshl_add_u64 v[50:51], s[92:93], 0, v[48:49]
	v_lshl_add_u64 v[36:37], s[40:41], 0, v[36:37]
	global_load_dwordx2 v[40:41], v[38:39], off
	global_load_dwordx2 v[42:43], v[38:39], off offset:32
	global_load_dwordx2 v[44:45], v[38:39], off offset:256
	s_nop 0
	global_load_dwordx2 v[38:39], v[38:39], off offset:288
	s_nop 0
	global_load_dwordx2 v[52:53], v[50:51], off
	global_load_dwordx2 v[54:55], v[50:51], off offset:32
	global_load_dwordx2 v[56:57], v[50:51], off offset:256
	s_nop 0
	global_load_dwordx2 v[50:51], v[50:51], off offset:288
	s_nop 0
	global_load_dwordx2 v[58:59], v[36:37], off
	global_load_dwordx2 v[60:61], v[36:37], off offset:32
	global_load_dwordx2 v[62:63], v[36:37], off offset:256
	s_nop 0
	global_load_dwordx2 v[36:37], v[36:37], off offset:288
	v_lshl_add_u64 v[48:49], s[40:41], 0, v[48:49]
	global_load_dwordx2 v[64:65], v[48:49], off
	global_load_dwordx2 v[70:71], v[48:49], off offset:32
	global_load_dwordx2 v[76:77], v[48:49], off offset:256
	v_lshlrev_b64 v[34:35], 11, v[34:35]
	global_load_dwordx2 v[48:49], v[48:49], off offset:288
	v_lshl_add_u64 v[34:35], s[94:95], 0, v[34:35]
	v_lshl_add_u64 v[34:35], v[34:35], 0, v[138:139]
	s_waitcnt vmcnt(0)
	v_lshlrev_b32_e32 v66, 16, v40
	v_and_b32_e32 v67, 0xffff0000, v40
	v_lshlrev_b32_e32 v86, 16, v58
	v_and_b32_e32 v87, 0xffff0000, v58
	v_lshlrev_b32_e32 v40, 16, v41
	v_and_b32_e32 v41, 0xffff0000, v41
	v_lshlrev_b32_e32 v58, 16, v59
	v_and_b32_e32 v59, 0xffff0000, v59
	v_pk_fma_f32 v[30:31], v[30:31], v[86:87], v[66:67]
	v_pk_fma_f32 v[32:33], v[32:33], v[58:59], v[40:41]
	v_cvt_pk_bf16_f32 v30, v30, v31
	v_lshlrev_b32_e32 v68, 16, v42
	v_cvt_pk_bf16_f32 v31, v32, v33
	v_and_b32_e32 v69, 0xffff0000, v42
	global_store_dwordx2 v[34:35], v[30:31], off
	v_lshlrev_b32_e32 v30, 16, v60
	v_and_b32_e32 v31, 0xffff0000, v60
	v_lshlrev_b32_e32 v42, 16, v43
	v_and_b32_e32 v43, 0xffff0000, v43
	v_lshlrev_b32_e32 v32, 16, v61
	v_and_b32_e32 v33, 0xffff0000, v61
	v_pk_fma_f32 v[26:27], v[26:27], v[30:31], v[68:69]
	v_pk_fma_f32 v[28:29], v[28:29], v[32:33], v[42:43]
	v_cvt_pk_bf16_f32 v26, v26, v27
	v_lshlrev_b32_e32 v72, 16, v44
	v_cvt_pk_bf16_f32 v27, v28, v29
	v_and_b32_e32 v73, 0xffff0000, v44
	global_store_dwordx2 v[34:35], v[26:27], off offset:32
	v_lshlrev_b32_e32 v26, 16, v62
	v_and_b32_e32 v27, 0xffff0000, v62
	v_lshlrev_b32_e32 v44, 16, v45
	v_and_b32_e32 v45, 0xffff0000, v45
	v_lshlrev_b32_e32 v28, 16, v63
	v_and_b32_e32 v29, 0xffff0000, v63
	v_pk_fma_f32 v[22:23], v[22:23], v[26:27], v[72:73]
	v_pk_fma_f32 v[24:25], v[24:25], v[28:29], v[44:45]
	v_cvt_pk_bf16_f32 v22, v22, v23
	v_lshlrev_b32_e32 v74, 16, v38
	v_cvt_pk_bf16_f32 v23, v24, v25
	v_and_b32_e32 v75, 0xffff0000, v38
	global_store_dwordx2 v[34:35], v[22:23], off offset:256
	v_lshlrev_b32_e32 v22, 16, v36
	v_and_b32_e32 v23, 0xffff0000, v36
	v_lshlrev_b32_e32 v38, 16, v39
	v_and_b32_e32 v39, 0xffff0000, v39
	v_lshlrev_b32_e32 v24, 16, v37
	v_and_b32_e32 v25, 0xffff0000, v37
	v_pk_fma_f32 v[14:15], v[14:15], v[22:23], v[74:75]
	v_pk_fma_f32 v[16:17], v[16:17], v[24:25], v[38:39]
	v_cvt_pk_bf16_f32 v14, v14, v15
	v_lshlrev_b32_e32 v78, 16, v52
	v_cvt_pk_bf16_f32 v15, v16, v17
	v_and_b32_e32 v79, 0xffff0000, v52
	global_store_dwordx2 v[34:35], v[14:15], off offset:288
	v_lshlrev_b64 v[14:15], 11, v[46:47]
	v_lshlrev_b32_e32 v16, 16, v64
	v_and_b32_e32 v17, 0xffff0000, v64
	v_lshlrev_b32_e32 v52, 16, v53
	v_and_b32_e32 v53, 0xffff0000, v53
	v_lshlrev_b32_e32 v22, 16, v65
	v_and_b32_e32 v23, 0xffff0000, v65
	v_lshl_add_u64 v[14:15], s[94:95], 0, v[14:15]
	v_pk_fma_f32 v[16:17], v[18:19], v[16:17], v[78:79]
	v_lshl_add_u64 v[14:15], v[14:15], 0, v[138:139]
	v_pk_fma_f32 v[20:21], v[20:21], v[22:23], v[52:53]
	v_cvt_pk_bf16_f32 v16, v16, v17
	v_lshlrev_b32_e32 v80, 16, v54
	v_cvt_pk_bf16_f32 v17, v20, v21
	v_and_b32_e32 v81, 0xffff0000, v54
	global_store_dwordx2 v[14:15], v[16:17], off
	v_lshlrev_b32_e32 v16, 16, v70
	v_and_b32_e32 v17, 0xffff0000, v70
	v_lshlrev_b32_e32 v54, 16, v55
	v_and_b32_e32 v55, 0xffff0000, v55
	v_lshlrev_b32_e32 v18, 16, v71
	v_and_b32_e32 v19, 0xffff0000, v71
	v_pk_fma_f32 v[10:11], v[10:11], v[16:17], v[80:81]
	v_pk_fma_f32 v[12:13], v[12:13], v[18:19], v[54:55]
	v_cvt_pk_bf16_f32 v10, v10, v11
	v_lshlrev_b32_e32 v82, 16, v56
	v_cvt_pk_bf16_f32 v11, v12, v13
	v_and_b32_e32 v83, 0xffff0000, v56
	global_store_dwordx2 v[14:15], v[10:11], off offset:32
	v_lshlrev_b32_e32 v10, 16, v76
	v_and_b32_e32 v11, 0xffff0000, v76
	v_lshlrev_b32_e32 v56, 16, v57
	v_and_b32_e32 v57, 0xffff0000, v57
	v_lshlrev_b32_e32 v12, 16, v77
	v_and_b32_e32 v13, 0xffff0000, v77
	v_pk_fma_f32 v[6:7], v[6:7], v[10:11], v[82:83]
	v_pk_fma_f32 v[8:9], v[8:9], v[12:13], v[56:57]
	v_cvt_pk_bf16_f32 v6, v6, v7
	v_lshlrev_b32_e32 v84, 16, v50
	v_cvt_pk_bf16_f32 v7, v8, v9
	v_and_b32_e32 v85, 0xffff0000, v50
	global_store_dwordx2 v[14:15], v[6:7], off offset:256
	v_lshlrev_b32_e32 v6, 16, v48
	v_and_b32_e32 v7, 0xffff0000, v48
	v_lshlrev_b32_e32 v50, 16, v51
	v_and_b32_e32 v51, 0xffff0000, v51
	v_lshlrev_b32_e32 v8, 16, v49
	v_and_b32_e32 v9, 0xffff0000, v49
	v_pk_fma_f32 v[2:3], v[2:3], v[6:7], v[84:85]
	v_pk_fma_f32 v[4:5], v[4:5], v[8:9], v[50:51]
	v_cvt_pk_bf16_f32 v2, v2, v3
	s_nop 0
	v_cvt_pk_bf16_f32 v3, v4, v5
	global_store_dwordx2 v[14:15], v[2:3], off offset:288
	s_cbranch_vccz .LBB0_3163
	s_waitcnt vmcnt(0)
	s_cmpk_gt_u32 s22, 0xff
	s_cbranch_scc1 .LBB0_3174
	s_barrier

.LBB0_3184:
	v_readlane_b32 s48, v253, 0
	s_ashr_i32 s17, s16, 31
	v_readlane_b32 s54, v253, 6
	v_readlane_b32 s55, v253, 7
	v_readlane_b32 s62, v253, 14
	v_readlane_b32 s63, v253, 15
	s_lshl_b64 s[18:19], s[16:17], 17
	s_mov_b64 s[54:55], s[62:63]
	s_add_u32 s18, s54, s18
	v_cmp_lt_i64_e32 vcc, s[12:13], v[6:7]
	s_addc_u32 s19, s55, s19
	ds_read_b128 v[14:17], v10
	ds_read_b128 v[18:21], v10 offset:1024
	ds_read_b128 v[22:25], v10 offset:2048
	ds_read_b128 v[26:29], v10 offset:3072
	v_readlane_b32 s49, v253, 1
	v_readlane_b32 s50, v253, 2
	v_readlane_b32 s51, v253, 3
	s_and_b64 s[20:21], vcc, exec
	s_cselect_b32 s29, s19, s23
	s_cselect_b32 s28, s18, s22
	s_ashr_i32 s15, s14, 31
	v_readlane_b32 s48, v253, 26
	s_lshl_b64 s[20:21], s[14:15], 17
	v_readlane_b32 s50, v253, 28
	v_readlane_b32 s51, v253, 29
	s_add_u32 s20, s50, s20
	s_addc_u32 s21, s51, s21
	s_and_b64 s[26:27], vcc, exec
	v_readlane_b32 s52, v253, 4
	v_readlane_b32 s53, v253, 5
	v_readlane_b32 s56, v253, 8
	v_readlane_b32 s57, v253, 9
	v_readlane_b32 s58, v253, 10
	v_readlane_b32 s59, v253, 11
	v_readlane_b32 s60, v253, 12
	v_readlane_b32 s61, v253, 13
	v_readlane_b32 s49, v253, 27
	s_cselect_b32 s27, s21, s25
	s_cselect_b32 s26, s20, s24
	s_add_u32 s48, s22, 0x10080
	s_addc_u32 s49, s23, 0
	s_mov_b32 m0, s44
	v_lshl_add_u64 v[62:63], s[48:49], 0, v[2:3]
	ds_read_b128 v[30:33], v11
	ds_read_b128 v[34:37], v11 offset:1024
	ds_read_b128 v[38:41], v11 offset:2048
	ds_read_b128 v[42:45], v11 offset:3072
	ds_read_b128 v[46:49], v11 offset:4096
	ds_read_b128 v[50:53], v11 offset:5120
	ds_read_b128 v[54:57], v11 offset:6144
	ds_read_b128 v[58:61], v11 offset:7168
	global_load_lds_dwordx4 v[62:63], off
	v_lshl_add_u64 v[62:63], s[48:49], 0, v[4:5]
	s_mov_b32 m0, s45
	s_nop 0
	global_load_lds_dwordx4 v[62:63], off
	s_waitcnt lgkmcnt(8)
	s_barrier
	s_waitcnt lgkmcnt(0)
	s_nop 0
	s_waitcnt lgkmcnt(0)
	v_mfma_f32_16x16x32_bf16 v[62:65], v[14:17], v[30:33], 0
	v_mfma_f32_16x16x32_bf16 v[66:69], v[22:25], v[30:33], 0
	v_mfma_f32_16x16x32_bf16 v[70:73], v[14:17], v[38:41], 0
	v_mfma_f32_16x16x32_bf16 v[74:77], v[22:25], v[38:41], 0
	v_mfma_f32_16x16x32_bf16 v[78:81], v[14:17], v[46:49], 0
	v_mfma_f32_16x16x32_bf16 v[82:85], v[22:25], v[46:49], 0
	v_mfma_f32_16x16x32_bf16 v[86:89], v[14:17], v[54:57], 0
	v_mfma_f32_16x16x32_bf16 v[90:93], v[22:25], v[54:57], 0
	v_mfma_f32_16x16x32_bf16 v[62:65], v[18:21], v[34:37], v[62:65]
	v_mfma_f32_16x16x32_bf16 v[66:69], v[26:29], v[34:37], v[66:69]
	v_mfma_f32_16x16x32_bf16 v[70:73], v[18:21], v[42:45], v[70:73]
	v_mfma_f32_16x16x32_bf16 v[74:77], v[26:29], v[42:45], v[74:77]
	v_mfma_f32_16x16x32_bf16 v[78:81], v[18:21], v[50:53], v[78:81]
	v_mfma_f32_16x16x32_bf16 v[82:85], v[26:29], v[50:53], v[82:85]
	v_mfma_f32_16x16x32_bf16 v[86:89], v[18:21], v[58:61], v[86:89]
	v_mfma_f32_16x16x32_bf16 v[90:93], v[26:29], v[58:61], v[90:93]
	s_nop 0
	s_barrier
	v_lshl_add_u64 v[208:209], s[24:25], 0, v[2:3]
	s_add_i32 s48, s43, s33
	v_lshl_add_u64 v[110:111], v[208:209], 0, s[6:7]
	s_mov_b32 m0, s48
	v_lshl_add_u64 v[210:211], s[24:25], 0, v[4:5]
	s_add_i32 s15, s48, 0x2000
	ds_read_b128 v[94:97], v12
	ds_read_b128 v[98:101], v12 offset:1024
	ds_read_b128 v[102:105], v12 offset:2048
	ds_read_b128 v[106:109], v12 offset:3072
	global_load_lds_dwordx4 v[110:111], off
	v_lshl_add_u64 v[110:111], v[210:211], 0, s[6:7]
	s_mov_b32 m0, s15
	s_nop 0
	global_load_lds_dwordx4 v[110:111], off
	s_barrier
	s_waitcnt lgkmcnt(0)
	s_nop 0
	s_waitcnt lgkmcnt(0)
	v_mfma_f32_16x16x32_bf16 v[110:113], v[94:97], v[30:33], 0
	v_mfma_f32_16x16x32_bf16 v[30:33], v[102:105], v[30:33], 0
	v_mfma_f32_16x16x32_bf16 v[110:113], v[98:101], v[34:37], v[110:113]
	v_mfma_f32_16x16x32_bf16 v[30:33], v[106:109], v[34:37], v[30:33]
	v_mfma_f32_16x16x32_bf16 v[34:37], v[94:97], v[38:41], 0
	v_mfma_f32_16x16x32_bf16 v[38:41], v[102:105], v[38:41], 0
	v_mfma_f32_16x16x32_bf16 v[34:37], v[98:101], v[42:45], v[34:37]
	v_mfma_f32_16x16x32_bf16 v[38:41], v[106:109], v[42:45], v[38:41]
	v_mfma_f32_16x16x32_bf16 v[42:45], v[94:97], v[46:49], 0
	v_mfma_f32_16x16x32_bf16 v[46:49], v[102:105], v[46:49], 0
	v_mfma_f32_16x16x32_bf16 v[42:45], v[98:101], v[50:53], v[42:45]
	v_mfma_f32_16x16x32_bf16 v[46:49], v[106:109], v[50:53], v[46:49]
	v_mfma_f32_16x16x32_bf16 v[50:53], v[94:97], v[54:57], 0
	v_mfma_f32_16x16x32_bf16 v[54:57], v[102:105], v[54:57], 0
	v_mfma_f32_16x16x32_bf16 v[50:53], v[98:101], v[58:61], v[50:53]
	v_mfma_f32_16x16x32_bf16 v[54:57], v[106:109], v[58:61], v[54:57]
	s_nop 0
	v_lshl_add_u64 v[212:213], s[22:23], 0, v[2:3]
	s_mov_b32 m0, s5
	v_lshl_add_u64 v[142:143], v[212:213], 0, s[6:7]
	v_lshl_add_u64 v[214:215], s[22:23], 0, v[4:5]
	s_barrier
	ds_read_b128 v[58:61], v11 offset:16384
	ds_read_b128 v[114:117], v11 offset:17408
	ds_read_b128 v[118:121], v11 offset:18432
	ds_read_b128 v[122:125], v11 offset:19456
	ds_read_b128 v[126:129], v11 offset:20480
	ds_read_b128 v[130:133], v11 offset:21504
	ds_read_b128 v[134:137], v11 offset:22528
	ds_read_b128 v[138:141], v11 offset:23552
	global_load_lds_dwordx4 v[142:143], off
	v_lshl_add_u64 v[142:143], v[214:215], 0, s[6:7]
	s_mov_b32 m0, s34
	s_nop 0
	global_load_lds_dwordx4 v[142:143], off
	s_barrier
	s_waitcnt lgkmcnt(0)
	s_nop 0
	s_waitcnt lgkmcnt(0)
	v_mfma_f32_16x16x32_bf16 v[142:145], v[14:17], v[58:61], 0
	v_mfma_f32_16x16x32_bf16 v[150:153], v[14:17], v[118:121], 0
	v_mfma_f32_16x16x32_bf16 v[158:161], v[14:17], v[126:129], 0
	v_mfma_f32_16x16x32_bf16 v[14:17], v[14:17], v[134:137], 0
	v_mfma_f32_16x16x32_bf16 v[142:145], v[18:21], v[114:117], v[142:145]
	v_mfma_f32_16x16x32_bf16 v[146:149], v[22:25], v[58:61], 0
	v_mfma_f32_16x16x32_bf16 v[150:153], v[18:21], v[122:125], v[150:153]
	v_mfma_f32_16x16x32_bf16 v[154:157], v[22:25], v[118:121], 0
	v_mfma_f32_16x16x32_bf16 v[158:161], v[18:21], v[130:133], v[158:161]
	v_mfma_f32_16x16x32_bf16 v[162:165], v[22:25], v[126:129], 0
	v_mfma_f32_16x16x32_bf16 v[14:17], v[18:21], v[138:141], v[14:17]
	v_mfma_f32_16x16x32_bf16 v[18:21], v[22:25], v[134:137], 0
	v_mfma_f32_16x16x32_bf16 v[146:149], v[26:29], v[114:117], v[146:149]
	v_mfma_f32_16x16x32_bf16 v[154:157], v[26:29], v[122:125], v[154:157]
	v_mfma_f32_16x16x32_bf16 v[162:165], v[26:29], v[130:133], v[162:165]
	v_mfma_f32_16x16x32_bf16 v[18:21], v[26:29], v[138:141], v[18:21]
	s_nop 0
	s_barrier
	s_add_u32 s50, s24, 0x10100
	s_addc_u32 s51, s25, 0
	s_add_i32 s49, s46, s33
	v_lshl_add_u64 v[22:23], s[50:51], 0, v[2:3]
	s_mov_b32 m0, s49
	s_add_i32 s17, s49, 0x2000
	global_load_lds_dwordx4 v[22:23], off
	v_lshl_add_u64 v[22:23], s[50:51], 0, v[4:5]
	s_mov_b32 m0, s17
	s_nop 0
	global_load_lds_dwordx4 v[22:23], off
	s_waitcnt vmcnt(6)
	s_barrier
	s_nop 0
	v_mfma_f32_16x16x32_bf16 v[22:25], v[94:97], v[58:61], 0
	v_mfma_f32_16x16x32_bf16 v[26:29], v[102:105], v[58:61], 0
	v_mfma_f32_16x16x32_bf16 v[22:25], v[98:101], v[114:117], v[22:25]
	v_mfma_f32_16x16x32_bf16 v[26:29], v[106:109], v[114:117], v[26:29]
	v_mfma_f32_16x16x32_bf16 v[58:61], v[94:97], v[118:121], 0
	v_mfma_f32_16x16x32_bf16 v[114:117], v[102:105], v[118:121], 0
	v_mfma_f32_16x16x32_bf16 v[118:121], v[94:97], v[126:129], 0
	v_mfma_f32_16x16x32_bf16 v[94:97], v[94:97], v[134:137], 0
	v_mfma_f32_16x16x32_bf16 v[58:61], v[98:101], v[122:125], v[58:61]
	v_mfma_f32_16x16x32_bf16 v[114:117], v[106:109], v[122:125], v[114:117]
	v_mfma_f32_16x16x32_bf16 v[118:121], v[98:101], v[130:133], v[118:121]
	v_mfma_f32_16x16x32_bf16 v[122:125], v[102:105], v[126:129], 0
	v_mfma_f32_16x16x32_bf16 v[94:97], v[98:101], v[138:141], v[94:97]
	v_mfma_f32_16x16x32_bf16 v[98:101], v[102:105], v[134:137], 0
	v_mfma_f32_16x16x32_bf16 v[122:125], v[106:109], v[130:133], v[122:125]
	v_mfma_f32_16x16x32_bf16 v[98:101], v[106:109], v[138:141], v[98:101]
	s_nop 0
	s_add_i32 s52, 0, 0x18000
	v_add_u32_e32 v13, s52, v1
	s_barrier
	ds_read_b128 v[102:105], v13
	ds_read_b128 v[106:109], v13 offset:1024
	ds_read_b128 v[126:129], v13 offset:2048
	ds_read_b128 v[130:133], v13 offset:3072
	s_add_u32 s50, s22, 0x10100
	s_addc_u32 s51, s23, 0
	s_mov_b32 m0, s35
	v_lshl_add_u64 v[192:193], s[50:51], 0, v[2:3]
	ds_read_b128 v[134:137], v11 offset:32768
	ds_read_b128 v[138:141], v11 offset:33792
	ds_read_b128 v[166:169], v11 offset:34816
	ds_read_b128 v[170:173], v11 offset:35840
	ds_read_b128 v[174:177], v11 offset:36864
	ds_read_b128 v[178:181], v11 offset:37888
	ds_read_b128 v[184:187], v11 offset:38912
	ds_read_b128 v[188:191], v11 offset:39936
	global_load_lds_dwordx4 v[192:193], off
	v_lshl_add_u64 v[192:193], s[50:51], 0, v[4:5]
	s_mov_b32 m0, s36
	s_nop 0
	global_load_lds_dwordx4 v[192:193], off
	s_waitcnt lgkmcnt(8)
	s_barrier
	s_waitcnt lgkmcnt(0)
	s_nop 0
	s_waitcnt lgkmcnt(0)
	v_mfma_f32_16x16x32_bf16 v[62:65], v[102:105], v[134:137], v[62:65]
	v_mfma_f32_16x16x32_bf16 v[66:69], v[126:129], v[134:137], v[66:69]
	v_mfma_f32_16x16x32_bf16 v[70:73], v[102:105], v[166:169], v[70:73]
	v_mfma_f32_16x16x32_bf16 v[74:77], v[126:129], v[166:169], v[74:77]
	v_mfma_f32_16x16x32_bf16 v[78:81], v[102:105], v[174:177], v[78:81]
	v_mfma_f32_16x16x32_bf16 v[82:85], v[126:129], v[174:177], v[82:85]
	v_mfma_f32_16x16x32_bf16 v[86:89], v[102:105], v[184:187], v[86:89]
	v_mfma_f32_16x16x32_bf16 v[90:93], v[126:129], v[184:187], v[90:93]
	v_mfma_f32_16x16x32_bf16 v[62:65], v[106:109], v[138:141], v[62:65]
	v_mfma_f32_16x16x32_bf16 v[66:69], v[130:133], v[138:141], v[66:69]
	v_mfma_f32_16x16x32_bf16 v[70:73], v[106:109], v[170:173], v[70:73]
	v_mfma_f32_16x16x32_bf16 v[74:77], v[130:133], v[170:173], v[74:77]
	v_mfma_f32_16x16x32_bf16 v[78:81], v[106:109], v[178:181], v[78:81]
	v_mfma_f32_16x16x32_bf16 v[82:85], v[130:133], v[178:181], v[82:85]
	v_mfma_f32_16x16x32_bf16 v[86:89], v[106:109], v[188:191], v[86:89]
	v_mfma_f32_16x16x32_bf16 v[90:93], v[130:133], v[188:191], v[90:93]
	s_nop 0
	s_barrier
	s_add_i32 s54, 0, 0x1c000
	s_add_i32 s51, s52, s33
	v_add_u32_e32 v183, s54, v1
	v_lshl_add_u64 v[208:209], v[208:209], 0, s[10:11]
	s_mov_b32 m0, s51
	s_add_i32 s50, s51, 0x2000
	ds_read_b128 v[192:195], v183
	ds_read_b128 v[196:199], v183 offset:1024
	ds_read_b128 v[200:203], v183 offset:2048
	ds_read_b128 v[204:207], v183 offset:3072
	global_load_lds_dwordx4 v[208:209], off
	v_lshl_add_u64 v[208:209], v[210:211], 0, s[10:11]
	s_mov_b32 m0, s50
	s_nop 0
	global_load_lds_dwordx4 v[208:209], off
	s_barrier
	s_waitcnt lgkmcnt(0)
	s_nop 0
	s_waitcnt lgkmcnt(0)
	v_mfma_f32_16x16x32_bf16 v[110:113], v[192:195], v[134:137], v[110:113]
	v_mfma_f32_16x16x32_bf16 v[30:33], v[200:203], v[134:137], v[30:33]
	v_mfma_f32_16x16x32_bf16 v[34:37], v[192:195], v[166:169], v[34:37]
	v_mfma_f32_16x16x32_bf16 v[38:41], v[200:203], v[166:169], v[38:41]
	v_mfma_f32_16x16x32_bf16 v[42:45], v[192:195], v[174:177], v[42:45]
	v_mfma_f32_16x16x32_bf16 v[46:49], v[200:203], v[174:177], v[46:49]
	v_mfma_f32_16x16x32_bf16 v[50:53], v[192:195], v[184:187], v[50:53]
	v_mfma_f32_16x16x32_bf16 v[54:57], v[200:203], v[184:187], v[54:57]
	v_mfma_f32_16x16x32_bf16 v[110:113], v[196:199], v[138:141], v[110:113]
	v_mfma_f32_16x16x32_bf16 v[30:33], v[204:207], v[138:141], v[30:33]
	v_mfma_f32_16x16x32_bf16 v[34:37], v[196:199], v[170:173], v[34:37]
	v_mfma_f32_16x16x32_bf16 v[38:41], v[204:207], v[170:173], v[38:41]
	v_mfma_f32_16x16x32_bf16 v[42:45], v[196:199], v[178:181], v[42:45]
	v_mfma_f32_16x16x32_bf16 v[46:49], v[204:207], v[178:181], v[46:49]
	v_mfma_f32_16x16x32_bf16 v[50:53], v[196:199], v[188:191], v[50:53]
	v_mfma_f32_16x16x32_bf16 v[54:57], v[204:207], v[188:191], v[54:57]
	s_nop 0
	s_mov_b32 m0, s39
	v_lshl_add_u64 v[208:209], v[212:213], 0, s[10:11]
	s_barrier
	ds_read_b128 v[134:137], v11 offset:49152
	ds_read_b128 v[138:141], v11 offset:50176
	ds_read_b128 v[166:169], v11 offset:51200
	ds_read_b128 v[170:173], v11 offset:52224
	ds_read_b128 v[174:177], v11 offset:53248
	ds_read_b128 v[178:181], v11 offset:54272
	ds_read_b128 v[184:187], v11 offset:55296
	ds_read_b128 v[188:191], v11 offset:56320
	global_load_lds_dwordx4 v[208:209], off
	v_lshl_add_u64 v[208:209], v[214:215], 0, s[10:11]
	s_mov_b32 m0, s40
	s_nop 0
	global_load_lds_dwordx4 v[208:209], off
	s_barrier
	s_waitcnt lgkmcnt(0)
	s_nop 0
	s_waitcnt lgkmcnt(0)
	v_mfma_f32_16x16x32_bf16 v[142:145], v[102:105], v[134:137], v[142:145]
	v_mfma_f32_16x16x32_bf16 v[146:149], v[126:129], v[134:137], v[146:149]
	v_mfma_f32_16x16x32_bf16 v[150:153], v[102:105], v[166:169], v[150:153]
	v_mfma_f32_16x16x32_bf16 v[154:157], v[126:129], v[166:169], v[154:157]
	v_mfma_f32_16x16x32_bf16 v[158:161], v[102:105], v[174:177], v[158:161]
	v_mfma_f32_16x16x32_bf16 v[162:165], v[126:129], v[174:177], v[162:165]
	v_mfma_f32_16x16x32_bf16 v[14:17], v[102:105], v[184:187], v[14:17]
	v_mfma_f32_16x16x32_bf16 v[18:21], v[126:129], v[184:187], v[18:21]
	v_mfma_f32_16x16x32_bf16 v[142:145], v[106:109], v[138:141], v[142:145]
	v_mfma_f32_16x16x32_bf16 v[146:149], v[130:133], v[138:141], v[146:149]
	v_mfma_f32_16x16x32_bf16 v[150:153], v[106:109], v[170:173], v[150:153]
	v_mfma_f32_16x16x32_bf16 v[154:157], v[130:133], v[170:173], v[154:157]
	v_mfma_f32_16x16x32_bf16 v[158:161], v[106:109], v[178:181], v[158:161]
	v_mfma_f32_16x16x32_bf16 v[162:165], v[130:133], v[178:181], v[162:165]
	v_mfma_f32_16x16x32_bf16 v[14:17], v[106:109], v[188:191], v[14:17]
	v_mfma_f32_16x16x32_bf16 v[18:21], v[130:133], v[188:191], v[18:21]
	s_nop 0
	s_barrier
	s_add_u32 s52, s24, 0x10180
	s_addc_u32 s53, s25, 0
	s_add_i32 s25, s54, s33
	v_lshl_add_u64 v[102:103], s[52:53], 0, v[2:3]
	s_mov_b32 m0, s25
	s_add_i32 s24, s25, 0x2000
	global_load_lds_dwordx4 v[102:103], off
	v_lshl_add_u64 v[102:103], s[52:53], 0, v[4:5]
	s_mov_b32 m0, s24
	s_nop 0
	global_load_lds_dwordx4 v[102:103], off
	s_waitcnt vmcnt(6)
	s_barrier
	s_nop 0
	v_mfma_f32_16x16x32_bf16 v[22:25], v[192:195], v[134:137], v[22:25]
	v_mfma_f32_16x16x32_bf16 v[26:29], v[200:203], v[134:137], v[26:29]
	v_mfma_f32_16x16x32_bf16 v[58:61], v[192:195], v[166:169], v[58:61]
	v_mfma_f32_16x16x32_bf16 v[102:105], v[200:203], v[166:169], v[114:117]
	v_mfma_f32_16x16x32_bf16 v[106:109], v[192:195], v[174:177], v[118:121]
	v_mfma_f32_16x16x32_bf16 v[114:117], v[200:203], v[174:177], v[122:125]
	v_mfma_f32_16x16x32_bf16 v[94:97], v[192:195], v[184:187], v[94:97]
	v_mfma_f32_16x16x32_bf16 v[98:101], v[200:203], v[184:187], v[98:101]
	v_mfma_f32_16x16x32_bf16 v[22:25], v[196:199], v[138:141], v[22:25]
	v_mfma_f32_16x16x32_bf16 v[26:29], v[204:207], v[138:141], v[26:29]
	v_mfma_f32_16x16x32_bf16 v[58:61], v[196:199], v[170:173], v[58:61]
	v_mfma_f32_16x16x32_bf16 v[102:105], v[204:207], v[170:173], v[102:105]
	v_mfma_f32_16x16x32_bf16 v[106:109], v[196:199], v[178:181], v[106:109]
	v_mfma_f32_16x16x32_bf16 v[114:117], v[204:207], v[178:181], v[114:117]
	v_mfma_f32_16x16x32_bf16 v[94:97], v[196:199], v[188:191], v[94:97]
	v_mfma_f32_16x16x32_bf16 v[98:101], v[204:207], v[188:191], v[98:101]
	s_nop 0
	s_barrier
	ds_read_b128 v[118:121], v10
	ds_read_b128 v[122:125], v10 offset:1024
	ds_read_b128 v[126:129], v10 offset:2048
	ds_read_b128 v[130:133], v10 offset:3072
	s_add_u32 s22, s22, 0x10180
	s_addc_u32 s23, s23, 0
	s_mov_b32 m0, s44
	v_lshl_add_u64 v[192:193], s[22:23], 0, v[2:3]
	ds_read_b128 v[134:137], v11
	ds_read_b128 v[138:141], v11 offset:1024
	ds_read_b128 v[166:169], v11 offset:2048
	ds_read_b128 v[170:173], v11 offset:3072
	ds_read_b128 v[174:177], v11 offset:4096
	ds_read_b128 v[178:181], v11 offset:5120
	ds_read_b128 v[184:187], v11 offset:6144
	ds_read_b128 v[188:191], v11 offset:7168
	global_load_lds_dwordx4 v[192:193], off
	v_lshl_add_u64 v[192:193], s[22:23], 0, v[4:5]
	s_mov_b32 m0, s45
	s_nop 0
	global_load_lds_dwordx4 v[192:193], off
	s_waitcnt lgkmcnt(8)
	s_barrier
	s_waitcnt lgkmcnt(0)
	s_nop 0
	s_waitcnt lgkmcnt(0)
	v_mfma_f32_16x16x32_bf16 v[62:65], v[118:121], v[134:137], v[62:65]
	v_mfma_f32_16x16x32_bf16 v[66:69], v[126:129], v[134:137], v[66:69]
	v_mfma_f32_16x16x32_bf16 v[70:73], v[118:121], v[166:169], v[70:73]
	v_mfma_f32_16x16x32_bf16 v[74:77], v[126:129], v[166:169], v[74:77]
	v_mfma_f32_16x16x32_bf16 v[78:81], v[118:121], v[174:177], v[78:81]
	v_mfma_f32_16x16x32_bf16 v[82:85], v[126:129], v[174:177], v[82:85]
	v_mfma_f32_16x16x32_bf16 v[86:89], v[118:121], v[184:187], v[86:89]
	v_mfma_f32_16x16x32_bf16 v[90:93], v[126:129], v[184:187], v[90:93]
	v_mfma_f32_16x16x32_bf16 v[62:65], v[122:125], v[138:141], v[62:65]
	v_mfma_f32_16x16x32_bf16 v[66:69], v[130:133], v[138:141], v[66:69]
	v_mfma_f32_16x16x32_bf16 v[70:73], v[122:125], v[170:173], v[70:73]
	v_mfma_f32_16x16x32_bf16 v[74:77], v[130:133], v[170:173], v[74:77]
	v_mfma_f32_16x16x32_bf16 v[78:81], v[122:125], v[178:181], v[78:81]
	v_mfma_f32_16x16x32_bf16 v[82:85], v[130:133], v[178:181], v[82:85]
	v_mfma_f32_16x16x32_bf16 v[86:89], v[122:125], v[188:191], v[86:89]
	v_mfma_f32_16x16x32_bf16 v[90:93], v[130:133], v[188:191], v[90:93]
	s_nop 0
	s_barrier
	s_mov_b32 m0, s48
	v_lshl_add_u64 v[208:209], s[26:27], 0, v[2:3]
	ds_read_b128 v[192:195], v12
	ds_read_b128 v[196:199], v12 offset:1024
	ds_read_b128 v[200:203], v12 offset:2048
	ds_read_b128 v[204:207], v12 offset:3072
	global_load_lds_dwordx4 v[208:209], off
	v_lshl_add_u64 v[210:211], s[26:27], 0, v[4:5]
	s_mov_b32 m0, s15
	s_nop 0
	global_load_lds_dwordx4 v[210:211], off
	s_barrier
	s_waitcnt lgkmcnt(0)
	s_nop 0
	s_waitcnt lgkmcnt(0)
	v_mfma_f32_16x16x32_bf16 v[110:113], v[192:195], v[134:137], v[110:113]
	v_mfma_f32_16x16x32_bf16 v[30:33], v[200:203], v[134:137], v[30:33]
	v_mfma_f32_16x16x32_bf16 v[34:37], v[192:195], v[166:169], v[34:37]
	v_mfma_f32_16x16x32_bf16 v[38:41], v[200:203], v[166:169], v[38:41]
	v_mfma_f32_16x16x32_bf16 v[42:45], v[192:195], v[174:177], v[42:45]
	v_mfma_f32_16x16x32_bf16 v[46:49], v[200:203], v[174:177], v[46:49]
	v_mfma_f32_16x16x32_bf16 v[50:53], v[192:195], v[184:187], v[50:53]
	v_mfma_f32_16x16x32_bf16 v[54:57], v[200:203], v[184:187], v[54:57]
	v_mfma_f32_16x16x32_bf16 v[110:113], v[196:199], v[138:141], v[110:113]
	v_mfma_f32_16x16x32_bf16 v[30:33], v[204:207], v[138:141], v[30:33]
	v_mfma_f32_16x16x32_bf16 v[34:37], v[196:199], v[170:173], v[34:37]
	v_mfma_f32_16x16x32_bf16 v[38:41], v[204:207], v[170:173], v[38:41]
	v_mfma_f32_16x16x32_bf16 v[42:45], v[196:199], v[178:181], v[42:45]
	v_mfma_f32_16x16x32_bf16 v[46:49], v[204:207], v[178:181], v[46:49]
	v_mfma_f32_16x16x32_bf16 v[50:53], v[196:199], v[188:191], v[50:53]
	v_mfma_f32_16x16x32_bf16 v[54:57], v[204:207], v[188:191], v[54:57]
	s_nop 0
	s_mov_b32 m0, s5
	v_lshl_add_u64 v[212:213], s[28:29], 0, v[2:3]
	s_barrier
	ds_read_b128 v[134:137], v11 offset:16384
	ds_read_b128 v[138:141], v11 offset:17408
	ds_read_b128 v[166:169], v11 offset:18432
	ds_read_b128 v[170:173], v11 offset:19456
	ds_read_b128 v[174:177], v11 offset:20480
	ds_read_b128 v[178:181], v11 offset:21504
	ds_read_b128 v[184:187], v11 offset:22528
	ds_read_b128 v[188:191], v11 offset:23552
	global_load_lds_dwordx4 v[212:213], off
	v_lshl_add_u64 v[214:215], s[28:29], 0, v[4:5]
	s_mov_b32 m0, s34
	s_nop 0
	global_load_lds_dwordx4 v[214:215], off
	s_barrier
	s_waitcnt lgkmcnt(0)
	s_nop 0
	s_waitcnt lgkmcnt(0)
	v_mfma_f32_16x16x32_bf16 v[142:145], v[118:121], v[134:137], v[142:145]
	v_mfma_f32_16x16x32_bf16 v[146:149], v[126:129], v[134:137], v[146:149]
	v_mfma_f32_16x16x32_bf16 v[150:153], v[118:121], v[166:169], v[150:153]
	v_mfma_f32_16x16x32_bf16 v[154:157], v[126:129], v[166:169], v[154:157]
	v_mfma_f32_16x16x32_bf16 v[158:161], v[118:121], v[174:177], v[158:161]
	v_mfma_f32_16x16x32_bf16 v[162:165], v[126:129], v[174:177], v[162:165]
	v_mfma_f32_16x16x32_bf16 v[14:17], v[118:121], v[184:187], v[14:17]
	v_mfma_f32_16x16x32_bf16 v[18:21], v[126:129], v[184:187], v[18:21]
	v_mfma_f32_16x16x32_bf16 v[142:145], v[122:125], v[138:141], v[142:145]
	v_mfma_f32_16x16x32_bf16 v[146:149], v[130:133], v[138:141], v[146:149]
	v_mfma_f32_16x16x32_bf16 v[150:153], v[122:125], v[170:173], v[150:153]
	v_mfma_f32_16x16x32_bf16 v[154:157], v[130:133], v[170:173], v[154:157]
	v_mfma_f32_16x16x32_bf16 v[158:161], v[122:125], v[178:181], v[158:161]
	v_mfma_f32_16x16x32_bf16 v[162:165], v[130:133], v[178:181], v[162:165]
	v_mfma_f32_16x16x32_bf16 v[14:17], v[122:125], v[188:191], v[14:17]
	v_mfma_f32_16x16x32_bf16 v[18:21], v[130:133], v[188:191], v[18:21]
	s_nop 0
	s_barrier
	s_add_u32 s22, s26, 0x10000
	s_addc_u32 s23, s27, 0
	s_mov_b32 m0, s49
	v_lshl_add_u64 v[118:119], s[22:23], 0, v[2:3]
	global_load_lds_dwordx4 v[118:119], off
	v_lshl_add_u64 v[118:119], s[22:23], 0, v[4:5]
	s_mov_b32 m0, s17
	s_nop 0
	global_load_lds_dwordx4 v[118:119], off
	s_waitcnt vmcnt(6)
	s_barrier
	s_nop 0
	v_mfma_f32_16x16x32_bf16 v[22:25], v[192:195], v[134:137], v[22:25]
	v_mfma_f32_16x16x32_bf16 v[26:29], v[200:203], v[134:137], v[26:29]
	v_mfma_f32_16x16x32_bf16 v[58:61], v[192:195], v[166:169], v[58:61]
	v_mfma_f32_16x16x32_bf16 v[102:105], v[200:203], v[166:169], v[102:105]
	v_mfma_f32_16x16x32_bf16 v[106:109], v[192:195], v[174:177], v[106:109]
	v_mfma_f32_16x16x32_bf16 v[114:117], v[200:203], v[174:177], v[114:117]
	v_mfma_f32_16x16x32_bf16 v[94:97], v[192:195], v[184:187], v[94:97]
	v_mfma_f32_16x16x32_bf16 v[98:101], v[200:203], v[184:187], v[98:101]
	v_mfma_f32_16x16x32_bf16 v[22:25], v[196:199], v[138:141], v[22:25]
	v_mfma_f32_16x16x32_bf16 v[26:29], v[204:207], v[138:141], v[26:29]
	v_mfma_f32_16x16x32_bf16 v[58:61], v[196:199], v[170:173], v[58:61]
	v_mfma_f32_16x16x32_bf16 v[102:105], v[204:207], v[170:173], v[102:105]
	v_mfma_f32_16x16x32_bf16 v[106:109], v[196:199], v[178:181], v[106:109]
	v_mfma_f32_16x16x32_bf16 v[114:117], v[204:207], v[178:181], v[114:117]
	v_mfma_f32_16x16x32_bf16 v[94:97], v[196:199], v[188:191], v[94:97]
	v_mfma_f32_16x16x32_bf16 v[98:101], v[204:207], v[188:191], v[98:101]
	s_nop 0
	s_barrier
	ds_read_b128 v[118:121], v13
	ds_read_b128 v[122:125], v13 offset:1024
	ds_read_b128 v[126:129], v13 offset:2048
	ds_read_b128 v[130:133], v13 offset:3072
	s_add_u32 s22, s28, 0x10000
	s_addc_u32 s23, s29, 0
	s_mov_b32 m0, s35
	v_lshl_add_u64 v[192:193], s[22:23], 0, v[2:3]
	ds_read_b128 v[134:137], v11 offset:32768
	ds_read_b128 v[138:141], v11 offset:33792
	ds_read_b128 v[166:169], v11 offset:34816
	ds_read_b128 v[170:173], v11 offset:35840
	ds_read_b128 v[174:177], v11 offset:36864
	ds_read_b128 v[178:181], v11 offset:37888
	ds_read_b128 v[184:187], v11 offset:38912
	ds_read_b128 v[188:191], v11 offset:39936
	global_load_lds_dwordx4 v[192:193], off
	v_lshl_add_u64 v[192:193], s[22:23], 0, v[4:5]
	s_mov_b32 m0, s36
	s_nop 0
	global_load_lds_dwordx4 v[192:193], off
	s_waitcnt lgkmcnt(8)
	s_barrier
	s_waitcnt lgkmcnt(0)
	s_nop 0
	s_waitcnt lgkmcnt(0)
	v_mfma_f32_16x16x32_bf16 v[62:65], v[118:121], v[134:137], v[62:65]
	v_mfma_f32_16x16x32_bf16 v[66:69], v[126:129], v[134:137], v[66:69]
	v_mfma_f32_16x16x32_bf16 v[70:73], v[118:121], v[166:169], v[70:73]
	v_mfma_f32_16x16x32_bf16 v[74:77], v[126:129], v[166:169], v[74:77]
	v_mfma_f32_16x16x32_bf16 v[78:81], v[118:121], v[174:177], v[78:81]
	v_mfma_f32_16x16x32_bf16 v[82:85], v[126:129], v[174:177], v[82:85]
	v_mfma_f32_16x16x32_bf16 v[86:89], v[118:121], v[184:187], v[86:89]
	v_mfma_f32_16x16x32_bf16 v[90:93], v[126:129], v[184:187], v[90:93]
	v_mfma_f32_16x16x32_bf16 v[62:65], v[122:125], v[138:141], v[62:65]
	v_mfma_f32_16x16x32_bf16 v[66:69], v[130:133], v[138:141], v[66:69]
	v_mfma_f32_16x16x32_bf16 v[70:73], v[122:125], v[170:173], v[70:73]
	v_mfma_f32_16x16x32_bf16 v[74:77], v[130:133], v[170:173], v[74:77]
	v_mfma_f32_16x16x32_bf16 v[78:81], v[122:125], v[178:181], v[78:81]
	v_mfma_f32_16x16x32_bf16 v[82:85], v[130:133], v[178:181], v[82:85]
	v_mfma_f32_16x16x32_bf16 v[86:89], v[122:125], v[188:191], v[86:89]
	v_mfma_f32_16x16x32_bf16 v[90:93], v[130:133], v[188:191], v[90:93]
	s_nop 0
	s_barrier
	s_mov_b32 m0, s51
	v_lshl_add_u64 v[208:209], v[208:209], 0, s[2:3]
	ds_read_b128 v[192:195], v183
	ds_read_b128 v[196:199], v183 offset:1024
	ds_read_b128 v[200:203], v183 offset:2048
	ds_read_b128 v[204:207], v183 offset:3072
	global_load_lds_dwordx4 v[208:209], off
	v_lshl_add_u64 v[208:209], v[210:211], 0, s[2:3]
	s_mov_b32 m0, s50
	s_nop 0
	global_load_lds_dwordx4 v[208:209], off
	s_barrier
	s_waitcnt lgkmcnt(0)
	s_nop 0
	s_waitcnt lgkmcnt(0)
	v_mfma_f32_16x16x32_bf16 v[110:113], v[192:195], v[134:137], v[110:113]
	v_mfma_f32_16x16x32_bf16 v[30:33], v[200:203], v[134:137], v[30:33]
	v_mfma_f32_16x16x32_bf16 v[34:37], v[192:195], v[166:169], v[34:37]
	v_mfma_f32_16x16x32_bf16 v[38:41], v[200:203], v[166:169], v[38:41]
	v_mfma_f32_16x16x32_bf16 v[42:45], v[192:195], v[174:177], v[42:45]
	v_mfma_f32_16x16x32_bf16 v[46:49], v[200:203], v[174:177], v[46:49]
	v_mfma_f32_16x16x32_bf16 v[50:53], v[192:195], v[184:187], v[50:53]
	v_mfma_f32_16x16x32_bf16 v[54:57], v[200:203], v[184:187], v[54:57]
	v_mfma_f32_16x16x32_bf16 v[110:113], v[196:199], v[138:141], v[110:113]
	v_mfma_f32_16x16x32_bf16 v[30:33], v[204:207], v[138:141], v[30:33]
	v_mfma_f32_16x16x32_bf16 v[34:37], v[196:199], v[170:173], v[34:37]
	v_mfma_f32_16x16x32_bf16 v[38:41], v[204:207], v[170:173], v[38:41]
	v_mfma_f32_16x16x32_bf16 v[42:45], v[196:199], v[178:181], v[42:45]
	v_mfma_f32_16x16x32_bf16 v[46:49], v[204:207], v[178:181], v[46:49]
	v_mfma_f32_16x16x32_bf16 v[50:53], v[196:199], v[188:191], v[50:53]
	v_mfma_f32_16x16x32_bf16 v[54:57], v[204:207], v[188:191], v[54:57]
	s_nop 0
	s_mov_b32 m0, s39
	v_lshl_add_u64 v[208:209], v[212:213], 0, s[2:3]
	s_barrier
	ds_read_b128 v[134:137], v11 offset:49152
	ds_read_b128 v[138:141], v11 offset:50176
	ds_read_b128 v[166:169], v11 offset:51200
	ds_read_b128 v[170:173], v11 offset:52224
	ds_read_b128 v[174:177], v11 offset:53248
	ds_read_b128 v[178:181], v11 offset:54272
	ds_read_b128 v[184:187], v11 offset:55296
	ds_read_b128 v[188:191], v11 offset:56320
	global_load_lds_dwordx4 v[208:209], off
	v_lshl_add_u64 v[208:209], v[214:215], 0, s[2:3]
	s_mov_b32 m0, s40
	s_nop 0
	global_load_lds_dwordx4 v[208:209], off
	s_barrier
	s_waitcnt lgkmcnt(0)
	s_nop 0
	s_waitcnt lgkmcnt(0)
	v_mfma_f32_16x16x32_bf16 v[142:145], v[118:121], v[134:137], v[142:145]
	v_mfma_f32_16x16x32_bf16 v[146:149], v[126:129], v[134:137], v[146:149]
	v_mfma_f32_16x16x32_bf16 v[150:153], v[118:121], v[166:169], v[150:153]
	v_mfma_f32_16x16x32_bf16 v[154:157], v[126:129], v[166:169], v[154:157]
	v_mfma_f32_16x16x32_bf16 v[158:161], v[118:121], v[174:177], v[158:161]
	v_mfma_f32_16x16x32_bf16 v[162:165], v[126:129], v[174:177], v[162:165]
	v_mfma_f32_16x16x32_bf16 v[14:17], v[118:121], v[184:187], v[14:17]
	v_mfma_f32_16x16x32_bf16 v[18:21], v[126:129], v[184:187], v[18:21]
	v_mfma_f32_16x16x32_bf16 v[142:145], v[122:125], v[138:141], v[142:145]
	v_mfma_f32_16x16x32_bf16 v[146:149], v[130:133], v[138:141], v[146:149]
	v_mfma_f32_16x16x32_bf16 v[150:153], v[122:125], v[170:173], v[150:153]
	v_mfma_f32_16x16x32_bf16 v[154:157], v[130:133], v[170:173], v[154:157]
	v_mfma_f32_16x16x32_bf16 v[158:161], v[122:125], v[178:181], v[158:161]
	v_mfma_f32_16x16x32_bf16 v[162:165], v[130:133], v[178:181], v[162:165]
	v_mfma_f32_16x16x32_bf16 v[14:17], v[122:125], v[188:191], v[14:17]
	v_mfma_f32_16x16x32_bf16 v[18:21], v[130:133], v[188:191], v[18:21]
	s_nop 0
	s_barrier
	s_add_u32 s22, s26, 0x10080
	s_addc_u32 s23, s27, 0
	s_mov_b32 m0, s25
	v_lshl_add_u64 v[118:119], s[22:23], 0, v[2:3]
	global_load_lds_dwordx4 v[118:119], off
	v_lshl_add_u64 v[118:119], s[22:23], 0, v[4:5]
	s_mov_b32 m0, s24
	s_nop 0
	global_load_lds_dwordx4 v[118:119], off
	s_waitcnt vmcnt(6)
	s_barrier
	s_nop 0
	v_mfma_f32_16x16x32_bf16 v[22:25], v[192:195], v[134:137], v[22:25]
	v_mfma_f32_16x16x32_bf16 v[26:29], v[200:203], v[134:137], v[26:29]
	v_mfma_f32_16x16x32_bf16 v[58:61], v[192:195], v[166:169], v[58:61]
	v_mfma_f32_16x16x32_bf16 v[102:105], v[200:203], v[166:169], v[102:105]
	v_mfma_f32_16x16x32_bf16 v[106:109], v[192:195], v[174:177], v[106:109]
	v_mfma_f32_16x16x32_bf16 v[114:117], v[200:203], v[174:177], v[114:117]
	v_mfma_f32_16x16x32_bf16 v[94:97], v[192:195], v[184:187], v[94:97]
	v_mfma_f32_16x16x32_bf16 v[98:101], v[200:203], v[184:187], v[98:101]
	v_mfma_f32_16x16x32_bf16 v[22:25], v[196:199], v[138:141], v[22:25]
	v_mfma_f32_16x16x32_bf16 v[26:29], v[204:207], v[138:141], v[26:29]
	v_mfma_f32_16x16x32_bf16 v[58:61], v[196:199], v[170:173], v[58:61]
	v_mfma_f32_16x16x32_bf16 v[102:105], v[204:207], v[170:173], v[102:105]
	v_mfma_f32_16x16x32_bf16 v[106:109], v[196:199], v[178:181], v[106:109]
	v_mfma_f32_16x16x32_bf16 v[114:117], v[204:207], v[178:181], v[114:117]
	v_mfma_f32_16x16x32_bf16 v[94:97], v[196:199], v[188:191], v[94:97]
	v_mfma_f32_16x16x32_bf16 v[98:101], v[204:207], v[188:191], v[98:101]
	s_nop 0
	s_lshl_b32 s4, s4, 8
	v_mov_b32_e32 v13, v238
	v_mov_b32_e32 v119, v239
	s_add_i32 s4, s4, s37
	s_barrier
	v_readlane_b32 s48, v251, 51
	v_add_u32_e32 v118, s4, v13
	s_lshl_b32 s4, s47, 8
	s_or_b32 s4, s4, s38
	v_lshl_add_u32 v120, v119, 2, s4
	v_ashrrev_i32_e32 v119, 31, v118
	v_lshlrev_b64 v[118:119], 12, v[118:119]
	v_readlane_b32 s52, v251, 55
	v_readlane_b32 s53, v251, 56
	v_ashrrev_i32_e32 v121, 31, v120
	s_mov_b32 s4, 0x10000
	v_lshl_add_u64 v[118:119], s[52:53], 0, v[118:119]
	v_lshl_add_u64 v[118:119], v[120:121], 2, v[118:119]
	global_store_dwordx4 v[118:119], v[62:65], off
	global_store_dwordx4 v[118:119], v[66:69], off offset:64
	global_store_dwordx4 v[118:119], v[110:113], off offset:512
	global_store_dwordx4 v[118:119], v[30:33], off offset:576
	s_mov_b64 s[22:23], 0x10000
	s_add_i32 s42, s42, s88
	v_add_co_u32_e32 v32, vcc, s4, v118
	s_mov_b32 s4, 0x20000
	s_nop 0
	v_addc_co_u32_e32 v33, vcc, 0, v119, vcc
	v_lshl_add_u64 v[30:31], v[118:119], 0, s[22:23]
	global_store_dwordx4 v[32:33], v[70:73], off
	global_store_dwordx4 v[30:31], v[74:77], off offset:64
	global_store_dwordx4 v[30:31], v[34:37], off offset:512
	global_store_dwordx4 v[30:31], v[38:41], off offset:576
	v_add_co_u32_e32 v32, vcc, s4, v118
	s_mov_b64 s[22:23], 0x20000
	s_nop 0
	v_addc_co_u32_e32 v33, vcc, 0, v119, vcc
	s_mov_b32 s4, 0x30000
	v_lshl_add_u64 v[30:31], v[118:119], 0, s[22:23]
	global_store_dwordx4 v[32:33], v[78:81], off
	global_store_dwordx4 v[30:31], v[82:85], off offset:64
	global_store_dwordx4 v[30:31], v[42:45], off offset:512
	global_store_dwordx4 v[30:31], v[46:49], off offset:576
	v_add_co_u32_e32 v32, vcc, s4, v118
	s_mov_b64 s[22:23], 0x30000
	s_nop 0
	v_addc_co_u32_e32 v33, vcc, 0, v119, vcc
	s_mov_b32 s4, 0x80000
	v_lshl_add_u64 v[30:31], v[118:119], 0, s[22:23]
	global_store_dwordx4 v[32:33], v[86:89], off
	global_store_dwordx4 v[30:31], v[90:93], off offset:64
	global_store_dwordx4 v[30:31], v[50:53], off offset:512
	global_store_dwordx4 v[30:31], v[54:57], off offset:576
	v_add_co_u32_e32 v32, vcc, s4, v118
	s_mov_b64 s[22:23], 0x80000
	s_nop 0
	v_addc_co_u32_e32 v33, vcc, 0, v119, vcc
	s_mov_b32 s4, 0x90000
	v_lshl_add_u64 v[30:31], v[118:119], 0, s[22:23]
	global_store_dwordx4 v[32:33], v[142:145], off
	global_store_dwordx4 v[30:31], v[146:149], off offset:64
	global_store_dwordx4 v[30:31], v[22:25], off offset:512
	global_store_dwordx4 v[30:31], v[26:29], off offset:576
	s_mov_b64 s[22:23], 0x90000
	v_add_co_u32_e32 v24, vcc, s4, v118
	s_mov_b32 s4, 0xa0000
	s_nop 0
	v_addc_co_u32_e32 v25, vcc, 0, v119, vcc
	v_lshl_add_u64 v[22:23], v[118:119], 0, s[22:23]
	global_store_dwordx4 v[24:25], v[150:153], off
	global_store_dwordx4 v[22:23], v[154:157], off offset:64
	global_store_dwordx4 v[22:23], v[58:61], off offset:512
	global_store_dwordx4 v[22:23], v[102:105], off offset:576
	v_add_co_u32_e32 v24, vcc, s4, v118
	s_mov_b64 s[22:23], 0xa0000
	s_nop 0
	v_addc_co_u32_e32 v25, vcc, 0, v119, vcc
	v_lshl_add_u64 v[22:23], v[118:119], 0, s[22:23]
	global_store_dwordx4 v[24:25], v[158:161], off
	global_store_dwordx4 v[22:23], v[162:165], off offset:64
	global_store_dwordx4 v[22:23], v[106:109], off offset:512
	global_store_dwordx4 v[22:23], v[114:117], off offset:576
	v_add_co_u32_e32 v24, vcc, 0xb0000, v118
	s_mov_b64 s[22:23], 0xb0000
	s_nop 0
	v_addc_co_u32_e32 v25, vcc, 0, v119, vcc
	v_lshl_add_u64 v[22:23], v[118:119], 0, s[22:23]
	s_andn2_b64 vcc, exec, s[0:1]
	s_mov_b32 s47, s14
	s_mov_b32 s4, s16
	s_mov_b64 s[24:25], s[20:21]
	s_mov_b64 s[22:23], s[18:19]
	v_readlane_b32 s49, v251, 52
	v_readlane_b32 s50, v251, 53
	v_readlane_b32 s51, v251, 54
	v_readlane_b32 s54, v251, 57
	v_readlane_b32 s55, v251, 58
	v_readlane_b32 s56, v251, 59
	v_readlane_b32 s57, v251, 60
	v_readlane_b32 s58, v251, 61
	v_readlane_b32 s59, v251, 62
	v_readlane_b32 s60, v251, 63
	v_readlane_b32 s61, v252, 0
	v_readlane_b32 s62, v252, 1
	v_readlane_b32 s63, v252, 2
	global_store_dwordx4 v[24:25], v[14:17], off
	global_store_dwordx4 v[22:23], v[18:21], off offset:64
	global_store_dwordx4 v[22:23], v[94:97], off offset:512
	global_store_dwordx4 v[22:23], v[98:101], off offset:576
	s_cbranch_vccz .LBB0_3190

.LBB0_3266:
	ds_read_b128 v[138:141], v180
	ds_read_b128 v[142:145], v180 offset:1024
	ds_read_b128 v[146:149], v180 offset:2048
	ds_read_b128 v[150:153], v180 offset:3072
	s_add_u32 s20, s18, 0xfffc0080
	s_addc_u32 s21, s19, -1
	s_cmp_eq_u32 s43, 12
	s_cselect_b32 s23, s9, s21
	s_cselect_b32 s22, s15, s20
	s_cselect_b32 s21, s7, s42
	s_cselect_b32 s20, s40, s41
	v_lshl_add_u64 v[178:179], s[18:19], 0, v[130:131]
	s_add_i32 m0, s17, 0xc000
	ds_read_b128 v[154:157], v181
	ds_read_b128 v[158:161], v181 offset:1024
	ds_read_b128 v[162:165], v181 offset:2048
	ds_read_b128 v[166:169], v181 offset:3072
	ds_read_b128 v[170:173], v181 offset:4096
	ds_read_b128 v[174:177], v181 offset:5120
	ds_read_b128 v[184:187], v181 offset:6144
	ds_read_b128 v[188:191], v181 offset:7168
	global_load_lds_dwordx4 v[178:179], off
	v_lshl_add_u64 v[178:179], s[18:19], 0, v[132:133]
	s_add_i32 m0, s17, 0xe000
	s_nop 0
	global_load_lds_dwordx4 v[178:179], off
	s_waitcnt lgkmcnt(8)
	s_barrier
	s_waitcnt lgkmcnt(0)
	s_nop 0
	s_waitcnt lgkmcnt(0)
	v_mfma_f32_16x16x32_bf16 v[126:129], v[138:141], v[154:157], v[126:129]
	v_mfma_f32_16x16x32_bf16 v[122:125], v[146:149], v[154:157], v[122:125]
	v_mfma_f32_16x16x32_bf16 v[114:117], v[138:141], v[162:165], v[114:117]
	v_mfma_f32_16x16x32_bf16 v[106:109], v[146:149], v[162:165], v[106:109]
	v_mfma_f32_16x16x32_bf16 v[94:97], v[138:141], v[170:173], v[94:97]
	v_mfma_f32_16x16x32_bf16 v[90:93], v[146:149], v[170:173], v[90:93]
	v_mfma_f32_16x16x32_bf16 v[82:85], v[138:141], v[184:187], v[82:85]
	v_mfma_f32_16x16x32_bf16 v[74:77], v[146:149], v[184:187], v[74:77]
	v_mfma_f32_16x16x32_bf16 v[126:129], v[142:145], v[158:161], v[126:129]
	v_mfma_f32_16x16x32_bf16 v[122:125], v[150:153], v[158:161], v[122:125]
	v_mfma_f32_16x16x32_bf16 v[114:117], v[142:145], v[166:169], v[114:117]
	v_mfma_f32_16x16x32_bf16 v[106:109], v[150:153], v[166:169], v[106:109]
	v_mfma_f32_16x16x32_bf16 v[94:97], v[142:145], v[174:177], v[94:97]
	v_mfma_f32_16x16x32_bf16 v[90:93], v[150:153], v[174:177], v[90:93]
	v_mfma_f32_16x16x32_bf16 v[82:85], v[142:145], v[188:191], v[82:85]
	v_mfma_f32_16x16x32_bf16 v[74:77], v[150:153], v[188:191], v[74:77]
	s_nop 0
	s_barrier
	s_add_i32 s44, s38, s24
	v_lshl_add_u64 v[178:179], s[20:21], 0, v[226:227]
	s_mov_b32 m0, s44
	ds_read_b128 v[192:195], v183
	ds_read_b128 v[196:199], v183 offset:1024
	ds_read_b128 v[200:203], v183 offset:2048
	ds_read_b128 v[204:207], v183 offset:3072
	global_load_lds_dwordx4 v[178:179], off
	v_lshl_add_u64 v[208:209], s[20:21], 0, v[228:229]
	s_add_i32 m0, s44, 0x2000
	s_nop 0
	global_load_lds_dwordx4 v[208:209], off
	s_barrier
	s_waitcnt lgkmcnt(0)
	s_nop 0
	s_waitcnt lgkmcnt(0)
	v_mfma_f32_16x16x32_bf16 v[118:121], v[192:195], v[154:157], v[118:121]
	v_mfma_f32_16x16x32_bf16 v[110:113], v[200:203], v[154:157], v[110:113]
	v_mfma_f32_16x16x32_bf16 v[102:105], v[192:195], v[162:165], v[102:105]
	v_mfma_f32_16x16x32_bf16 v[98:101], v[200:203], v[162:165], v[98:101]
	v_mfma_f32_16x16x32_bf16 v[86:89], v[192:195], v[170:173], v[86:89]
	v_mfma_f32_16x16x32_bf16 v[78:81], v[200:203], v[170:173], v[78:81]
	v_mfma_f32_16x16x32_bf16 v[70:73], v[192:195], v[184:187], v[70:73]
	v_mfma_f32_16x16x32_bf16 v[66:69], v[200:203], v[184:187], v[66:69]
	v_mfma_f32_16x16x32_bf16 v[118:121], v[196:199], v[158:161], v[118:121]
	v_mfma_f32_16x16x32_bf16 v[110:113], v[204:207], v[158:161], v[110:113]
	v_mfma_f32_16x16x32_bf16 v[102:105], v[196:199], v[166:169], v[102:105]
	v_mfma_f32_16x16x32_bf16 v[98:101], v[204:207], v[166:169], v[98:101]
	v_mfma_f32_16x16x32_bf16 v[86:89], v[196:199], v[174:177], v[86:89]
	v_mfma_f32_16x16x32_bf16 v[78:81], v[204:207], v[174:177], v[78:81]
	v_mfma_f32_16x16x32_bf16 v[70:73], v[196:199], v[188:191], v[70:73]
	v_mfma_f32_16x16x32_bf16 v[66:69], v[204:207], v[188:191], v[66:69]
	s_nop 0
	s_mov_b32 m0, s17
	v_lshl_add_u64 v[210:211], s[22:23], 0, v[226:227]
	s_barrier
	ds_read_b128 v[154:157], v181 offset:16384
	ds_read_b128 v[158:161], v181 offset:17408
	ds_read_b128 v[162:165], v181 offset:18432
	ds_read_b128 v[166:169], v181 offset:19456
	ds_read_b128 v[170:173], v181 offset:20480
	ds_read_b128 v[174:177], v181 offset:21504
	ds_read_b128 v[184:187], v181 offset:22528
	ds_read_b128 v[188:191], v181 offset:23552
	global_load_lds_dwordx4 v[210:211], off
	v_lshl_add_u64 v[212:213], s[22:23], 0, v[228:229]
	s_mov_b32 m0, s25
	s_nop 0
	global_load_lds_dwordx4 v[212:213], off
	s_barrier
	s_waitcnt lgkmcnt(0)
	s_nop 0
	s_waitcnt lgkmcnt(0)
	v_mfma_f32_16x16x32_bf16 v[62:65], v[138:141], v[154:157], v[62:65]
	v_mfma_f32_16x16x32_bf16 v[58:61], v[146:149], v[154:157], v[58:61]
	v_mfma_f32_16x16x32_bf16 v[50:53], v[138:141], v[162:165], v[50:53]
	v_mfma_f32_16x16x32_bf16 v[42:45], v[146:149], v[162:165], v[42:45]
	v_mfma_f32_16x16x32_bf16 v[30:33], v[138:141], v[170:173], v[30:33]
	v_mfma_f32_16x16x32_bf16 v[26:29], v[146:149], v[170:173], v[26:29]
	v_mfma_f32_16x16x32_bf16 v[18:21], v[138:141], v[184:187], v[18:21]
	v_mfma_f32_16x16x32_bf16 v[10:13], v[146:149], v[184:187], v[10:13]
	v_mfma_f32_16x16x32_bf16 v[62:65], v[142:145], v[158:161], v[62:65]
	v_mfma_f32_16x16x32_bf16 v[58:61], v[150:153], v[158:161], v[58:61]
	v_mfma_f32_16x16x32_bf16 v[50:53], v[142:145], v[166:169], v[50:53]
	v_mfma_f32_16x16x32_bf16 v[42:45], v[150:153], v[166:169], v[42:45]
	v_mfma_f32_16x16x32_bf16 v[30:33], v[142:145], v[174:177], v[30:33]
	v_mfma_f32_16x16x32_bf16 v[26:29], v[150:153], v[174:177], v[26:29]
	v_mfma_f32_16x16x32_bf16 v[18:21], v[142:145], v[188:191], v[18:21]
	v_mfma_f32_16x16x32_bf16 v[10:13], v[150:153], v[188:191], v[10:13]
	s_nop 0
	s_barrier
	s_add_u32 s44, s20, 0x40000
	s_addc_u32 s45, s21, 0
	s_add_i32 s46, s39, s24
	v_lshl_add_u64 v[138:139], s[44:45], 0, v[226:227]
	s_mov_b32 m0, s46
	s_nop 0
	global_load_lds_dwordx4 v[138:139], off
	v_lshl_add_u64 v[138:139], s[44:45], 0, v[228:229]
	s_add_i32 m0, s46, 0x2000
	s_nop 0
	global_load_lds_dwordx4 v[138:139], off
	s_waitcnt vmcnt(6)
	s_barrier
	s_nop 0
	v_mfma_f32_16x16x32_bf16 v[54:57], v[192:195], v[154:157], v[54:57]
	v_mfma_f32_16x16x32_bf16 v[46:49], v[200:203], v[154:157], v[46:49]
	v_mfma_f32_16x16x32_bf16 v[38:41], v[192:195], v[162:165], v[38:41]
	v_mfma_f32_16x16x32_bf16 v[34:37], v[200:203], v[162:165], v[34:37]
	v_mfma_f32_16x16x32_bf16 v[22:25], v[192:195], v[170:173], v[22:25]
	v_mfma_f32_16x16x32_bf16 v[14:17], v[200:203], v[170:173], v[14:17]
	v_mfma_f32_16x16x32_bf16 v[6:9], v[192:195], v[184:187], v[6:9]
	v_mfma_f32_16x16x32_bf16 v[2:5], v[200:203], v[184:187], v[2:5]
	v_mfma_f32_16x16x32_bf16 v[54:57], v[196:199], v[158:161], v[54:57]
	v_mfma_f32_16x16x32_bf16 v[46:49], v[204:207], v[158:161], v[46:49]
	v_mfma_f32_16x16x32_bf16 v[38:41], v[196:199], v[166:169], v[38:41]
	v_mfma_f32_16x16x32_bf16 v[34:37], v[204:207], v[166:169], v[34:37]
	v_mfma_f32_16x16x32_bf16 v[22:25], v[196:199], v[174:177], v[22:25]
	v_mfma_f32_16x16x32_bf16 v[14:17], v[204:207], v[174:177], v[14:17]
	v_mfma_f32_16x16x32_bf16 v[6:9], v[196:199], v[188:191], v[6:9]
	v_mfma_f32_16x16x32_bf16 v[2:5], v[204:207], v[188:191], v[2:5]
	s_nop 0
	s_add_i32 s44, 0, 0x18000
	v_add_u32_e32 v150, s44, v1
	s_barrier
	ds_read_b128 v[138:141], v150
	ds_read_b128 v[142:145], v150 offset:1024
	ds_read_b128 v[146:149], v150 offset:2048
	ds_read_b128 v[150:153], v150 offset:3072
	s_add_u32 s22, s22, 0x40000
	s_addc_u32 s23, s23, 0
	s_mov_b32 m0, s26
	v_lshl_add_u64 v[192:193], s[22:23], 0, v[226:227]
	ds_read_b128 v[154:157], v181 offset:32768
	ds_read_b128 v[158:161], v181 offset:33792
	ds_read_b128 v[162:165], v181 offset:34816
	ds_read_b128 v[166:169], v181 offset:35840
	ds_read_b128 v[170:173], v181 offset:36864
	ds_read_b128 v[174:177], v181 offset:37888
	ds_read_b128 v[184:187], v181 offset:38912
	ds_read_b128 v[188:191], v181 offset:39936
	global_load_lds_dwordx4 v[192:193], off
	v_lshl_add_u64 v[192:193], s[22:23], 0, v[228:229]
	s_mov_b32 m0, s27
	s_nop 0
	global_load_lds_dwordx4 v[192:193], off
	s_waitcnt lgkmcnt(8)
	s_barrier
	s_waitcnt lgkmcnt(0)
	s_nop 0
	s_waitcnt lgkmcnt(0)
	v_mfma_f32_16x16x32_bf16 v[126:129], v[138:141], v[154:157], v[126:129]
	v_mfma_f32_16x16x32_bf16 v[122:125], v[146:149], v[154:157], v[122:125]
	v_mfma_f32_16x16x32_bf16 v[114:117], v[138:141], v[162:165], v[114:117]
	v_mfma_f32_16x16x32_bf16 v[106:109], v[146:149], v[162:165], v[106:109]
	v_mfma_f32_16x16x32_bf16 v[94:97], v[138:141], v[170:173], v[94:97]
	v_mfma_f32_16x16x32_bf16 v[90:93], v[146:149], v[170:173], v[90:93]
	v_mfma_f32_16x16x32_bf16 v[82:85], v[138:141], v[184:187], v[82:85]
	v_mfma_f32_16x16x32_bf16 v[74:77], v[146:149], v[184:187], v[74:77]
	v_mfma_f32_16x16x32_bf16 v[126:129], v[142:145], v[158:161], v[126:129]
	v_mfma_f32_16x16x32_bf16 v[122:125], v[150:153], v[158:161], v[122:125]
	v_mfma_f32_16x16x32_bf16 v[114:117], v[142:145], v[166:169], v[114:117]
	v_mfma_f32_16x16x32_bf16 v[106:109], v[150:153], v[166:169], v[106:109]
	v_mfma_f32_16x16x32_bf16 v[94:97], v[142:145], v[174:177], v[94:97]
	v_mfma_f32_16x16x32_bf16 v[90:93], v[150:153], v[174:177], v[90:93]
	v_mfma_f32_16x16x32_bf16 v[82:85], v[142:145], v[188:191], v[82:85]
	v_mfma_f32_16x16x32_bf16 v[74:77], v[150:153], v[188:191], v[74:77]
	s_nop 0
	s_barrier
	s_add_i32 s22, 0, 0x1c000
	s_add_i32 s23, s44, s24
	v_add_u32_e32 v204, s22, v1
	v_lshl_add_u64 v[178:179], v[178:179], 0, s[0:1]
	s_mov_b32 m0, s23
	ds_read_b128 v[192:195], v204
	ds_read_b128 v[196:199], v204 offset:1024
	ds_read_b128 v[200:203], v204 offset:2048
	ds_read_b128 v[204:207], v204 offset:3072
	global_load_lds_dwordx4 v[178:179], off
	v_lshl_add_u64 v[178:179], v[208:209], 0, s[0:1]
	s_add_i32 m0, s23, 0x2000
	s_nop 0
	global_load_lds_dwordx4 v[178:179], off
	s_barrier
	s_waitcnt lgkmcnt(0)
	s_nop 0
	s_waitcnt lgkmcnt(0)
	v_mfma_f32_16x16x32_bf16 v[118:121], v[192:195], v[154:157], v[118:121]
	v_mfma_f32_16x16x32_bf16 v[110:113], v[200:203], v[154:157], v[110:113]
	v_mfma_f32_16x16x32_bf16 v[102:105], v[192:195], v[162:165], v[102:105]
	v_mfma_f32_16x16x32_bf16 v[98:101], v[200:203], v[162:165], v[98:101]
	v_mfma_f32_16x16x32_bf16 v[86:89], v[192:195], v[170:173], v[86:89]
	v_mfma_f32_16x16x32_bf16 v[78:81], v[200:203], v[170:173], v[78:81]
	v_mfma_f32_16x16x32_bf16 v[70:73], v[192:195], v[184:187], v[70:73]
	v_mfma_f32_16x16x32_bf16 v[66:69], v[200:203], v[184:187], v[66:69]
	v_mfma_f32_16x16x32_bf16 v[118:121], v[196:199], v[158:161], v[118:121]
	v_mfma_f32_16x16x32_bf16 v[110:113], v[204:207], v[158:161], v[110:113]
	v_mfma_f32_16x16x32_bf16 v[102:105], v[196:199], v[166:169], v[102:105]
	v_mfma_f32_16x16x32_bf16 v[98:101], v[204:207], v[166:169], v[98:101]
	v_mfma_f32_16x16x32_bf16 v[86:89], v[196:199], v[174:177], v[86:89]
	v_mfma_f32_16x16x32_bf16 v[78:81], v[204:207], v[174:177], v[78:81]
	v_mfma_f32_16x16x32_bf16 v[70:73], v[196:199], v[188:191], v[70:73]
	v_mfma_f32_16x16x32_bf16 v[66:69], v[204:207], v[188:191], v[66:69]
	s_nop 0
	s_mov_b32 m0, s34
	v_lshl_add_u64 v[178:179], v[210:211], 0, s[0:1]
	s_barrier
	ds_read_b128 v[154:157], v181 offset:49152
	ds_read_b128 v[158:161], v181 offset:50176
	ds_read_b128 v[162:165], v181 offset:51200
	ds_read_b128 v[166:169], v181 offset:52224
	ds_read_b128 v[170:173], v181 offset:53248
	ds_read_b128 v[174:177], v181 offset:54272
	ds_read_b128 v[184:187], v181 offset:55296
	ds_read_b128 v[188:191], v181 offset:56320
	global_load_lds_dwordx4 v[178:179], off
	v_lshl_add_u64 v[178:179], v[212:213], 0, s[0:1]
	s_mov_b32 m0, s35
	s_nop 0
	global_load_lds_dwordx4 v[178:179], off
	s_barrier
	s_waitcnt lgkmcnt(0)
	s_nop 0
	s_waitcnt lgkmcnt(0)
	v_mfma_f32_16x16x32_bf16 v[62:65], v[138:141], v[154:157], v[62:65]
	v_mfma_f32_16x16x32_bf16 v[58:61], v[146:149], v[154:157], v[58:61]
	v_mfma_f32_16x16x32_bf16 v[50:53], v[138:141], v[162:165], v[50:53]
	v_mfma_f32_16x16x32_bf16 v[42:45], v[146:149], v[162:165], v[42:45]
	v_mfma_f32_16x16x32_bf16 v[30:33], v[138:141], v[170:173], v[30:33]
	v_mfma_f32_16x16x32_bf16 v[26:29], v[146:149], v[170:173], v[26:29]
	v_mfma_f32_16x16x32_bf16 v[18:21], v[138:141], v[184:187], v[18:21]
	v_mfma_f32_16x16x32_bf16 v[10:13], v[146:149], v[184:187], v[10:13]
	v_mfma_f32_16x16x32_bf16 v[62:65], v[142:145], v[158:161], v[62:65]
	v_mfma_f32_16x16x32_bf16 v[58:61], v[150:153], v[158:161], v[58:61]
	v_mfma_f32_16x16x32_bf16 v[50:53], v[142:145], v[166:169], v[50:53]
	v_mfma_f32_16x16x32_bf16 v[42:45], v[150:153], v[166:169], v[42:45]
	v_mfma_f32_16x16x32_bf16 v[30:33], v[142:145], v[174:177], v[30:33]
	v_mfma_f32_16x16x32_bf16 v[26:29], v[150:153], v[174:177], v[26:29]
	v_mfma_f32_16x16x32_bf16 v[18:21], v[142:145], v[188:191], v[18:21]
	v_mfma_f32_16x16x32_bf16 v[10:13], v[150:153], v[188:191], v[10:13]
	s_nop 0
	s_barrier
	s_add_u32 s20, s20, 0x40080
	s_addc_u32 s21, s21, 0
	s_add_i32 s22, s22, s24
	v_lshl_add_u64 v[138:139], s[20:21], 0, v[226:227]
	s_mov_b32 m0, s22
	s_nop 0
	global_load_lds_dwordx4 v[138:139], off
	v_lshl_add_u64 v[138:139], s[20:21], 0, v[228:229]
	s_add_i32 m0, s22, 0x2000
	s_nop 0
	global_load_lds_dwordx4 v[138:139], off
	s_waitcnt vmcnt(6)
	s_barrier
	s_nop 0
	v_mfma_f32_16x16x32_bf16 v[54:57], v[192:195], v[154:157], v[54:57]
	v_mfma_f32_16x16x32_bf16 v[46:49], v[200:203], v[154:157], v[46:49]
	v_mfma_f32_16x16x32_bf16 v[38:41], v[192:195], v[162:165], v[38:41]
	v_mfma_f32_16x16x32_bf16 v[34:37], v[200:203], v[162:165], v[34:37]
	v_mfma_f32_16x16x32_bf16 v[22:25], v[192:195], v[170:173], v[22:25]
	v_mfma_f32_16x16x32_bf16 v[14:17], v[200:203], v[170:173], v[14:17]
	v_mfma_f32_16x16x32_bf16 v[6:9], v[192:195], v[184:187], v[6:9]
	v_mfma_f32_16x16x32_bf16 v[2:5], v[200:203], v[184:187], v[2:5]
	v_mfma_f32_16x16x32_bf16 v[54:57], v[196:199], v[158:161], v[54:57]
	v_mfma_f32_16x16x32_bf16 v[46:49], v[204:207], v[158:161], v[46:49]
	v_mfma_f32_16x16x32_bf16 v[38:41], v[196:199], v[166:169], v[38:41]
	v_mfma_f32_16x16x32_bf16 v[34:37], v[204:207], v[166:169], v[34:37]
	v_mfma_f32_16x16x32_bf16 v[22:25], v[196:199], v[174:177], v[22:25]
	v_mfma_f32_16x16x32_bf16 v[14:17], v[204:207], v[174:177], v[14:17]
	v_mfma_f32_16x16x32_bf16 v[6:9], v[196:199], v[188:191], v[6:9]
	v_mfma_f32_16x16x32_bf16 v[2:5], v[204:207], v[188:191], v[2:5]
	s_nop 0
	s_add_i32 s43, s43, 2
	s_add_u32 s18, s18, 0x100
	s_addc_u32 s19, s19, 0
	s_add_u32 s41, s41, 0x100
	s_addc_u32 s42, s42, 0
	s_cmp_gt_u32 s43, 13
	s_barrier
	s_cbranch_scc0 .LBB0_3266
	v_mov_b32_e32 v138, v238
	v_mov_b32_e32 v139, v239
	s_lshl_b32 s7, s16, 8
	s_add_i32 s7, s7, s31
	v_add_u32_e32 v138, s7, v138
	s_lshl_b32 s7, s14, 8
	s_or_b32 s7, s7, s33
	v_lshl_add_u32 v142, v139, 2, s7
	v_readlane_b32 s40, v253, 32
	v_ashrrev_i32_e32 v143, 31, v142
	v_readlane_b32 s41, v253, 33
	v_ashrrev_i32_e32 v139, 31, v138
	v_lshlrev_b64 v[144:145], 12, v[138:139]
	v_lshl_add_u64 v[140:141], v[142:143], 2, s[40:41]
	v_cmp_gt_i32_e32 vcc, s29, v138
	v_lshl_add_u64 v[158:159], v[140:141], 0, v[144:145]
	v_mov_b32_e32 v144, 0
	v_mov_b32_e32 v146, 0
	v_mov_b32_e32 v147, 0
	v_mov_b32_e32 v148, 0
	v_mov_b32_e32 v149, 0
	v_readlane_b32 s42, v253, 34
	v_readlane_b32 s43, v253, 35
	v_readlane_b32 s44, v253, 36
	v_readlane_b32 s45, v253, 37
	v_readlane_b32 s46, v253, 38
	v_readlane_b32 s47, v253, 39
	v_readlane_b32 s48, v253, 40
	v_readlane_b32 s49, v253, 41
	v_readlane_b32 s50, v253, 42
	v_readlane_b32 s51, v253, 43
	v_readlane_b32 s52, v253, 44
	v_readlane_b32 s53, v253, 45
	v_readlane_b32 s54, v253, 46
	v_readlane_b32 s55, v253, 47
	s_and_saveexec_b64 s[14:15], vcc
	s_cbranch_execz .LBB0_3269
	global_load_dwordx4 v[146:149], v[158:159], off
	s_waitcnt vmcnt(0)
	v_pk_mul_f32 v[148:149], v[148:149], s[2:3] op_sel_hi:[1,0]
	v_pk_mul_f32 v[146:147], v[146:147], s[2:3] op_sel_hi:[1,0]

.LBB0_3462:
	ds_read_b128 v[130:133], v154
	ds_read_b128 v[134:137], v154 offset:1024
	ds_read_b128 v[146:149], v154 offset:2048
	ds_read_b128 v[150:153], v154 offset:3072
	s_add_u32 s28, s26, 0xfffc0080
	s_addc_u32 s29, s27, -1
	s_cmp_eq_u32 s59, 12
	s_cselect_b32 s31, s19, s29
	s_cselect_b32 s30, s55, s28
	s_cselect_b32 s29, s17, s58
	s_cselect_b32 s28, s56, s57
	v_lshl_add_u64 v[192:193], s[26:27], 0, v[138:139]
	s_add_i32 m0, s36, 0xc000
	ds_read_b128 v[158:161], v155
	ds_read_b128 v[162:165], v155 offset:1024
	ds_read_b128 v[166:169], v155 offset:2048
	ds_read_b128 v[170:173], v155 offset:3072
	ds_read_b128 v[174:177], v155 offset:4096
	ds_read_b128 v[178:181], v155 offset:5120
	ds_read_b128 v[184:187], v155 offset:6144
	ds_read_b128 v[188:191], v155 offset:7168
	global_load_lds_dwordx4 v[192:193], off
	v_lshl_add_u64 v[192:193], s[26:27], 0, v[140:141]
	s_add_i32 m0, s36, 0xe000
	s_nop 0
	global_load_lds_dwordx4 v[192:193], off
	s_waitcnt lgkmcnt(8)
	s_barrier
	s_waitcnt lgkmcnt(0)
	s_nop 0
	s_waitcnt lgkmcnt(0)
	v_mfma_f32_16x16x32_bf16 v[126:129], v[130:133], v[158:161], v[126:129]
	v_mfma_f32_16x16x32_bf16 v[122:125], v[146:149], v[158:161], v[122:125]
	v_mfma_f32_16x16x32_bf16 v[118:121], v[130:133], v[166:169], v[118:121]
	v_mfma_f32_16x16x32_bf16 v[106:109], v[146:149], v[166:169], v[106:109]
	v_mfma_f32_16x16x32_bf16 v[102:105], v[130:133], v[174:177], v[102:105]
	v_mfma_f32_16x16x32_bf16 v[90:93], v[146:149], v[174:177], v[90:93]
	v_mfma_f32_16x16x32_bf16 v[86:89], v[130:133], v[184:187], v[86:89]
	v_mfma_f32_16x16x32_bf16 v[74:77], v[146:149], v[184:187], v[74:77]
	v_mfma_f32_16x16x32_bf16 v[126:129], v[134:137], v[162:165], v[126:129]
	v_mfma_f32_16x16x32_bf16 v[122:125], v[150:153], v[162:165], v[122:125]
	v_mfma_f32_16x16x32_bf16 v[118:121], v[134:137], v[170:173], v[118:121]
	v_mfma_f32_16x16x32_bf16 v[106:109], v[150:153], v[170:173], v[106:109]
	v_mfma_f32_16x16x32_bf16 v[102:105], v[134:137], v[178:181], v[102:105]
	v_mfma_f32_16x16x32_bf16 v[90:93], v[150:153], v[178:181], v[90:93]
	v_mfma_f32_16x16x32_bf16 v[86:89], v[134:137], v[188:191], v[86:89]
	v_mfma_f32_16x16x32_bf16 v[74:77], v[150:153], v[188:191], v[74:77]
	s_nop 0
	s_barrier
	s_add_i32 s60, s46, s33
	v_lshl_add_u64 v[208:209], s[28:29], 0, v[226:227]
	s_mov_b32 m0, s60
	ds_read_b128 v[192:195], v156
	ds_read_b128 v[196:199], v156 offset:1024
	ds_read_b128 v[200:203], v156 offset:2048
	ds_read_b128 v[204:207], v156 offset:3072
	global_load_lds_dwordx4 v[208:209], off
	v_lshl_add_u64 v[210:211], s[28:29], 0, v[228:229]
	s_add_i32 m0, s60, 0x2000
	s_nop 0
	global_load_lds_dwordx4 v[210:211], off
	s_barrier
	s_waitcnt lgkmcnt(0)
	s_nop 0
	s_waitcnt lgkmcnt(0)
	v_mfma_f32_16x16x32_bf16 v[114:117], v[192:195], v[158:161], v[114:117]
	v_mfma_f32_16x16x32_bf16 v[110:113], v[200:203], v[158:161], v[110:113]
	v_mfma_f32_16x16x32_bf16 v[98:101], v[192:195], v[166:169], v[98:101]
	v_mfma_f32_16x16x32_bf16 v[94:97], v[200:203], v[166:169], v[94:97]
	v_mfma_f32_16x16x32_bf16 v[82:85], v[192:195], v[174:177], v[82:85]
	v_mfma_f32_16x16x32_bf16 v[78:81], v[200:203], v[174:177], v[78:81]
	v_mfma_f32_16x16x32_bf16 v[70:73], v[192:195], v[184:187], v[70:73]
	v_mfma_f32_16x16x32_bf16 v[66:69], v[200:203], v[184:187], v[66:69]
	v_mfma_f32_16x16x32_bf16 v[114:117], v[196:199], v[162:165], v[114:117]
	v_mfma_f32_16x16x32_bf16 v[110:113], v[204:207], v[162:165], v[110:113]
	v_mfma_f32_16x16x32_bf16 v[98:101], v[196:199], v[170:173], v[98:101]
	v_mfma_f32_16x16x32_bf16 v[94:97], v[204:207], v[170:173], v[94:97]
	v_mfma_f32_16x16x32_bf16 v[82:85], v[196:199], v[178:181], v[82:85]
	v_mfma_f32_16x16x32_bf16 v[78:81], v[204:207], v[178:181], v[78:81]
	v_mfma_f32_16x16x32_bf16 v[70:73], v[196:199], v[188:191], v[70:73]
	v_mfma_f32_16x16x32_bf16 v[66:69], v[204:207], v[188:191], v[66:69]
	s_nop 0
	s_mov_b32 m0, s36
	v_lshl_add_u64 v[212:213], s[30:31], 0, v[226:227]
	s_barrier
	ds_read_b128 v[158:161], v155 offset:16384
	ds_read_b128 v[162:165], v155 offset:17408
	ds_read_b128 v[166:169], v155 offset:18432
	ds_read_b128 v[170:173], v155 offset:19456
	ds_read_b128 v[174:177], v155 offset:20480
	ds_read_b128 v[178:181], v155 offset:21504
	ds_read_b128 v[184:187], v155 offset:22528
	ds_read_b128 v[188:191], v155 offset:23552
	global_load_lds_dwordx4 v[212:213], off
	v_lshl_add_u64 v[214:215], s[30:31], 0, v[228:229]
	s_mov_b32 m0, s37
	s_nop 0
	global_load_lds_dwordx4 v[214:215], off
	s_barrier
	s_waitcnt lgkmcnt(0)
	s_nop 0
	s_waitcnt lgkmcnt(0)
	v_mfma_f32_16x16x32_bf16 v[62:65], v[130:133], v[158:161], v[62:65]
	v_mfma_f32_16x16x32_bf16 v[58:61], v[146:149], v[158:161], v[58:61]
	v_mfma_f32_16x16x32_bf16 v[54:57], v[130:133], v[166:169], v[54:57]
	v_mfma_f32_16x16x32_bf16 v[46:49], v[146:149], v[166:169], v[46:49]
	v_mfma_f32_16x16x32_bf16 v[38:41], v[130:133], v[174:177], v[38:41]
	v_mfma_f32_16x16x32_bf16 v[30:33], v[146:149], v[174:177], v[30:33]
	v_mfma_f32_16x16x32_bf16 v[22:25], v[130:133], v[184:187], v[22:25]
	v_mfma_f32_16x16x32_bf16 v[14:17], v[146:149], v[184:187], v[14:17]
	v_mfma_f32_16x16x32_bf16 v[62:65], v[134:137], v[162:165], v[62:65]
	v_mfma_f32_16x16x32_bf16 v[58:61], v[150:153], v[162:165], v[58:61]
	v_mfma_f32_16x16x32_bf16 v[54:57], v[134:137], v[170:173], v[54:57]
	v_mfma_f32_16x16x32_bf16 v[46:49], v[150:153], v[170:173], v[46:49]
	v_mfma_f32_16x16x32_bf16 v[38:41], v[134:137], v[178:181], v[38:41]
	v_mfma_f32_16x16x32_bf16 v[30:33], v[150:153], v[178:181], v[30:33]
	v_mfma_f32_16x16x32_bf16 v[22:25], v[134:137], v[188:191], v[22:25]
	v_mfma_f32_16x16x32_bf16 v[14:17], v[150:153], v[188:191], v[14:17]
	s_nop 0
	s_barrier
	s_add_u32 s60, s28, 0x40000
	s_addc_u32 s61, s29, 0
	s_add_i32 s62, s47, s33
	v_lshl_add_u64 v[130:131], s[60:61], 0, v[226:227]
	s_mov_b32 m0, s62
	s_nop 0
	global_load_lds_dwordx4 v[130:131], off
	v_lshl_add_u64 v[130:131], s[60:61], 0, v[228:229]
	s_add_i32 m0, s62, 0x2000
	s_nop 0
	global_load_lds_dwordx4 v[130:131], off
	s_waitcnt vmcnt(6)
	s_barrier
	s_nop 0
	v_mfma_f32_16x16x32_bf16 v[50:53], v[192:195], v[158:161], v[50:53]
	v_mfma_f32_16x16x32_bf16 v[42:45], v[200:203], v[158:161], v[42:45]
	v_mfma_f32_16x16x32_bf16 v[34:37], v[192:195], v[166:169], v[34:37]
	v_mfma_f32_16x16x32_bf16 v[26:29], v[200:203], v[166:169], v[26:29]
	v_mfma_f32_16x16x32_bf16 v[18:21], v[192:195], v[174:177], v[18:21]
	v_mfma_f32_16x16x32_bf16 v[10:13], v[200:203], v[174:177], v[10:13]
	v_mfma_f32_16x16x32_bf16 v[6:9], v[192:195], v[184:187], v[6:9]
	v_mfma_f32_16x16x32_bf16 v[2:5], v[200:203], v[184:187], v[2:5]
	v_mfma_f32_16x16x32_bf16 v[50:53], v[196:199], v[162:165], v[50:53]
	v_mfma_f32_16x16x32_bf16 v[42:45], v[204:207], v[162:165], v[42:45]
	v_mfma_f32_16x16x32_bf16 v[34:37], v[196:199], v[170:173], v[34:37]
	v_mfma_f32_16x16x32_bf16 v[26:29], v[204:207], v[170:173], v[26:29]
	v_mfma_f32_16x16x32_bf16 v[18:21], v[196:199], v[178:181], v[18:21]
	v_mfma_f32_16x16x32_bf16 v[10:13], v[204:207], v[178:181], v[10:13]
	v_mfma_f32_16x16x32_bf16 v[6:9], v[196:199], v[188:191], v[6:9]
	v_mfma_f32_16x16x32_bf16 v[2:5], v[204:207], v[188:191], v[2:5]
	s_nop 0
	s_add_i32 s60, 0, 0x18000
	v_add_u32_e32 v150, s60, v1
	s_barrier
	ds_read_b128 v[130:133], v150
	ds_read_b128 v[134:137], v150 offset:1024
	ds_read_b128 v[146:149], v150 offset:2048
	ds_read_b128 v[150:153], v150 offset:3072
	s_add_u32 s30, s30, 0x40000
	s_addc_u32 s31, s31, 0
	s_mov_b32 m0, s38
	v_lshl_add_u64 v[192:193], s[30:31], 0, v[226:227]
	ds_read_b128 v[158:161], v155 offset:32768
	ds_read_b128 v[162:165], v155 offset:33792
	ds_read_b128 v[166:169], v155 offset:34816
	ds_read_b128 v[170:173], v155 offset:35840
	ds_read_b128 v[174:177], v155 offset:36864
	ds_read_b128 v[178:181], v155 offset:37888
	ds_read_b128 v[184:187], v155 offset:38912
	ds_read_b128 v[188:191], v155 offset:39936
	global_load_lds_dwordx4 v[192:193], off
	v_lshl_add_u64 v[192:193], s[30:31], 0, v[228:229]
	s_mov_b32 m0, s39
	s_nop 0
	global_load_lds_dwordx4 v[192:193], off
	s_waitcnt lgkmcnt(8)
	s_barrier
	s_waitcnt lgkmcnt(0)
	s_nop 0
	s_waitcnt lgkmcnt(0)
	v_mfma_f32_16x16x32_bf16 v[126:129], v[130:133], v[158:161], v[126:129]
	v_mfma_f32_16x16x32_bf16 v[122:125], v[146:149], v[158:161], v[122:125]
	v_mfma_f32_16x16x32_bf16 v[118:121], v[130:133], v[166:169], v[118:121]
	v_mfma_f32_16x16x32_bf16 v[106:109], v[146:149], v[166:169], v[106:109]
	v_mfma_f32_16x16x32_bf16 v[102:105], v[130:133], v[174:177], v[102:105]
	v_mfma_f32_16x16x32_bf16 v[90:93], v[146:149], v[174:177], v[90:93]
	v_mfma_f32_16x16x32_bf16 v[86:89], v[130:133], v[184:187], v[86:89]
	v_mfma_f32_16x16x32_bf16 v[74:77], v[146:149], v[184:187], v[74:77]
	v_mfma_f32_16x16x32_bf16 v[126:129], v[134:137], v[162:165], v[126:129]
	v_mfma_f32_16x16x32_bf16 v[122:125], v[150:153], v[162:165], v[122:125]
	v_mfma_f32_16x16x32_bf16 v[118:121], v[134:137], v[170:173], v[118:121]
	v_mfma_f32_16x16x32_bf16 v[106:109], v[150:153], v[170:173], v[106:109]
	v_mfma_f32_16x16x32_bf16 v[102:105], v[134:137], v[178:181], v[102:105]
	v_mfma_f32_16x16x32_bf16 v[90:93], v[150:153], v[178:181], v[90:93]
	v_mfma_f32_16x16x32_bf16 v[86:89], v[134:137], v[188:191], v[86:89]
	v_mfma_f32_16x16x32_bf16 v[74:77], v[150:153], v[188:191], v[74:77]
	s_nop 0
	s_barrier
	s_add_i32 s30, 0, 0x1c000
	s_add_i32 s31, s60, s33
	v_add_u32_e32 v157, s30, v1
	v_lshl_add_u64 v[208:209], v[208:209], 0, s[0:1]
	s_mov_b32 m0, s31
	ds_read_b128 v[192:195], v157
	ds_read_b128 v[196:199], v157 offset:1024
	ds_read_b128 v[200:203], v157 offset:2048
	ds_read_b128 v[204:207], v157 offset:3072
	global_load_lds_dwordx4 v[208:209], off
	v_lshl_add_u64 v[208:209], v[210:211], 0, s[0:1]
	s_add_i32 m0, s31, 0x2000
	s_nop 0
	global_load_lds_dwordx4 v[208:209], off
	s_barrier
	s_waitcnt lgkmcnt(0)
	s_nop 0
	s_waitcnt lgkmcnt(0)
	v_mfma_f32_16x16x32_bf16 v[114:117], v[192:195], v[158:161], v[114:117]
	v_mfma_f32_16x16x32_bf16 v[110:113], v[200:203], v[158:161], v[110:113]
	v_mfma_f32_16x16x32_bf16 v[98:101], v[192:195], v[166:169], v[98:101]
	v_mfma_f32_16x16x32_bf16 v[94:97], v[200:203], v[166:169], v[94:97]
	v_mfma_f32_16x16x32_bf16 v[82:85], v[192:195], v[174:177], v[82:85]
	v_mfma_f32_16x16x32_bf16 v[78:81], v[200:203], v[174:177], v[78:81]
	v_mfma_f32_16x16x32_bf16 v[70:73], v[192:195], v[184:187], v[70:73]
	v_mfma_f32_16x16x32_bf16 v[66:69], v[200:203], v[184:187], v[66:69]
	v_mfma_f32_16x16x32_bf16 v[114:117], v[196:199], v[162:165], v[114:117]
	v_mfma_f32_16x16x32_bf16 v[110:113], v[204:207], v[162:165], v[110:113]
	v_mfma_f32_16x16x32_bf16 v[98:101], v[196:199], v[170:173], v[98:101]
	v_mfma_f32_16x16x32_bf16 v[94:97], v[204:207], v[170:173], v[94:97]
	v_mfma_f32_16x16x32_bf16 v[82:85], v[196:199], v[178:181], v[82:85]
	v_mfma_f32_16x16x32_bf16 v[78:81], v[204:207], v[178:181], v[78:81]
	v_mfma_f32_16x16x32_bf16 v[70:73], v[196:199], v[188:191], v[70:73]
	v_mfma_f32_16x16x32_bf16 v[66:69], v[204:207], v[188:191], v[66:69]
	s_nop 0
	s_mov_b32 m0, s43
	v_lshl_add_u64 v[208:209], v[212:213], 0, s[0:1]
	s_barrier
	ds_read_b128 v[158:161], v155 offset:49152
	ds_read_b128 v[162:165], v155 offset:50176
	ds_read_b128 v[166:169], v155 offset:51200
	ds_read_b128 v[170:173], v155 offset:52224
	ds_read_b128 v[174:177], v155 offset:53248
	ds_read_b128 v[178:181], v155 offset:54272
	ds_read_b128 v[184:187], v155 offset:55296
	ds_read_b128 v[188:191], v155 offset:56320
	global_load_lds_dwordx4 v[208:209], off
	v_lshl_add_u64 v[208:209], v[214:215], 0, s[0:1]
	s_mov_b32 m0, s44
	s_nop 0
	global_load_lds_dwordx4 v[208:209], off
	s_barrier
	s_waitcnt lgkmcnt(0)
	s_nop 0
	s_waitcnt lgkmcnt(0)
	v_mfma_f32_16x16x32_bf16 v[62:65], v[130:133], v[158:161], v[62:65]
	v_mfma_f32_16x16x32_bf16 v[58:61], v[146:149], v[158:161], v[58:61]
	v_mfma_f32_16x16x32_bf16 v[54:57], v[130:133], v[166:169], v[54:57]
	v_mfma_f32_16x16x32_bf16 v[46:49], v[146:149], v[166:169], v[46:49]
	v_mfma_f32_16x16x32_bf16 v[38:41], v[130:133], v[174:177], v[38:41]
	v_mfma_f32_16x16x32_bf16 v[30:33], v[146:149], v[174:177], v[30:33]
	v_mfma_f32_16x16x32_bf16 v[22:25], v[130:133], v[184:187], v[22:25]
	v_mfma_f32_16x16x32_bf16 v[14:17], v[146:149], v[184:187], v[14:17]
	v_mfma_f32_16x16x32_bf16 v[62:65], v[134:137], v[162:165], v[62:65]
	v_mfma_f32_16x16x32_bf16 v[58:61], v[150:153], v[162:165], v[58:61]
	v_mfma_f32_16x16x32_bf16 v[54:57], v[134:137], v[170:173], v[54:57]
	v_mfma_f32_16x16x32_bf16 v[46:49], v[150:153], v[170:173], v[46:49]
	v_mfma_f32_16x16x32_bf16 v[38:41], v[134:137], v[178:181], v[38:41]
	v_mfma_f32_16x16x32_bf16 v[30:33], v[150:153], v[178:181], v[30:33]
	v_mfma_f32_16x16x32_bf16 v[22:25], v[134:137], v[188:191], v[22:25]
	v_mfma_f32_16x16x32_bf16 v[14:17], v[150:153], v[188:191], v[14:17]
	s_nop 0
	s_barrier
	s_add_u32 s28, s28, 0x40080
	s_addc_u32 s29, s29, 0
	s_add_i32 s30, s30, s33
	v_lshl_add_u64 v[130:131], s[28:29], 0, v[226:227]
	s_mov_b32 m0, s30
	s_nop 0
	global_load_lds_dwordx4 v[130:131], off
	v_lshl_add_u64 v[130:131], s[28:29], 0, v[228:229]
	s_add_i32 m0, s30, 0x2000
	s_nop 0
	global_load_lds_dwordx4 v[130:131], off
	s_waitcnt vmcnt(6)
	s_barrier
	s_nop 0
	v_mfma_f32_16x16x32_bf16 v[50:53], v[192:195], v[158:161], v[50:53]
	v_mfma_f32_16x16x32_bf16 v[42:45], v[200:203], v[158:161], v[42:45]
	v_mfma_f32_16x16x32_bf16 v[34:37], v[192:195], v[166:169], v[34:37]
	v_mfma_f32_16x16x32_bf16 v[26:29], v[200:203], v[166:169], v[26:29]
	v_mfma_f32_16x16x32_bf16 v[18:21], v[192:195], v[174:177], v[18:21]
	v_mfma_f32_16x16x32_bf16 v[10:13], v[200:203], v[174:177], v[10:13]
	v_mfma_f32_16x16x32_bf16 v[6:9], v[192:195], v[184:187], v[6:9]
	v_mfma_f32_16x16x32_bf16 v[2:5], v[200:203], v[184:187], v[2:5]
	v_mfma_f32_16x16x32_bf16 v[50:53], v[196:199], v[162:165], v[50:53]
	v_mfma_f32_16x16x32_bf16 v[42:45], v[204:207], v[162:165], v[42:45]
	v_mfma_f32_16x16x32_bf16 v[34:37], v[196:199], v[170:173], v[34:37]
	v_mfma_f32_16x16x32_bf16 v[26:29], v[204:207], v[170:173], v[26:29]
	v_mfma_f32_16x16x32_bf16 v[18:21], v[196:199], v[178:181], v[18:21]
	v_mfma_f32_16x16x32_bf16 v[10:13], v[204:207], v[178:181], v[10:13]
	v_mfma_f32_16x16x32_bf16 v[6:9], v[196:199], v[188:191], v[6:9]
	v_mfma_f32_16x16x32_bf16 v[2:5], v[204:207], v[188:191], v[2:5]
	s_nop 0
	s_add_i32 s59, s59, 2
	s_add_u32 s26, s26, 0x100
	s_addc_u32 s27, s27, 0
	s_add_u32 s57, s57, 0x100
	s_addc_u32 s58, s58, 0
	s_cmp_gt_u32 s59, 13
	s_barrier
	s_cbranch_scc0 .LBB0_3462
	s_lshl_b32 s17, s24, 8
	v_mov_b32_e32 v130, v238
	v_mov_b32_e32 v131, v239
	s_add_i32 s17, s17, s41
	s_nop 0
	v_add_u32_e32 v148, s17, v130
	s_lshl_b32 s17, s25, 8
	s_or_b32 s17, s17, s42
	v_lshl_add_u32 v146, v131, 2, s17
	s_cmp_lt_i32 s25, 8
	v_ashrrev_i32_e32 v147, 31, v146
	s_mov_b64 s[24:25], -1
	v_ashrrev_i32_e32 v149, 31, v148
	s_cbranch_scc1 .LBB0_3465
	v_readlane_b32 s68, v251, 51
	v_readlane_b32 s72, v251, 55
	v_readlane_b32 s73, v251, 56
	v_lshlrev_b64 v[130:131], 12, v[148:149]
	v_mul_f32_e32 v166, 0xbfb8aa3b, v127
	v_lshl_add_u64 v[152:153], v[146:147], 2, s[72:73]
	v_lshl_add_u64 v[130:131], v[152:153], 0, v[130:131]
	v_add_co_u32_e32 v132, vcc, 0xffffe000, v130
	v_mul_f32_e32 v167, 0xbfb8aa3b, v128
	s_nop 0
	v_addc_co_u32_e32 v133, vcc, -1, v131, vcc
	v_add_co_u32_e32 v130, vcc, 0xfffff000, v130
	global_load_dwordx4 v[134:137], v[132:133], off
	s_nop 0
	v_addc_co_u32_e32 v131, vcc, -1, v131, vcc
	global_load_dwordx4 v[158:161], v[130:131], off offset:-4032
	global_load_dwordx4 v[162:165], v[130:131], off offset:-3584
	v_mul_f32_e32 v168, 0xbfb8aa3b, v129
	v_mul_f32_e32 v169, 0xbfb8aa3b, v122
	v_exp_f32_e32 v183, v166
	v_exp_f32_e32 v188, v167
	v_exp_f32_e32 v189, v168
	v_exp_f32_e32 v190, v169
	global_load_dwordx4 v[166:169], v[130:131], off offset:-3520
	v_add_u32_e32 v184, 16, v148
	v_ashrrev_i32_e32 v185, 31, v184
	v_readlane_b32 s74, v251, 57
	v_readlane_b32 s75, v251, 58
	v_lshlrev_b64 v[132:133], 11, v[148:149]
	v_lshlrev_b64 v[130:131], 12, v[184:185]
	v_lshlrev_b64 v[150:151], 1, v[146:147]
	v_lshl_add_u64 v[132:133], s[74:75], 0, v[132:133]
	v_lshl_add_u64 v[130:131], v[152:153], 0, v[130:131]
	v_lshl_add_u64 v[186:187], v[132:133], 0, v[150:151]
	v_add_co_u32_e32 v132, vcc, s48, v130
	v_mul_f32_e32 v170, 0xbfb8aa3b, v123
	s_nop 0
	v_addc_co_u32_e32 v133, vcc, -1, v131, vcc
	v_add_co_u32_e32 v130, vcc, s49, v130
	v_mul_f32_e32 v171, 0xbfb8aa3b, v124
	v_mul_f32_e32 v172, 0xbfb8aa3b, v125
	v_mul_f32_e32 v173, 0xbfb8aa3b, v114
	v_mul_f32_e32 v174, 0xbfb8aa3b, v115
	v_mul_f32_e32 v175, 0xbfb8aa3b, v116
	v_addc_co_u32_e32 v131, vcc, -1, v131, vcc
	v_exp_f32_e32 v191, v170
	v_exp_f32_e32 v192, v171
	v_exp_f32_e32 v193, v172
	v_exp_f32_e32 v194, v173
	v_exp_f32_e32 v197, v174
	v_exp_f32_e32 v198, v175
	global_load_dwordx4 v[170:173], v[132:133], off
	global_load_dwordx4 v[174:177], v[130:131], off offset:-4032
	global_load_dwordx4 v[178:181], v[130:131], off offset:-3584
	s_nop 0
	global_load_dwordx4 v[130:133], v[130:131], off offset:-3520
	v_mul_f32_e32 v157, 0xbfb8aa3b, v126
	v_exp_f32_e32 v157, v157
	v_add_f32_e32 v183, 1.0, v183
	v_add_f32_e32 v195, 1.0, v188
	v_add_f32_e32 v196, 1.0, v189
	v_add_f32_e32 v157, 1.0, v157
	v_add_f32_e32 v199, 1.0, v190
	v_add_f32_e32 v200, 1.0, v191
	v_add_f32_e32 v201, 1.0, v192
	v_add_f32_e32 v202, 1.0, v193
	v_rcp_f32_e32 v188, v157
	v_rcp_f32_e32 v189, v183
	v_rcp_f32_e32 v190, v195
	v_rcp_f32_e32 v191, v196
	v_add_f32_e32 v203, 1.0, v194
	v_rcp_f32_e32 v194, v201
	v_rcp_f32_e32 v195, v202
	v_rcp_f32_e32 v192, v199
	v_rcp_f32_e32 v193, v200
	v_rcp_f32_e32 v196, v203
	v_mul_f32_e32 v183, 0xbfb8aa3b, v104
	v_exp_f32_e32 v183, v183
	s_mov_b64 s[24:25], 0
	v_readlane_b32 s69, v251, 52
	v_readlane_b32 s70, v251, 53
	v_add_f32_e32 v183, 1.0, v183
	v_readlane_b32 s71, v251, 54
	v_readlane_b32 s76, v251, 59
	v_readlane_b32 s77, v251, 60
	v_readlane_b32 s78, v251, 61
	v_readlane_b32 s79, v251, 62
	v_readlane_b32 s80, v251, 63
	v_readlane_b32 s81, v252, 0
	v_readlane_b32 s82, v252, 1
	v_readlane_b32 s83, v252, 2
	s_waitcnt vmcnt(0)
	v_pk_mul_f32 v[136:137], v[190:191], v[136:137]
	v_pk_mul_f32 v[134:135], v[188:189], v[134:135]
	v_mul_f32_e32 v189, 0xbfb8aa3b, v105
	v_cvt_pk_bf16_f32 v134, v134, v135
	v_cvt_pk_bf16_f32 v135, v136, v137
	v_pk_mul_f32 v[136:137], v[194:195], v[160:161]
	v_pk_mul_f32 v[158:159], v[192:193], v[158:159]
	global_store_dwordx2 v[186:187], v[134:135], off offset:-4096
	v_cvt_pk_bf16_f32 v134, v158, v159
	v_cvt_pk_bf16_f32 v135, v136, v137
	v_add_f32_e32 v136, 1.0, v197
	v_rcp_f32_e32 v197, v136
	v_mul_f32_e32 v136, 0xbfb8aa3b, v110
	v_exp_f32_e32 v157, v136
	global_store_dwordx2 v[186:187], v[134:135], off offset:-4064
	v_pk_mul_f32 v[136:137], v[196:197], v[162:163]
	v_mul_f32_e32 v134, 0xbfb8aa3b, v117
	v_cvt_pk_bf16_f32 v136, v136, v137
	v_add_f32_e32 v137, 1.0, v157
	v_exp_f32_e32 v135, v134
	v_rcp_f32_e32 v158, v137
	v_mul_f32_e32 v137, 0xbfb8aa3b, v111
	v_mul_f32_e32 v157, 0xbfb8aa3b, v112
	v_exp_f32_e32 v137, v137
	v_exp_f32_e32 v157, v157
	v_mul_f32_e32 v159, 0xbfb8aa3b, v113
	v_exp_f32_e32 v159, v159
	v_add_f32_e32 v134, 1.0, v198
	v_add_f32_e32 v135, 1.0, v135
	v_rcp_f32_e32 v134, v134
	v_rcp_f32_e32 v135, v135
	v_add_f32_e32 v137, 1.0, v137
	v_add_f32_e32 v157, 1.0, v157
	v_rcp_f32_e32 v160, v157
	v_add_f32_e32 v157, 1.0, v159
	v_rcp_f32_e32 v159, v137
	v_rcp_f32_e32 v161, v157
	v_pk_mul_f32 v[134:135], v[134:135], v[164:165]
	v_mul_f32_e32 v157, 0xbfb8aa3b, v120
	v_cvt_pk_bf16_f32 v137, v134, v135
	global_store_dwordx2 v[186:187], v[136:137], off offset:-3840
	v_pk_mul_f32 v[136:137], v[158:159], v[166:167]
	v_pk_mul_f32 v[134:135], v[160:161], v[168:169]
	v_cvt_pk_bf16_f32 v136, v136, v137
	v_exp_f32_e32 v157, v157
	v_cvt_pk_bf16_f32 v137, v134, v135
	global_store_dwordx2 v[186:187], v[136:137], off offset:-3808
	v_mul_f32_e32 v134, 0xbfb8aa3b, v118
	v_mul_f32_e32 v137, 0xbfb8aa3b, v119
	v_mul_f32_e32 v158, 0xbfb8aa3b, v121
	v_exp_f32_e32 v136, v134
	v_exp_f32_e32 v137, v137
	v_exp_f32_e32 v159, v158
	v_add_f32_e32 v157, 1.0, v157
	v_add_f32_e32 v136, 1.0, v136
	v_add_f32_e32 v137, 1.0, v137
	v_rcp_f32_e32 v158, v157
	v_add_f32_e32 v157, 1.0, v159
	v_rcp_f32_e32 v136, v136
	v_rcp_f32_e32 v159, v157
	v_rcp_f32_e32 v137, v137
	v_mul_f32_e32 v157, 0xbfb8aa3b, v106
	v_exp_f32_e32 v157, v157
	v_mul_f32_e32 v161, 0xbfb8aa3b, v109
	v_pk_mul_f32 v[136:137], v[136:137], v[170:171]
	v_exp_f32_e32 v161, v161
	v_cvt_pk_bf16_f32 v136, v136, v137
	v_add_f32_e32 v137, 1.0, v157
	v_mul_f32_e32 v157, 0xbfb8aa3b, v108
	v_rcp_f32_e32 v160, v137
	v_mul_f32_e32 v137, 0xbfb8aa3b, v107
	v_exp_f32_e32 v157, v157
	v_exp_f32_e32 v137, v137
	v_lshlrev_b64 v[134:135], 11, v[184:185]
	v_lshl_add_u64 v[134:135], s[74:75], 0, v[134:135]
	v_add_f32_e32 v157, 1.0, v157
	v_add_f32_e32 v137, 1.0, v137
	v_rcp_f32_e32 v162, v157
	v_add_f32_e32 v157, 1.0, v161
	v_rcp_f32_e32 v163, v157
	v_rcp_f32_e32 v161, v137
	v_mul_f32_e32 v157, 0xbfb8aa3b, v98
	v_exp_f32_e32 v157, v157
	v_lshl_add_u64 v[134:135], v[134:135], 0, v[150:151]
	v_pk_mul_f32 v[158:159], v[158:159], v[172:173]
	v_add_u32_e32 v184, 32, v148
	v_cvt_pk_bf16_f32 v137, v158, v159
	global_store_dwordx2 v[134:135], v[136:137], off offset:-4096
	v_pk_mul_f32 v[136:137], v[162:163], v[176:177]
	v_pk_mul_f32 v[158:159], v[160:161], v[174:175]
	v_mul_f32_e32 v161, 0xbfb8aa3b, v97
	v_cvt_pk_bf16_f32 v158, v158, v159
	v_cvt_pk_bf16_f32 v159, v136, v137
	v_add_f32_e32 v136, 1.0, v157
	v_mul_f32_e32 v157, 0xbfb8aa3b, v100
	global_store_dwordx2 v[134:135], v[158:159], off offset:-4064
	v_mul_f32_e32 v137, 0xbfb8aa3b, v99
	v_exp_f32_e32 v157, v157
	v_mul_f32_e32 v158, 0xbfb8aa3b, v101
	v_exp_f32_e32 v137, v137
	v_exp_f32_e32 v159, v158
	v_add_f32_e32 v157, 1.0, v157
	v_rcp_f32_e32 v158, v157
	v_add_f32_e32 v137, 1.0, v137
	v_add_f32_e32 v157, 1.0, v159
	v_rcp_f32_e32 v136, v136
	v_rcp_f32_e32 v159, v157
	v_rcp_f32_e32 v137, v137
	v_mul_f32_e32 v157, 0xbfb8aa3b, v94
	v_exp_f32_e32 v157, v157
	v_exp_f32_e32 v161, v161
	v_pk_mul_f32 v[136:137], v[136:137], v[178:179]
	v_pk_mul_f32 v[158:159], v[158:159], v[180:181]
	v_cvt_pk_bf16_f32 v136, v136, v137
	v_add_f32_e32 v137, 1.0, v157
	v_rcp_f32_e32 v160, v137
	v_mul_f32_e32 v137, 0xbfb8aa3b, v95
	v_mul_f32_e32 v157, 0xbfb8aa3b, v96
	v_exp_f32_e32 v137, v137
	v_exp_f32_e32 v157, v157
	v_ashrrev_i32_e32 v185, 31, v184
	v_add_u32_e32 v186, 48, v148
	v_add_f32_e32 v137, 1.0, v137
	v_add_f32_e32 v157, 1.0, v157
	v_rcp_f32_e32 v162, v157
	v_add_f32_e32 v157, 1.0, v161
	v_rcp_f32_e32 v161, v137
	v_rcp_f32_e32 v163, v157
	v_cvt_pk_bf16_f32 v137, v158, v159
	global_store_dwordx2 v[134:135], v[136:137], off offset:-3840
	v_pk_mul_f32 v[130:131], v[160:161], v[130:131]
	v_pk_mul_f32 v[132:133], v[162:163], v[132:133]
	v_cvt_pk_bf16_f32 v130, v130, v131
	v_ashrrev_i32_e32 v187, 31, v186
	v_cvt_pk_bf16_f32 v131, v132, v133
	global_store_dwordx2 v[134:135], v[130:131], off offset:-3808
	v_lshlrev_b64 v[130:131], 12, v[184:185]
	v_lshl_add_u64 v[130:131], v[152:153], 0, v[130:131]
	v_add_co_u32_e32 v132, vcc, s48, v130
	v_mul_f32_e32 v157, 0xbfb8aa3b, v102
	s_nop 0
	v_addc_co_u32_e32 v133, vcc, -1, v131, vcc
	global_load_dwordx4 v[158:161], v[132:133], off
	v_add_co_u32_e32 v130, vcc, s49, v130
	v_exp_f32_e32 v157, v157
	s_nop 0
	v_addc_co_u32_e32 v131, vcc, -1, v131, vcc
	global_load_dwordx4 v[162:165], v[130:131], off offset:-4032
	global_load_dwordx4 v[166:169], v[130:131], off offset:-3584
	global_load_dwordx4 v[170:173], v[130:131], off offset:-3520
	v_lshlrev_b64 v[130:131], 12, v[186:187]
	v_lshl_add_u64 v[130:131], v[152:153], 0, v[130:131]
	v_add_co_u32_e32 v132, vcc, s48, v130
	v_add_f32_e32 v157, 1.0, v157
	s_nop 0
	v_addc_co_u32_e32 v133, vcc, -1, v131, vcc
	v_add_co_u32_e32 v130, vcc, s49, v130
	v_rcp_f32_e32 v188, v157
	s_nop 0
	v_addc_co_u32_e32 v131, vcc, -1, v131, vcc
	global_load_dwordx4 v[174:177], v[132:133], off
	global_load_dwordx4 v[178:181], v[130:131], off offset:-4032
	global_load_dwordx4 v[134:137], v[130:131], off offset:-3584
	s_nop 0
	global_load_dwordx4 v[130:133], v[130:131], off offset:-3520
	v_mul_f32_e32 v157, 0xbfb8aa3b, v103
	v_exp_f32_e32 v157, v157
	v_exp_f32_e32 v189, v189
	v_rcp_f32_e32 v190, v183
	v_add_f32_e32 v157, 1.0, v157
	v_add_f32_e32 v183, 1.0, v189
	v_rcp_f32_e32 v189, v157
	v_mul_f32_e32 v157, 0xbfb8aa3b, v90
	v_exp_f32_e32 v157, v157
	v_rcp_f32_e32 v191, v183
	v_mul_f32_e32 v183, 0xbfb8aa3b, v93
	v_exp_f32_e32 v183, v183
	v_add_f32_e32 v157, 1.0, v157
	v_lshlrev_b64 v[184:185], 11, v[184:185]
	v_lshl_add_u64 v[184:185], s[74:75], 0, v[184:185]
	v_lshl_add_u64 v[184:185], v[184:185], 0, v[150:151]
	s_waitcnt vmcnt(0)
	v_pk_mul_f32 v[158:159], v[188:189], v[158:159]
	s_nop 0
	v_cvt_pk_bf16_f32 v158, v158, v159
	v_mul_f32_e32 v159, 0xbfb8aa3b, v92
	v_rcp_f32_e32 v188, v157
	v_mul_f32_e32 v157, 0xbfb8aa3b, v91
	v_exp_f32_e32 v159, v159
	v_exp_f32_e32 v157, v157
	v_pk_mul_f32 v[160:161], v[190:191], v[160:161]
	v_add_f32_e32 v159, 1.0, v159
	v_add_f32_e32 v157, 1.0, v157
	v_rcp_f32_e32 v190, v159
	v_add_f32_e32 v159, 1.0, v183
	v_rcp_f32_e32 v191, v159
	v_rcp_f32_e32 v189, v157
	v_mul_f32_e32 v157, 0xbfb8aa3b, v82
	v_exp_f32_e32 v157, v157
	v_cvt_pk_bf16_f32 v159, v160, v161
	global_store_dwordx2 v[184:185], v[158:159], off offset:-4096
	v_pk_mul_f32 v[158:159], v[190:191], v[164:165]
	v_pk_mul_f32 v[160:161], v[188:189], v[162:163]
	v_add_f32_e32 v157, 1.0, v157
	v_cvt_pk_bf16_f32 v160, v160, v161
	v_cvt_pk_bf16_f32 v161, v158, v159
	v_mul_f32_e32 v159, 0xbfb8aa3b, v84
	global_store_dwordx2 v[184:185], v[160:161], off offset:-4064
	v_rcp_f32_e32 v158, v157
	v_mul_f32_e32 v157, 0xbfb8aa3b, v83
	v_exp_f32_e32 v159, v159
	v_mul_f32_e32 v160, 0xbfb8aa3b, v85
	v_exp_f32_e32 v157, v157
	v_exp_f32_e32 v161, v160
	v_add_f32_e32 v159, 1.0, v159
	v_rcp_f32_e32 v160, v159
	v_add_f32_e32 v157, 1.0, v157
	v_add_f32_e32 v159, 1.0, v161
	v_rcp_f32_e32 v161, v159
	v_rcp_f32_e32 v159, v157
	v_mul_f32_e32 v157, 0xbfb8aa3b, v78
	v_exp_f32_e32 v157, v157
	v_mul_f32_e32 v163, 0xbfb8aa3b, v81
	v_pk_mul_f32 v[158:159], v[158:159], v[166:167]
	v_exp_f32_e32 v163, v163
	v_add_f32_e32 v157, 1.0, v157
	v_cvt_pk_bf16_f32 v158, v158, v159
	v_rcp_f32_e32 v162, v157
	v_mul_f32_e32 v157, 0xbfb8aa3b, v79
	v_mul_f32_e32 v159, 0xbfb8aa3b, v80
	v_exp_f32_e32 v157, v157
	v_exp_f32_e32 v159, v159
	v_pk_mul_f32 v[160:161], v[160:161], v[168:169]
	v_mul_f32_e32 v183, 0xbfb8aa3b, v64
	v_add_f32_e32 v157, 1.0, v157
	v_add_f32_e32 v159, 1.0, v159
	v_rcp_f32_e32 v164, v159
	v_add_f32_e32 v159, 1.0, v163
	v_rcp_f32_e32 v163, v157
	v_rcp_f32_e32 v165, v159
	v_mul_f32_e32 v157, 0xbfb8aa3b, v86
	v_exp_f32_e32 v157, v157
	v_cvt_pk_bf16_f32 v159, v160, v161
	v_pk_mul_f32 v[160:161], v[162:163], v[170:171]
	global_store_dwordx2 v[184:185], v[158:159], off offset:-3840
	v_pk_mul_f32 v[158:159], v[164:165], v[172:173]
	v_cvt_pk_bf16_f32 v160, v160, v161
	v_add_f32_e32 v157, 1.0, v157
	v_cvt_pk_bf16_f32 v161, v158, v159
	global_store_dwordx2 v[184:185], v[160:161], off offset:-3808
	v_mul_f32_e32 v161, 0xbfb8aa3b, v88
	v_rcp_f32_e32 v160, v157
	v_mul_f32_e32 v157, 0xbfb8aa3b, v87
	v_exp_f32_e32 v161, v161
	v_mul_f32_e32 v162, 0xbfb8aa3b, v89
	v_exp_f32_e32 v157, v157
	v_exp_f32_e32 v163, v162
	v_add_f32_e32 v161, 1.0, v161
	v_rcp_f32_e32 v162, v161
	v_add_f32_e32 v157, 1.0, v157
	v_add_f32_e32 v161, 1.0, v163
	v_rcp_f32_e32 v163, v161
	v_rcp_f32_e32 v161, v157
	v_mul_f32_e32 v157, 0xbfb8aa3b, v74
	v_exp_f32_e32 v157, v157
	v_mul_f32_e32 v165, 0xbfb8aa3b, v77
	v_pk_mul_f32 v[160:161], v[160:161], v[174:175]
	v_exp_f32_e32 v165, v165
	v_cvt_pk_bf16_f32 v160, v160, v161
	v_add_f32_e32 v157, 1.0, v157
	v_mul_f32_e32 v161, 0xbfb8aa3b, v76
	v_rcp_f32_e32 v164, v157
	v_mul_f32_e32 v157, 0xbfb8aa3b, v75
	v_exp_f32_e32 v161, v161
	v_exp_f32_e32 v157, v157
	v_lshlrev_b64 v[158:159], 11, v[186:187]
	v_lshl_add_u64 v[158:159], s[74:75], 0, v[158:159]
	v_add_f32_e32 v161, 1.0, v161
	v_add_f32_e32 v157, 1.0, v157
	v_rcp_f32_e32 v166, v161
	v_add_f32_e32 v161, 1.0, v165
	v_rcp_f32_e32 v167, v161
	v_rcp_f32_e32 v165, v157
	v_mul_f32_e32 v157, 0xbfb8aa3b, v70
	v_exp_f32_e32 v157, v157
	v_lshl_add_u64 v[158:159], v[158:159], 0, v[150:151]
	v_pk_mul_f32 v[162:163], v[162:163], v[176:177]
	v_add_u32_e32 v184, 0x80, v148
	v_cvt_pk_bf16_f32 v161, v162, v163
	global_store_dwordx2 v[158:159], v[160:161], off offset:-4096
	v_pk_mul_f32 v[160:161], v[166:167], v[180:181]
	v_pk_mul_f32 v[162:163], v[164:165], v[178:179]
	v_add_f32_e32 v157, 1.0, v157
	v_cvt_pk_bf16_f32 v162, v162, v163
	v_cvt_pk_bf16_f32 v163, v160, v161
	v_mul_f32_e32 v161, 0xbfb8aa3b, v72
	global_store_dwordx2 v[158:159], v[162:163], off offset:-4064
	v_rcp_f32_e32 v160, v157
	v_mul_f32_e32 v157, 0xbfb8aa3b, v71
	v_exp_f32_e32 v161, v161
	v_mul_f32_e32 v162, 0xbfb8aa3b, v73
	v_exp_f32_e32 v157, v157
	v_exp_f32_e32 v163, v162
	v_add_f32_e32 v161, 1.0, v161
	v_rcp_f32_e32 v162, v161
	v_add_f32_e32 v157, 1.0, v157
	v_add_f32_e32 v161, 1.0, v163
	v_rcp_f32_e32 v163, v161
	v_rcp_f32_e32 v161, v157
	v_mul_f32_e32 v157, 0xbfb8aa3b, v66
	v_exp_f32_e32 v157, v157
	v_pk_mul_f32 v[136:137], v[162:163], v[136:137]
	v_pk_mul_f32 v[134:135], v[160:161], v[134:135]
	v_mul_f32_e32 v161, 0xbfb8aa3b, v69
	v_cvt_pk_bf16_f32 v134, v134, v135
	v_add_f32_e32 v135, 1.0, v157
	v_rcp_f32_e32 v160, v135
	v_mul_f32_e32 v135, 0xbfb8aa3b, v67
	v_mul_f32_e32 v157, 0xbfb8aa3b, v68
	v_exp_f32_e32 v135, v135
	v_exp_f32_e32 v157, v157
	v_exp_f32_e32 v161, v161
	v_ashrrev_i32_e32 v185, 31, v184
	v_add_f32_e32 v135, 1.0, v135
	v_add_f32_e32 v157, 1.0, v157
	v_rcp_f32_e32 v162, v157
	v_add_f32_e32 v157, 1.0, v161
	v_rcp_f32_e32 v161, v135
	v_rcp_f32_e32 v163, v157
	v_cvt_pk_bf16_f32 v135, v136, v137
	global_store_dwordx2 v[158:159], v[134:135], off offset:-3840
	v_pk_mul_f32 v[130:131], v[160:161], v[130:131]
	v_pk_mul_f32 v[132:133], v[162:163], v[132:133]
	v_cvt_pk_bf16_f32 v130, v130, v131
	v_add_u32_e32 v186, 0x90, v148
	v_cvt_pk_bf16_f32 v131, v132, v133
	global_store_dwordx2 v[158:159], v[130:131], off offset:-3808
	v_lshlrev_b64 v[130:131], 12, v[184:185]
	v_lshl_add_u64 v[130:131], v[152:153], 0, v[130:131]
	v_add_co_u32_e32 v132, vcc, s48, v130
	v_ashrrev_i32_e32 v187, 31, v186
	s_nop 0
	v_addc_co_u32_e32 v133, vcc, -1, v131, vcc
	global_load_dwordx4 v[158:161], v[132:133], off
	v_add_co_u32_e32 v130, vcc, s49, v130
	v_mul_f32_e32 v157, 0xbfb8aa3b, v62
	s_nop 0
	v_addc_co_u32_e32 v131, vcc, -1, v131, vcc
	global_load_dwordx4 v[162:165], v[130:131], off offset:-4032
	global_load_dwordx4 v[166:169], v[130:131], off offset:-3584
	global_load_dwordx4 v[170:173], v[130:131], off offset:-3520
	v_lshlrev_b64 v[130:131], 12, v[186:187]
	v_lshl_add_u64 v[130:131], v[152:153], 0, v[130:131]
	v_add_co_u32_e32 v132, vcc, s48, v130
	v_exp_f32_e32 v157, v157
	s_nop 0
	v_addc_co_u32_e32 v133, vcc, -1, v131, vcc
	v_add_co_u32_e32 v130, vcc, s49, v130
	v_add_f32_e32 v157, 1.0, v157
	s_nop 0
	v_addc_co_u32_e32 v131, vcc, -1, v131, vcc
	global_load_dwordx4 v[174:177], v[132:133], off
	global_load_dwordx4 v[178:181], v[130:131], off offset:-4032
	global_load_dwordx4 v[134:137], v[130:131], off offset:-3584
	s_nop 0
	global_load_dwordx4 v[130:133], v[130:131], off offset:-3520
	v_rcp_f32_e32 v188, v157
	v_mul_f32_e32 v157, 0xbfb8aa3b, v63
	v_exp_f32_e32 v157, v157
	v_exp_f32_e32 v183, v183
	v_mul_f32_e32 v189, 0xbfb8aa3b, v65
	v_exp_f32_e32 v189, v189
	v_add_f32_e32 v157, 1.0, v157
	v_add_f32_e32 v183, 1.0, v183
	v_rcp_f32_e32 v190, v183
	v_add_f32_e32 v183, 1.0, v189
	v_rcp_f32_e32 v189, v157
	v_mul_f32_e32 v157, 0xbfb8aa3b, v58
	v_exp_f32_e32 v157, v157
	v_rcp_f32_e32 v191, v183
	v_mul_f32_e32 v183, 0xbfb8aa3b, v61
	v_add_f32_e32 v157, 1.0, v157
	v_exp_f32_e32 v183, v183
	v_lshlrev_b64 v[184:185], 11, v[184:185]
	v_lshl_add_u64 v[184:185], s[74:75], 0, v[184:185]
	v_lshl_add_u64 v[184:185], v[184:185], 0, v[150:151]
	s_waitcnt vmcnt(0)
	v_pk_mul_f32 v[158:159], v[188:189], v[158:159]
	s_nop 0
	v_cvt_pk_bf16_f32 v158, v158, v159
	v_mul_f32_e32 v159, 0xbfb8aa3b, v60
	v_rcp_f32_e32 v188, v157
	v_mul_f32_e32 v157, 0xbfb8aa3b, v59
	v_exp_f32_e32 v159, v159
	v_exp_f32_e32 v157, v157
	v_pk_mul_f32 v[160:161], v[190:191], v[160:161]
	v_add_f32_e32 v159, 1.0, v159
	v_add_f32_e32 v157, 1.0, v157
	v_rcp_f32_e32 v190, v159
	v_add_f32_e32 v159, 1.0, v183
	v_rcp_f32_e32 v191, v159
	v_rcp_f32_e32 v189, v157
	v_mul_f32_e32 v157, 0xbfb8aa3b, v50
	v_exp_f32_e32 v157, v157
	v_cvt_pk_bf16_f32 v159, v160, v161
	global_store_dwordx2 v[184:185], v[158:159], off offset:-4096
	v_pk_mul_f32 v[158:159], v[190:191], v[164:165]
	v_pk_mul_f32 v[160:161], v[188:189], v[162:163]
	v_add_f32_e32 v157, 1.0, v157
	v_cvt_pk_bf16_f32 v160, v160, v161
	v_cvt_pk_bf16_f32 v161, v158, v159
	v_mul_f32_e32 v159, 0xbfb8aa3b, v52
	global_store_dwordx2 v[184:185], v[160:161], off offset:-4064
	v_rcp_f32_e32 v158, v157
	v_mul_f32_e32 v157, 0xbfb8aa3b, v51
	v_exp_f32_e32 v159, v159
	v_mul_f32_e32 v160, 0xbfb8aa3b, v53
	v_exp_f32_e32 v157, v157
	v_exp_f32_e32 v161, v160
	v_add_f32_e32 v159, 1.0, v159
	v_rcp_f32_e32 v160, v159
	v_add_f32_e32 v157, 1.0, v157
	v_add_f32_e32 v159, 1.0, v161
	v_rcp_f32_e32 v161, v159
	v_rcp_f32_e32 v159, v157
	v_mul_f32_e32 v157, 0xbfb8aa3b, v42
	v_exp_f32_e32 v157, v157
	v_mul_f32_e32 v163, 0xbfb8aa3b, v45
	v_pk_mul_f32 v[158:159], v[158:159], v[166:167]
	v_exp_f32_e32 v163, v163
	v_add_f32_e32 v157, 1.0, v157
	v_cvt_pk_bf16_f32 v158, v158, v159
	v_rcp_f32_e32 v162, v157
	v_mul_f32_e32 v157, 0xbfb8aa3b, v43
	v_mul_f32_e32 v159, 0xbfb8aa3b, v44
	v_exp_f32_e32 v157, v157
	v_exp_f32_e32 v159, v159
	v_pk_mul_f32 v[160:161], v[160:161], v[168:169]
	v_mul_f32_e32 v183, 0xbfb8aa3b, v40
	v_add_f32_e32 v157, 1.0, v157
	v_add_f32_e32 v159, 1.0, v159
	v_rcp_f32_e32 v164, v159
	v_add_f32_e32 v159, 1.0, v163
	v_rcp_f32_e32 v163, v157
	v_rcp_f32_e32 v165, v159
	v_mul_f32_e32 v157, 0xbfb8aa3b, v54
	v_exp_f32_e32 v157, v157
	v_cvt_pk_bf16_f32 v159, v160, v161
	v_pk_mul_f32 v[160:161], v[162:163], v[170:171]
	global_store_dwordx2 v[184:185], v[158:159], off offset:-3840
	v_pk_mul_f32 v[158:159], v[164:165], v[172:173]
	v_cvt_pk_bf16_f32 v160, v160, v161
	v_add_f32_e32 v157, 1.0, v157
	v_cvt_pk_bf16_f32 v161, v158, v159
	global_store_dwordx2 v[184:185], v[160:161], off offset:-3808
	v_mul_f32_e32 v161, 0xbfb8aa3b, v56
	v_rcp_f32_e32 v160, v157
	v_mul_f32_e32 v157, 0xbfb8aa3b, v55
	v_exp_f32_e32 v161, v161
	v_mul_f32_e32 v162, 0xbfb8aa3b, v57
	v_exp_f32_e32 v157, v157
	v_exp_f32_e32 v163, v162
	v_add_f32_e32 v161, 1.0, v161
	v_rcp_f32_e32 v162, v161
	v_add_f32_e32 v157, 1.0, v157
	v_add_f32_e32 v161, 1.0, v163
	v_rcp_f32_e32 v163, v161
	v_rcp_f32_e32 v161, v157
	v_mul_f32_e32 v157, 0xbfb8aa3b, v46
	v_exp_f32_e32 v157, v157
	v_mul_f32_e32 v165, 0xbfb8aa3b, v49
	v_pk_mul_f32 v[160:161], v[160:161], v[174:175]
	v_exp_f32_e32 v165, v165
	v_cvt_pk_bf16_f32 v160, v160, v161
	v_add_f32_e32 v157, 1.0, v157
	v_mul_f32_e32 v161, 0xbfb8aa3b, v48
	v_rcp_f32_e32 v164, v157
	v_mul_f32_e32 v157, 0xbfb8aa3b, v47
	v_exp_f32_e32 v161, v161
	v_exp_f32_e32 v157, v157
	v_lshlrev_b64 v[158:159], 11, v[186:187]
	v_lshl_add_u64 v[158:159], s[74:75], 0, v[158:159]
	v_add_f32_e32 v161, 1.0, v161
	v_add_f32_e32 v157, 1.0, v157
	v_rcp_f32_e32 v166, v161
	v_add_f32_e32 v161, 1.0, v165
	v_rcp_f32_e32 v167, v161
	v_rcp_f32_e32 v165, v157
	v_mul_f32_e32 v157, 0xbfb8aa3b, v34
	v_exp_f32_e32 v157, v157
	v_lshl_add_u64 v[158:159], v[158:159], 0, v[150:151]
	v_pk_mul_f32 v[162:163], v[162:163], v[176:177]
	v_add_u32_e32 v184, 0xa0, v148
	v_cvt_pk_bf16_f32 v161, v162, v163
	global_store_dwordx2 v[158:159], v[160:161], off offset:-4096
	v_pk_mul_f32 v[160:161], v[166:167], v[180:181]
	v_pk_mul_f32 v[162:163], v[164:165], v[178:179]
	v_add_f32_e32 v157, 1.0, v157
	v_cvt_pk_bf16_f32 v162, v162, v163
	v_cvt_pk_bf16_f32 v163, v160, v161
	v_mul_f32_e32 v161, 0xbfb8aa3b, v36
	global_store_dwordx2 v[158:159], v[162:163], off offset:-4064
	v_rcp_f32_e32 v160, v157
	v_mul_f32_e32 v157, 0xbfb8aa3b, v35
	v_exp_f32_e32 v161, v161
	v_mul_f32_e32 v162, 0xbfb8aa3b, v37
	v_exp_f32_e32 v157, v157
	v_exp_f32_e32 v163, v162
	v_add_f32_e32 v161, 1.0, v161
	v_rcp_f32_e32 v162, v161
	v_add_f32_e32 v157, 1.0, v157
	v_add_f32_e32 v161, 1.0, v163
	v_rcp_f32_e32 v163, v161
	v_rcp_f32_e32 v161, v157
	v_mul_f32_e32 v157, 0xbfb8aa3b, v26
	v_exp_f32_e32 v157, v157
	v_pk_mul_f32 v[136:137], v[162:163], v[136:137]
	v_pk_mul_f32 v[134:135], v[160:161], v[134:135]
	v_mul_f32_e32 v161, 0xbfb8aa3b, v29
	v_cvt_pk_bf16_f32 v134, v134, v135
	v_add_f32_e32 v135, 1.0, v157
	v_rcp_f32_e32 v160, v135
	v_mul_f32_e32 v135, 0xbfb8aa3b, v27
	v_mul_f32_e32 v157, 0xbfb8aa3b, v28
	v_exp_f32_e32 v135, v135
	v_exp_f32_e32 v157, v157
	v_exp_f32_e32 v161, v161
	v_ashrrev_i32_e32 v185, 31, v184
	v_add_f32_e32 v135, 1.0, v135
	v_add_f32_e32 v157, 1.0, v157
	v_rcp_f32_e32 v162, v157
	v_add_f32_e32 v157, 1.0, v161
	v_rcp_f32_e32 v161, v135
	v_rcp_f32_e32 v163, v157
	v_cvt_pk_bf16_f32 v135, v136, v137
	global_store_dwordx2 v[158:159], v[134:135], off offset:-3840
	v_pk_mul_f32 v[130:131], v[160:161], v[130:131]
	v_pk_mul_f32 v[132:133], v[162:163], v[132:133]
	v_cvt_pk_bf16_f32 v130, v130, v131
	v_add_u32_e32 v186, 0xb0, v148
	v_cvt_pk_bf16_f32 v131, v132, v133
	global_store_dwordx2 v[158:159], v[130:131], off offset:-3808
	v_lshlrev_b64 v[130:131], 12, v[184:185]
	v_lshl_add_u64 v[130:131], v[152:153], 0, v[130:131]
	v_add_co_u32_e32 v132, vcc, s48, v130
	v_ashrrev_i32_e32 v187, 31, v186
	s_nop 0
	v_addc_co_u32_e32 v133, vcc, -1, v131, vcc
	global_load_dwordx4 v[158:161], v[132:133], off
	v_add_co_u32_e32 v130, vcc, s49, v130
	v_exp_f32_e32 v183, v183
	s_nop 0
	v_addc_co_u32_e32 v131, vcc, -1, v131, vcc
	global_load_dwordx4 v[162:165], v[130:131], off offset:-4032
	global_load_dwordx4 v[166:169], v[130:131], off offset:-3584
	global_load_dwordx4 v[170:173], v[130:131], off offset:-3520
	v_lshlrev_b64 v[130:131], 12, v[186:187]
	v_lshl_add_u64 v[130:131], v[152:153], 0, v[130:131]
	v_add_co_u32_e32 v132, vcc, s48, v130
	v_mul_f32_e32 v152, 0xbfb8aa3b, v38
	s_nop 0
	v_addc_co_u32_e32 v133, vcc, -1, v131, vcc
	v_add_co_u32_e32 v130, vcc, s49, v130
	v_exp_f32_e32 v157, v152
	s_nop 0
	v_addc_co_u32_e32 v131, vcc, -1, v131, vcc
	global_load_dwordx4 v[174:177], v[132:133], off
	global_load_dwordx4 v[178:181], v[130:131], off offset:-4032
	global_load_dwordx4 v[134:137], v[130:131], off offset:-3584
	s_nop 0
	global_load_dwordx4 v[130:133], v[130:131], off offset:-3520
	v_add_f32_e32 v157, 1.0, v157
	v_lshlrev_b64 v[152:153], 11, v[184:185]
	v_rcp_f32_e32 v184, v157
	v_mul_f32_e32 v157, 0xbfb8aa3b, v39
	v_exp_f32_e32 v157, v157
	v_mul_f32_e32 v185, 0xbfb8aa3b, v41
	v_exp_f32_e32 v185, v185
	v_add_f32_e32 v183, 1.0, v183
	v_add_f32_e32 v157, 1.0, v157
	v_rcp_f32_e32 v188, v183
	v_add_f32_e32 v183, 1.0, v185
	v_rcp_f32_e32 v185, v157
	v_mul_f32_e32 v157, 0xbfb8aa3b, v30
	v_exp_f32_e32 v157, v157
	v_rcp_f32_e32 v189, v183
	v_mul_f32_e32 v183, 0xbfb8aa3b, v33
	v_add_f32_e32 v157, 1.0, v157
	v_exp_f32_e32 v183, v183
	v_lshl_add_u64 v[152:153], s[74:75], 0, v[152:153]
	v_lshl_add_u64 v[152:153], v[152:153], 0, v[150:151]
	s_waitcnt vmcnt(0)
	v_pk_mul_f32 v[158:159], v[184:185], v[158:159]
	s_nop 0
	v_cvt_pk_bf16_f32 v158, v158, v159
	v_mul_f32_e32 v159, 0xbfb8aa3b, v32
	v_rcp_f32_e32 v184, v157
	v_mul_f32_e32 v157, 0xbfb8aa3b, v31
	v_exp_f32_e32 v159, v159
	v_exp_f32_e32 v157, v157
	v_pk_mul_f32 v[160:161], v[188:189], v[160:161]
	v_add_f32_e32 v159, 1.0, v159
	v_add_f32_e32 v157, 1.0, v157
	v_rcp_f32_e32 v188, v159
	v_add_f32_e32 v159, 1.0, v183
	v_rcp_f32_e32 v189, v159
	v_rcp_f32_e32 v185, v157
	v_mul_f32_e32 v157, 0xbfb8aa3b, v18
	v_exp_f32_e32 v157, v157
	v_cvt_pk_bf16_f32 v159, v160, v161
	global_store_dwordx2 v[152:153], v[158:159], off offset:-4096
	v_pk_mul_f32 v[158:159], v[188:189], v[164:165]
	v_pk_mul_f32 v[160:161], v[184:185], v[162:163]
	v_add_f32_e32 v157, 1.0, v157
	v_cvt_pk_bf16_f32 v160, v160, v161
	v_cvt_pk_bf16_f32 v161, v158, v159
	v_mul_f32_e32 v159, 0xbfb8aa3b, v20
	global_store_dwordx2 v[152:153], v[160:161], off offset:-4064
	v_rcp_f32_e32 v158, v157
	v_mul_f32_e32 v157, 0xbfb8aa3b, v19
	v_exp_f32_e32 v159, v159
	v_mul_f32_e32 v160, 0xbfb8aa3b, v21
	v_exp_f32_e32 v157, v157
	v_exp_f32_e32 v161, v160
	v_add_f32_e32 v159, 1.0, v159
	v_rcp_f32_e32 v160, v159
	v_add_f32_e32 v157, 1.0, v157
	v_add_f32_e32 v159, 1.0, v161
	v_rcp_f32_e32 v161, v159
	v_rcp_f32_e32 v159, v157
	v_mul_f32_e32 v157, 0xbfb8aa3b, v10
	v_exp_f32_e32 v157, v157
	v_mul_f32_e32 v163, 0xbfb8aa3b, v13
	v_pk_mul_f32 v[158:159], v[158:159], v[166:167]
	v_exp_f32_e32 v163, v163
	v_add_f32_e32 v157, 1.0, v157
	v_cvt_pk_bf16_f32 v158, v158, v159
	v_rcp_f32_e32 v162, v157
	v_mul_f32_e32 v157, 0xbfb8aa3b, v11
	v_mul_f32_e32 v159, 0xbfb8aa3b, v12
	v_exp_f32_e32 v157, v157
	v_exp_f32_e32 v159, v159
	v_pk_mul_f32 v[160:161], v[160:161], v[168:169]
	v_add_f32_e32 v157, 1.0, v157
	v_add_f32_e32 v159, 1.0, v159
	v_rcp_f32_e32 v164, v159
	v_add_f32_e32 v159, 1.0, v163
	v_rcp_f32_e32 v163, v157
	v_rcp_f32_e32 v165, v159
	v_cvt_pk_bf16_f32 v159, v160, v161
	global_store_dwordx2 v[152:153], v[158:159], off offset:-3840
	v_pk_mul_f32 v[160:161], v[162:163], v[170:171]
	v_pk_mul_f32 v[158:159], v[164:165], v[172:173]
	v_cvt_pk_bf16_f32 v160, v160, v161
	s_nop 0
	v_cvt_pk_bf16_f32 v161, v158, v159
	global_store_dwordx2 v[152:153], v[160:161], off offset:-3808
	v_mul_f32_e32 v152, 0xbfb8aa3b, v22
	v_exp_f32_e32 v157, v152
	v_lshlrev_b64 v[152:153], 11, v[186:187]
	v_lshl_add_u64 v[152:153], s[74:75], 0, v[152:153]
	v_lshl_add_u64 v[150:151], v[152:153], 0, v[150:151]
	v_add_f32_e32 v152, 1.0, v157
	v_mul_f32_e32 v157, 0xbfb8aa3b, v24
	v_mul_f32_e32 v153, 0xbfb8aa3b, v23
	v_exp_f32_e32 v157, v157
	v_mul_f32_e32 v158, 0xbfb8aa3b, v25
	v_exp_f32_e32 v153, v153
	v_exp_f32_e32 v159, v158
	v_add_f32_e32 v157, 1.0, v157
	v_rcp_f32_e32 v158, v157
	v_add_f32_e32 v153, 1.0, v153
	v_add_f32_e32 v157, 1.0, v159
	v_rcp_f32_e32 v152, v152
	v_rcp_f32_e32 v159, v157
	v_rcp_f32_e32 v153, v153
	v_mul_f32_e32 v157, 0xbfb8aa3b, v14
	v_exp_f32_e32 v157, v157
	v_mul_f32_e32 v161, 0xbfb8aa3b, v17
	v_pk_mul_f32 v[152:153], v[152:153], v[174:175]
	v_exp_f32_e32 v161, v161
	v_cvt_pk_bf16_f32 v152, v152, v153
	v_add_f32_e32 v153, 1.0, v157
	v_mul_f32_e32 v157, 0xbfb8aa3b, v16
	v_rcp_f32_e32 v160, v153
	v_mul_f32_e32 v153, 0xbfb8aa3b, v15
	v_exp_f32_e32 v157, v157
	v_exp_f32_e32 v153, v153
	v_pk_mul_f32 v[158:159], v[158:159], v[176:177]
	v_add_f32_e32 v157, 1.0, v157
	v_add_f32_e32 v153, 1.0, v153
	v_rcp_f32_e32 v162, v157
	v_add_f32_e32 v157, 1.0, v161
	v_rcp_f32_e32 v163, v157
	v_rcp_f32_e32 v161, v153
	v_mul_f32_e32 v157, 0xbfb8aa3b, v6
	v_exp_f32_e32 v157, v157
	v_cvt_pk_bf16_f32 v153, v158, v159
	global_store_dwordx2 v[150:151], v[152:153], off offset:-4096
	v_pk_mul_f32 v[152:153], v[162:163], v[180:181]
	v_pk_mul_f32 v[158:159], v[160:161], v[178:179]
	s_nop 0
	v_cvt_pk_bf16_f32 v158, v158, v159
	v_cvt_pk_bf16_f32 v159, v152, v153
	v_add_f32_e32 v152, 1.0, v157
	v_mul_f32_e32 v157, 0xbfb8aa3b, v8
	global_store_dwordx2 v[150:151], v[158:159], off offset:-4064
	v_mul_f32_e32 v153, 0xbfb8aa3b, v7
	v_exp_f32_e32 v157, v157
	v_mul_f32_e32 v158, 0xbfb8aa3b, v9
	v_exp_f32_e32 v153, v153
	v_exp_f32_e32 v159, v158
	v_add_f32_e32 v157, 1.0, v157
	v_rcp_f32_e32 v158, v157
	v_add_f32_e32 v153, 1.0, v153
	v_add_f32_e32 v157, 1.0, v159
	v_rcp_f32_e32 v152, v152
	v_rcp_f32_e32 v159, v157
	v_rcp_f32_e32 v153, v153
	v_mul_f32_e32 v157, 0xbfb8aa3b, v2
	v_exp_f32_e32 v157, v157
	v_pk_mul_f32 v[136:137], v[158:159], v[136:137]
	v_pk_mul_f32 v[134:135], v[152:153], v[134:135]
	v_mul_f32_e32 v153, 0xbfb8aa3b, v4
	v_cvt_pk_bf16_f32 v134, v134, v135
	v_add_f32_e32 v135, 1.0, v157
	v_rcp_f32_e32 v152, v135
	v_mul_f32_e32 v135, 0xbfb8aa3b, v3
	v_exp_f32_e32 v153, v153
	v_mul_f32_e32 v157, 0xbfb8aa3b, v5
	v_exp_f32_e32 v135, v135
	v_exp_f32_e32 v157, v157
	v_add_f32_e32 v153, 1.0, v153
	v_rcp_f32_e32 v158, v153
	v_add_f32_e32 v135, 1.0, v135
	v_add_f32_e32 v153, 1.0, v157
	v_rcp_f32_e32 v159, v153
	v_rcp_f32_e32 v153, v135
	v_cvt_pk_bf16_f32 v135, v136, v137
	global_store_dwordx2 v[150:151], v[134:135], off offset:-3840
	v_pk_mul_f32 v[132:133], v[158:159], v[132:133]
	v_pk_mul_f32 v[130:131], v[152:153], v[130:131]
	s_nop 0
	v_cvt_pk_bf16_f32 v130, v130, v131
	v_cvt_pk_bf16_f32 v131, v132, v133
	global_store_dwordx2 v[150:151], v[130:131], off offset:-3808
